# GEMM main loops: dropped the redundant post-barrier lgkmcnt(0) in each MMA segment and merged the vmcnt/lgkmcnt wait pair before each barrier into one s_waitcnt
# speedup vs baseline: 1.0053x; 1.0053x over previous
; #define PG8_STAGE(bufoff, gbase, voff) do { _Pragma("unroll") for (int _i = 0; _i < 2; ++_i) \
;         __builtin_amdgcn_global_load_lds((const unsigned*)((const char*)(gbase) + (voff)[_i]), (LAS unsigned*)(lds + (bufoff) + ldsw + _i * 8192), 16, 0, 0); } while (0)
; #define PG8_LDA(dst, b, h) do { _Pragma("unroll") for (int m = 0; m < 4; ++m) _Pragma("unroll") for (int k = 0; k < 2; ++k) dst[m][k] = *(const LAS bf16x8*)(lds + PG8_SA(b, h) + aoff + m * 2048 + k * 1024); } while (0)
; #define PG8_LDB(dst, b, h) do { _Pragma("unroll") for (int n = 0; n < 2; ++n) _Pragma("unroll") for (int k = 0; k < 2; ++k) dst[n][k] = *(const LAS bf16x8*)(lds + PG8_SB(b, h) + boff + n * 2048 + k * 1024); } while (0)
; #define PG8_MMA(ai, bj, At, Bt) do { __builtin_amdgcn_s_setprio(1); _Pragma("unroll") for (int m = 0; m < 4; ++m) _Pragma("unroll") for (int n = 0; n < 2; ++n) _Pragma("unroll") for (int k = 0; k < 2; ++k) \
;         acc[ai][bj][m][n] = __builtin_amdgcn_mfma_f32_16x16x32_bf16(Bt[n][k], At[m][k], acc[ai][bj][m][n], 0, 0, 0); __builtin_amdgcn_s_setprio(0); } while (0)
; #define PG8_WAIT_V(n) asm volatile("s_waitcnt vmcnt(" #n ")" ::: "memory")
; #define PG8_WAIT_L(n) asm volatile("s_waitcnt lgkmcnt(" #n ")" ::: "memory")
; #define PG8_BAR __builtin_amdgcn_s_barrier()
; #define PG8_SCHED __builtin_amdgcn_sched_barrier(0)
; template <class Epi, bool SP2, class Sched>
; __device__ __forceinline__ void gemm_phase(LAS unsigned char* lds, const Gemm g, const Sched& S, const Epi& E) {
;     ...
;             PG8_LDB(B0, 0, 0); PG8_LDB(B1, 0, 1); PG8_SCHED; PG8_LDA(At, 0, 0); PG8_STAGE(PG8_SA(1, 1), a1 + hstep, voffA);
;             PG8_WAIT_V(8); PG8_WAIT_L(0); PG8_BAR; PG8_MMA(0, 0, At, B0); PG8_MMA(0, 1, At, B1); PG8_BAR; PG8_SCHED;
;             PG8_LDA(At, 0, 1); PG8_STAGE(PG8_SB(0, 0), b2, voffB); PG8_STAGE(PG8_SB(0, 1), b2 + hstepB, voffB); PG8_STAGE(PG8_SA(0, 0), a2, voffA);
.LBB0_313:
	s_add_u32 s10, vcc_lo, 0xfffc0080
	s_addc_u32 s11, vcc_hi, -1
	s_add_i32 s22, 0, 0x10000
	s_cmp_eq_u32 s21, 12
	s_cselect_b32 s97, s3, s11
	s_cselect_b32 s96, s17, s10
	v_add_u32_e32 v64, s22, v155
	s_cselect_b32 s11, s62, s20
	s_cselect_b32 s10, s93, s95
	s_add_i32 s24, 0, 0x14000
	ds_read_b128 v[130:133], v64
	ds_read_b128 v[148:151], v64 offset:1024
	ds_read_b128 v[156:159], v64 offset:2048
	ds_read_b128 v[164:167], v64 offset:3072
	v_add_u32_e32 v64, s24, v155
	ds_read_b128 v[168:171], v64
	ds_read_b128 v[172:175], v64 offset:1024
	ds_read_b128 v[176:179], v64 offset:2048
	ds_read_b128 v[180:183], v64 offset:3072
	v_lshl_add_u64 v[152:153], vcc, 0, v[146:147]
	s_add_i32 m0, s73, 0xc000
	ds_read_b128 v[184:187], v162
	ds_read_b128 v[188:191], v162 offset:1024
	ds_read_b128 v[214:217], v162 offset:2048
	ds_read_b128 v[218:221], v162 offset:3072
	ds_read_b128 v[222:225], v162 offset:4096
	ds_read_b128 v[226:229], v162 offset:5120
	ds_read_b128 v[230:233], v162 offset:6144
	ds_read_b128 v[234:237], v162 offset:7168
	global_load_lds_dwordx4 v[152:153], off
	v_lshl_add_u64 v[152:153], vcc, 0, v[144:145]
	s_add_i32 m0, s73, 0xe000
	s_nop 0
	global_load_lds_dwordx4 v[152:153], off
	s_waitcnt vmcnt(8) lgkmcnt(0)
	s_barrier
	s_setprio 1
	v_mfma_f32_16x16x32_bf16 v[126:129], v[130:133], v[184:187], v[126:129]
	v_mfma_f32_16x16x32_bf16 v[122:125], v[156:159], v[184:187], v[122:125]
	v_mfma_f32_16x16x32_bf16 v[110:113], v[130:133], v[214:217], v[110:113]
	v_mfma_f32_16x16x32_bf16 v[106:109], v[156:159], v[214:217], v[106:109]
	v_mfma_f32_16x16x32_bf16 v[94:97], v[130:133], v[222:225], v[94:97]
	v_mfma_f32_16x16x32_bf16 v[90:93], v[156:159], v[222:225], v[90:93]
	v_mfma_f32_16x16x32_bf16 v[78:81], v[130:133], v[230:233], v[78:81]
	v_mfma_f32_16x16x32_bf16 v[74:77], v[156:159], v[230:233], v[74:77]
	v_mfma_f32_16x16x32_bf16 v[126:129], v[148:151], v[188:191], v[126:129]
	v_mfma_f32_16x16x32_bf16 v[122:125], v[164:167], v[188:191], v[122:125]
	v_mfma_f32_16x16x32_bf16 v[110:113], v[148:151], v[218:221], v[110:113]
	v_mfma_f32_16x16x32_bf16 v[106:109], v[164:167], v[218:221], v[106:109]
	v_mfma_f32_16x16x32_bf16 v[94:97], v[148:151], v[226:229], v[94:97]
	v_mfma_f32_16x16x32_bf16 v[90:93], v[164:167], v[226:229], v[90:93]
	v_mfma_f32_16x16x32_bf16 v[78:81], v[148:151], v[234:237], v[78:81]
	v_mfma_f32_16x16x32_bf16 v[74:77], v[164:167], v[234:237], v[74:77]
	s_setprio 0
	s_setprio 1
	v_mfma_f32_16x16x32_bf16 v[118:121], v[168:171], v[184:187], v[118:121]
	v_mfma_f32_16x16x32_bf16 v[114:117], v[176:179], v[184:187], v[114:117]
	v_mfma_f32_16x16x32_bf16 v[102:105], v[168:171], v[214:217], v[102:105]
	v_mfma_f32_16x16x32_bf16 v[98:101], v[176:179], v[214:217], v[98:101]
	v_mfma_f32_16x16x32_bf16 v[86:89], v[168:171], v[222:225], v[86:89]
	v_mfma_f32_16x16x32_bf16 v[82:85], v[176:179], v[222:225], v[82:85]
	v_mfma_f32_16x16x32_bf16 v[70:73], v[168:171], v[230:233], v[70:73]
	v_mfma_f32_16x16x32_bf16 v[66:69], v[176:179], v[230:233], v[66:69]
	v_mfma_f32_16x16x32_bf16 v[118:121], v[172:175], v[188:191], v[118:121]
	v_mfma_f32_16x16x32_bf16 v[114:117], v[180:183], v[188:191], v[114:117]
	v_mfma_f32_16x16x32_bf16 v[102:105], v[172:175], v[218:221], v[102:105]
	v_mfma_f32_16x16x32_bf16 v[98:101], v[180:183], v[218:221], v[98:101]
	v_mfma_f32_16x16x32_bf16 v[86:89], v[172:175], v[226:229], v[86:89]
	v_mfma_f32_16x16x32_bf16 v[82:85], v[180:183], v[226:229], v[82:85]
	v_mfma_f32_16x16x32_bf16 v[70:73], v[172:175], v[234:237], v[70:73]
	v_mfma_f32_16x16x32_bf16 v[66:69], v[180:183], v[234:237], v[66:69]
	s_setprio 0
	s_barrier
	s_add_i32 s22, s22, s72
	v_lshl_add_u64 v[152:153], s[10:11], 0, v[136:137]
	s_mov_b32 m0, s22
	ds_read_b128 v[184:187], v162 offset:16384
	ds_read_b128 v[188:191], v162 offset:17408
	ds_read_b128 v[214:217], v162 offset:18432
	ds_read_b128 v[218:221], v162 offset:19456
	ds_read_b128 v[222:225], v162 offset:20480
	ds_read_b128 v[226:229], v162 offset:21504
	ds_read_b128 v[230:233], v162 offset:22528
	ds_read_b128 v[234:237], v162 offset:23552
	global_load_lds_dwordx4 v[152:153], off
	s_add_i32 m0, s22, 0x2000
	s_add_u32 s22, s10, 0x40000
	v_lshl_add_u64 v[192:193], s[10:11], 0, v[140:141]
	s_addc_u32 s23, s11, 0
	s_add_i32 s24, s24, s72
	global_load_lds_dwordx4 v[192:193], off
	v_lshl_add_u64 v[238:239], s[22:23], 0, v[136:137]
	s_mov_b32 m0, s24
	v_lshl_add_u64 v[240:241], s[96:97], 0, v[138:139]
	global_load_lds_dwordx4 v[238:239], off
	v_lshl_add_u64 v[238:239], s[22:23], 0, v[140:141]
	s_add_i32 m0, s24, 0x2000
	s_nop 0
	global_load_lds_dwordx4 v[238:239], off
	v_lshl_add_u64 v[238:239], s[96:97], 0, v[134:135]
	s_mov_b32 m0, s73
	s_nop 0
	global_load_lds_dwordx4 v[238:239], off
	s_mov_b32 m0, s74
	s_nop 0
	global_load_lds_dwordx4 v[240:241], off
	s_waitcnt vmcnt(8) lgkmcnt(0)
	s_barrier
; #define PG8_STAGE(bufoff, gbase, voff) do { _Pragma("unroll") for (int _i = 0; _i < 2; ++_i) \
;         __builtin_amdgcn_global_load_lds((const unsigned*)((const char*)(gbase) + (voff)[_i]), (LAS unsigned*)(lds + (bufoff) + ldsw + _i * 8192), 16, 0, 0); } while (0)
; #define PG8_LDA(dst, b, h) do { _Pragma("unroll") for (int m = 0; m < 4; ++m) _Pragma("unroll") for (int k = 0; k < 2; ++k) dst[m][k] = *(const LAS bf16x8*)(lds + PG8_SA(b, h) + aoff + m * 2048 + k * 1024); } while (0)
; #define PG8_LDB(dst, b, h) do { _Pragma("unroll") for (int n = 0; n < 2; ++n) _Pragma("unroll") for (int k = 0; k < 2; ++k) dst[n][k] = *(const LAS bf16x8*)(lds + PG8_SB(b, h) + boff + n * 2048 + k * 1024); } while (0)
; #define PG8_MMA(ai, bj, At, Bt) do { __builtin_amdgcn_s_setprio(1); _Pragma("unroll") for (int m = 0; m < 4; ++m) _Pragma("unroll") for (int n = 0; n < 2; ++n) _Pragma("unroll") for (int k = 0; k < 2; ++k) \
;         acc[ai][bj][m][n] = __builtin_amdgcn_mfma_f32_16x16x32_bf16(Bt[n][k], At[m][k], acc[ai][bj][m][n], 0, 0, 0); __builtin_amdgcn_s_setprio(0); } while (0)
; #define PG8_WAIT_V(n) asm volatile("s_waitcnt vmcnt(" #n ")" ::: "memory")
; #define PG8_WAIT_L(n) asm volatile("s_waitcnt lgkmcnt(" #n ")" ::: "memory")
; #define PG8_BAR __builtin_amdgcn_s_barrier()
; #define PG8_SCHED __builtin_amdgcn_sched_barrier(0)
; template <class Epi, bool SP2, class Sched>
; __device__ __forceinline__ void gemm_phase(LAS unsigned char* lds, const Gemm g, const Sched& S, const Epi& E) {
;     ...
;             PG8_WAIT_V(8); PG8_WAIT_L(0); PG8_BAR; PG8_MMA(1, 0, At, B0); PG8_MMA(1, 1, At, B1); PG8_BAR; PG8_SCHED;
;             PG8_LDB(B0, 1, 0); PG8_LDB(B1, 1, 1); PG8_SCHED; PG8_LDA(At, 1, 0); PG8_STAGE(PG8_SA(0, 1), a2 + hstep, voffA);
;             PG8_WAIT_V(8); PG8_WAIT_L(0); PG8_BAR; PG8_MMA(0, 0, At, B0); PG8_MMA(0, 1, At, B1); PG8_BAR; PG8_SCHED;
	s_setprio 1
	v_mfma_f32_16x16x32_bf16 v[60:63], v[130:133], v[184:187], v[60:63]
	v_mfma_f32_16x16x32_bf16 v[56:59], v[156:159], v[184:187], v[56:59]
	v_mfma_f32_16x16x32_bf16 v[44:47], v[130:133], v[214:217], v[44:47]
	v_mfma_f32_16x16x32_bf16 v[40:43], v[156:159], v[214:217], v[40:43]
	v_mfma_f32_16x16x32_bf16 v[28:31], v[130:133], v[222:225], v[28:31]
	v_mfma_f32_16x16x32_bf16 v[24:27], v[156:159], v[222:225], v[24:27]
	v_mfma_f32_16x16x32_bf16 v[12:15], v[130:133], v[230:233], v[12:15]
	v_mfma_f32_16x16x32_bf16 v[8:11], v[156:159], v[230:233], v[8:11]
	v_mfma_f32_16x16x32_bf16 v[60:63], v[148:151], v[188:191], v[60:63]
	v_mfma_f32_16x16x32_bf16 v[56:59], v[164:167], v[188:191], v[56:59]
	v_mfma_f32_16x16x32_bf16 v[44:47], v[148:151], v[218:221], v[44:47]
	v_mfma_f32_16x16x32_bf16 v[40:43], v[164:167], v[218:221], v[40:43]
	v_mfma_f32_16x16x32_bf16 v[28:31], v[148:151], v[226:229], v[28:31]
	v_mfma_f32_16x16x32_bf16 v[24:27], v[164:167], v[226:229], v[24:27]
	v_mfma_f32_16x16x32_bf16 v[12:15], v[148:151], v[234:237], v[12:15]
	v_mfma_f32_16x16x32_bf16 v[8:11], v[164:167], v[234:237], v[8:11]
	s_setprio 0
	s_setprio 1
	v_mfma_f32_16x16x32_bf16 v[52:55], v[168:171], v[184:187], v[52:55]
	v_mfma_f32_16x16x32_bf16 v[48:51], v[176:179], v[184:187], v[48:51]
	v_mfma_f32_16x16x32_bf16 v[36:39], v[168:171], v[214:217], v[36:39]
	v_mfma_f32_16x16x32_bf16 v[32:35], v[176:179], v[214:217], v[32:35]
	v_mfma_f32_16x16x32_bf16 v[20:23], v[168:171], v[222:225], v[20:23]
	v_mfma_f32_16x16x32_bf16 v[16:19], v[176:179], v[222:225], v[16:19]
	v_mfma_f32_16x16x32_bf16 v[4:7], v[168:171], v[230:233], v[4:7]
	v_mfma_f32_16x16x32_bf16 v[0:3], v[176:179], v[230:233], v[0:3]
	v_mfma_f32_16x16x32_bf16 v[52:55], v[172:175], v[188:191], v[52:55]
	v_mfma_f32_16x16x32_bf16 v[48:51], v[180:183], v[188:191], v[48:51]
	v_mfma_f32_16x16x32_bf16 v[36:39], v[172:175], v[218:221], v[36:39]
	v_mfma_f32_16x16x32_bf16 v[32:35], v[180:183], v[218:221], v[32:35]
	v_mfma_f32_16x16x32_bf16 v[20:23], v[172:175], v[226:229], v[20:23]
	v_mfma_f32_16x16x32_bf16 v[16:19], v[180:183], v[226:229], v[16:19]
	v_mfma_f32_16x16x32_bf16 v[4:7], v[172:175], v[234:237], v[4:7]
	v_mfma_f32_16x16x32_bf16 v[0:3], v[180:183], v[234:237], v[0:3]
	s_setprio 0
	s_barrier
	s_add_i32 s24, 0, 0x18000
	v_add_u32_e32 v64, s24, v155
	s_add_i32 s25, 0, 0x1c000
	ds_read_b128 v[130:133], v64
	ds_read_b128 v[148:151], v64 offset:1024
	ds_read_b128 v[156:159], v64 offset:2048
	ds_read_b128 v[164:167], v64 offset:3072
	v_add_u32_e32 v64, s25, v155
	ds_read_b128 v[168:171], v64
	ds_read_b128 v[172:175], v64 offset:1024
	ds_read_b128 v[176:179], v64 offset:2048
	ds_read_b128 v[180:183], v64 offset:3072
	s_add_u32 s22, s96, 0x40000
	s_addc_u32 s23, s97, 0
	s_mov_b32 m0, s75
	v_lshl_add_u64 v[248:249], s[22:23], 0, v[134:135]
	ds_read_b128 v[184:187], v162 offset:32768
	ds_read_b128 v[188:191], v162 offset:33792
	ds_read_b128 v[214:217], v162 offset:34816
	ds_read_b128 v[218:221], v162 offset:35840
	ds_read_b128 v[222:225], v162 offset:36864
	ds_read_b128 v[226:229], v162 offset:37888
	ds_read_b128 v[230:233], v162 offset:38912
	ds_read_b128 v[234:237], v162 offset:39936
	global_load_lds_dwordx4 v[248:249], off
	v_lshl_add_u64 v[248:249], s[22:23], 0, v[138:139]
	s_mov_b32 m0, s76
	s_nop 0
	global_load_lds_dwordx4 v[248:249], off
	s_waitcnt vmcnt(8) lgkmcnt(0)
	s_barrier
	s_setprio 1
	v_mfma_f32_16x16x32_bf16 v[126:129], v[130:133], v[184:187], v[126:129]
	v_mfma_f32_16x16x32_bf16 v[122:125], v[156:159], v[184:187], v[122:125]
	v_mfma_f32_16x16x32_bf16 v[110:113], v[130:133], v[214:217], v[110:113]
	v_mfma_f32_16x16x32_bf16 v[106:109], v[156:159], v[214:217], v[106:109]
	v_mfma_f32_16x16x32_bf16 v[94:97], v[130:133], v[222:225], v[94:97]
	v_mfma_f32_16x16x32_bf16 v[90:93], v[156:159], v[222:225], v[90:93]
	v_mfma_f32_16x16x32_bf16 v[78:81], v[130:133], v[230:233], v[78:81]
	v_mfma_f32_16x16x32_bf16 v[74:77], v[156:159], v[230:233], v[74:77]
	v_mfma_f32_16x16x32_bf16 v[126:129], v[148:151], v[188:191], v[126:129]
	v_mfma_f32_16x16x32_bf16 v[122:125], v[164:167], v[188:191], v[122:125]
	v_mfma_f32_16x16x32_bf16 v[110:113], v[148:151], v[218:221], v[110:113]
	v_mfma_f32_16x16x32_bf16 v[106:109], v[164:167], v[218:221], v[106:109]
	v_mfma_f32_16x16x32_bf16 v[94:97], v[148:151], v[226:229], v[94:97]
	v_mfma_f32_16x16x32_bf16 v[90:93], v[164:167], v[226:229], v[90:93]
	v_mfma_f32_16x16x32_bf16 v[78:81], v[148:151], v[234:237], v[78:81]
	v_mfma_f32_16x16x32_bf16 v[74:77], v[164:167], v[234:237], v[74:77]
	s_setprio 0
	s_setprio 1
	v_mfma_f32_16x16x32_bf16 v[118:121], v[168:171], v[184:187], v[118:121]
	v_mfma_f32_16x16x32_bf16 v[114:117], v[176:179], v[184:187], v[114:117]
	v_mfma_f32_16x16x32_bf16 v[102:105], v[168:171], v[214:217], v[102:105]
	v_mfma_f32_16x16x32_bf16 v[98:101], v[176:179], v[214:217], v[98:101]
	v_mfma_f32_16x16x32_bf16 v[86:89], v[168:171], v[222:225], v[86:89]
	v_mfma_f32_16x16x32_bf16 v[82:85], v[176:179], v[222:225], v[82:85]
	v_mfma_f32_16x16x32_bf16 v[70:73], v[168:171], v[230:233], v[70:73]
	v_mfma_f32_16x16x32_bf16 v[66:69], v[176:179], v[230:233], v[66:69]
	v_mfma_f32_16x16x32_bf16 v[118:121], v[172:175], v[188:191], v[118:121]
	v_mfma_f32_16x16x32_bf16 v[114:117], v[180:183], v[188:191], v[114:117]
	v_mfma_f32_16x16x32_bf16 v[102:105], v[172:175], v[218:221], v[102:105]
	v_mfma_f32_16x16x32_bf16 v[98:101], v[180:183], v[218:221], v[98:101]
	v_mfma_f32_16x16x32_bf16 v[86:89], v[172:175], v[226:229], v[86:89]
	v_mfma_f32_16x16x32_bf16 v[82:85], v[180:183], v[226:229], v[82:85]
	v_mfma_f32_16x16x32_bf16 v[70:73], v[172:175], v[234:237], v[70:73]
	v_mfma_f32_16x16x32_bf16 v[66:69], v[180:183], v[234:237], v[66:69]
	s_setprio 0
	s_barrier
; #define PG8_STAGE(bufoff, gbase, voff) do { _Pragma("unroll") for (int _i = 0; _i < 2; ++_i) \
;         __builtin_amdgcn_global_load_lds((const unsigned*)((const char*)(gbase) + (voff)[_i]), (LAS unsigned*)(lds + (bufoff) + ldsw + _i * 8192), 16, 0, 0); } while (0)
; #define PG8_LDA(dst, b, h) do { _Pragma("unroll") for (int m = 0; m < 4; ++m) _Pragma("unroll") for (int k = 0; k < 2; ++k) dst[m][k] = *(const LAS bf16x8*)(lds + PG8_SA(b, h) + aoff + m * 2048 + k * 1024); } while (0)
; #define PG8_LDB(dst, b, h) do { _Pragma("unroll") for (int n = 0; n < 2; ++n) _Pragma("unroll") for (int k = 0; k < 2; ++k) dst[n][k] = *(const LAS bf16x8*)(lds + PG8_SB(b, h) + boff + n * 2048 + k * 1024); } while (0)
; template <class Epi, bool SP2, class Sched>
; __device__ __forceinline__ void gemm_phase(LAS unsigned char* lds, const Gemm g, const Sched& S, const Epi& E) {
;     ...
;         for (int t = 0; t < nt; t += 2) {
;             const bool last = (t == nt - 2);
;             const char* a1 = cA + (size_t)(t + 1) * kstep;
;             const char* a2 = last ? nA : cA + (size_t)(t + 2) * kstep; const char* b2 = last ? nB : cB + (size_t)(t + 2) * kstep;
;             const char* a3 = a2 + kstep; const char* b3 = b2 + kstep;
;             if constexpr (Epi::MID) { if (t == (nt >> 1)) E.mid(acc, cur, wr, fr); }
;             if constexpr (SP2) {
;             PG8_LDB(B0, 0, 0); PG8_LDB(B1, 0, 1); PG8_SCHED; PG8_LDA(At, 0, 0); PG8_STAGE(PG8_SA(1, 1), a1 + hstep, voffA);
;             PG8_WAIT_V(8); PG8_WAIT_L(0); PG8_BAR; PG8_MMA(0, 0, At, B0); PG8_MMA(0, 1, At, B1); PG8_BAR; PG8_SCHED;
;             PG8_LDA(At, 0, 1); PG8_STAGE(PG8_SB(0, 0), b2, voffB); PG8_STAGE(PG8_SB(0, 1), b2 + hstepB, voffB); PG8_STAGE(PG8_SA(0, 0), a2, voffA);
;             PG8_WAIT_V(8); PG8_WAIT_L(0); PG8_BAR; PG8_MMA(1, 0, At, B0); PG8_MMA(1, 1, At, B1); PG8_BAR; PG8_SCHED;
;             PG8_LDB(B0, 1, 0); PG8_LDB(B1, 1, 1); PG8_SCHED; PG8_LDA(At, 1, 0); PG8_STAGE(PG8_SA(0, 1), a2 + hstep, voffA);
;             PG8_WAIT_V(8); PG8_WAIT_L(0); PG8_BAR; PG8_MMA(0, 0, At, B0); PG8_MMA(0, 1, At, B1); PG8_BAR; PG8_SCHED;
;             PG8_LDA(At, 1, 1); PG8_STAGE(PG8_SB(1, 0), b3, voffB); PG8_STAGE(PG8_SB(1, 1), b3 + hstepB, voffB); PG8_STAGE(PG8_SA(1, 0), a3, voffA);
;             PG8_WAIT_V(8); PG8_WAIT_L(0); PG8_BAR; PG8_MMA(1, 0, At, B0); PG8_MMA(1, 1, At, B1); PG8_BAR; PG8_SCHED;
	s_add_i32 s22, s24, s72
	v_lshl_add_u64 v[152:153], v[152:153], 0, s[66:67]
	s_mov_b32 m0, s22
	ds_read_b128 v[184:187], v162 offset:49152
	ds_read_b128 v[188:191], v162 offset:50176
	ds_read_b128 v[214:217], v162 offset:51200
	ds_read_b128 v[218:221], v162 offset:52224
	ds_read_b128 v[222:225], v162 offset:53248
	ds_read_b128 v[226:229], v162 offset:54272
	ds_read_b128 v[230:233], v162 offset:55296
	ds_read_b128 v[234:237], v162 offset:56320
	global_load_lds_dwordx4 v[152:153], off
	s_add_i32 m0, s22, 0x2000
	s_add_u32 s10, s10, 0x40080
	v_lshl_add_u64 v[152:153], v[192:193], 0, s[66:67]
	s_addc_u32 s11, s11, 0
	s_add_i32 s22, s25, s72
	global_load_lds_dwordx4 v[152:153], off
	v_lshl_add_u64 v[152:153], s[10:11], 0, v[136:137]
	s_mov_b32 m0, s22
	s_nop 0
	global_load_lds_dwordx4 v[152:153], off
	v_lshl_add_u64 v[152:153], s[10:11], 0, v[140:141]
	s_add_i32 m0, s22, 0x2000
	s_nop 0
	global_load_lds_dwordx4 v[152:153], off
	v_lshl_add_u64 v[152:153], v[238:239], 0, s[66:67]
	s_mov_b32 m0, s14
	s_nop 0
	global_load_lds_dwordx4 v[152:153], off
	v_lshl_add_u64 v[152:153], v[240:241], 0, s[66:67]
	s_mov_b32 m0, s15
	s_nop 0
	global_load_lds_dwordx4 v[152:153], off
	s_waitcnt vmcnt(8) lgkmcnt(0)
	s_barrier
	s_setprio 1
	v_mfma_f32_16x16x32_bf16 v[60:63], v[130:133], v[184:187], v[60:63]
	v_mfma_f32_16x16x32_bf16 v[56:59], v[156:159], v[184:187], v[56:59]
	v_mfma_f32_16x16x32_bf16 v[44:47], v[130:133], v[214:217], v[44:47]
	v_mfma_f32_16x16x32_bf16 v[40:43], v[156:159], v[214:217], v[40:43]
	v_mfma_f32_16x16x32_bf16 v[28:31], v[130:133], v[222:225], v[28:31]
	v_mfma_f32_16x16x32_bf16 v[24:27], v[156:159], v[222:225], v[24:27]
	v_mfma_f32_16x16x32_bf16 v[12:15], v[130:133], v[230:233], v[12:15]
	v_mfma_f32_16x16x32_bf16 v[8:11], v[156:159], v[230:233], v[8:11]
	v_mfma_f32_16x16x32_bf16 v[60:63], v[148:151], v[188:191], v[60:63]
	v_mfma_f32_16x16x32_bf16 v[56:59], v[164:167], v[188:191], v[56:59]
	v_mfma_f32_16x16x32_bf16 v[44:47], v[148:151], v[218:221], v[44:47]
	v_mfma_f32_16x16x32_bf16 v[40:43], v[164:167], v[218:221], v[40:43]
	v_mfma_f32_16x16x32_bf16 v[28:31], v[148:151], v[226:229], v[28:31]
	v_mfma_f32_16x16x32_bf16 v[24:27], v[164:167], v[226:229], v[24:27]
	v_mfma_f32_16x16x32_bf16 v[12:15], v[148:151], v[234:237], v[12:15]
	v_mfma_f32_16x16x32_bf16 v[8:11], v[164:167], v[234:237], v[8:11]
	s_setprio 0
	s_setprio 1
	v_mfma_f32_16x16x32_bf16 v[52:55], v[168:171], v[184:187], v[52:55]
	v_mfma_f32_16x16x32_bf16 v[48:51], v[176:179], v[184:187], v[48:51]
	v_mfma_f32_16x16x32_bf16 v[36:39], v[168:171], v[214:217], v[36:39]
	v_mfma_f32_16x16x32_bf16 v[32:35], v[176:179], v[214:217], v[32:35]
	v_mfma_f32_16x16x32_bf16 v[20:23], v[168:171], v[222:225], v[20:23]
	v_mfma_f32_16x16x32_bf16 v[16:19], v[176:179], v[222:225], v[16:19]
	v_mfma_f32_16x16x32_bf16 v[4:7], v[168:171], v[230:233], v[4:7]
	v_mfma_f32_16x16x32_bf16 v[0:3], v[176:179], v[230:233], v[0:3]
	v_mfma_f32_16x16x32_bf16 v[52:55], v[172:175], v[188:191], v[52:55]
	v_mfma_f32_16x16x32_bf16 v[48:51], v[180:183], v[188:191], v[48:51]
	v_mfma_f32_16x16x32_bf16 v[36:39], v[172:175], v[218:221], v[36:39]
	v_mfma_f32_16x16x32_bf16 v[32:35], v[180:183], v[218:221], v[32:35]
	v_mfma_f32_16x16x32_bf16 v[20:23], v[172:175], v[226:229], v[20:23]
	v_mfma_f32_16x16x32_bf16 v[16:19], v[180:183], v[226:229], v[16:19]
	v_mfma_f32_16x16x32_bf16 v[4:7], v[172:175], v[234:237], v[4:7]
	v_mfma_f32_16x16x32_bf16 v[0:3], v[180:183], v[234:237], v[0:3]
	s_setprio 0
	s_barrier
	s_add_i32 s21, s21, 2
	s_add_u32 s95, s95, 0x100
	s_addc_u32 s20, s20, 0
	s_add_u32 vcc_lo, vcc_lo, 0x100
	s_addc_u32 vcc_hi, vcc_hi, 0
	s_cmp_gt_u32 s21, 13
	s_cbranch_scc0 .LBB0_313
	s_and_b64 vcc, exec, s[88:89]
	s_cbranch_vccz .LBB0_316
	s_barrier

; #define PG8_STAGE(bufoff, gbase, voff) do { _Pragma("unroll") for (int _i = 0; _i < 2; ++_i) \
;         __builtin_amdgcn_global_load_lds((const unsigned*)((const char*)(gbase) + (voff)[_i]), (LAS unsigned*)(lds + (bufoff) + ldsw + _i * 8192), 16, 0, 0); } while (0)
; #define PG8_LDA(dst, b, h) do { _Pragma("unroll") for (int m = 0; m < 4; ++m) _Pragma("unroll") for (int k = 0; k < 2; ++k) dst[m][k] = *(const LAS bf16x8*)(lds + PG8_SA(b, h) + aoff + m * 2048 + k * 1024); } while (0)
; #define PG8_LDB(dst, b, h) do { _Pragma("unroll") for (int n = 0; n < 2; ++n) _Pragma("unroll") for (int k = 0; k < 2; ++k) dst[n][k] = *(const LAS bf16x8*)(lds + PG8_SB(b, h) + boff + n * 2048 + k * 1024); } while (0)
; #define PG8_MMA(ai, bj, At, Bt) do { __builtin_amdgcn_s_setprio(1); _Pragma("unroll") for (int m = 0; m < 4; ++m) _Pragma("unroll") for (int n = 0; n < 2; ++n) _Pragma("unroll") for (int k = 0; k < 2; ++k) \
;         acc[ai][bj][m][n] = __builtin_amdgcn_mfma_f32_16x16x32_bf16(Bt[n][k], At[m][k], acc[ai][bj][m][n], 0, 0, 0); __builtin_amdgcn_s_setprio(0); } while (0)
; #define PG8_WAIT_V(n) asm volatile("s_waitcnt vmcnt(" #n ")" ::: "memory")
; #define PG8_WAIT_L(n) asm volatile("s_waitcnt lgkmcnt(" #n ")" ::: "memory")
; #define PG8_BAR __builtin_amdgcn_s_barrier()
; #define PG8_SCHED __builtin_amdgcn_sched_barrier(0)
; template <class Epi, bool SP2, class Sched>
; __device__ __forceinline__ void gemm_phase(LAS unsigned char* lds, const Gemm g, const Sched& S, const Epi& E) {
;     ...
;             PG8_LDB(B0, 0, 0); PG8_LDB(B1, 0, 1); PG8_SCHED; PG8_LDA(At, 0, 0); PG8_STAGE(PG8_SA(1, 1), a1 + hstep, voffA);
;             PG8_WAIT_V(8); PG8_WAIT_L(0); PG8_BAR; PG8_MMA(0, 0, At, B0); PG8_MMA(0, 1, At, B1); PG8_BAR; PG8_SCHED;
;             PG8_LDA(At, 0, 1); PG8_STAGE(PG8_SB(0, 0), b2, voffB); PG8_STAGE(PG8_SB(0, 1), b2 + hstepB, voffB); PG8_STAGE(PG8_SA(0, 0), a2, voffA);
.LBB0_381:
	s_add_u32 s6, s90, 0xfffc0080
	s_addc_u32 s7, s91, -1
	s_add_i32 s22, 0, 0x10000
	s_cmp_eq_u32 s21, 12
	s_cselect_b32 s11, s74, s7
	s_cselect_b32 s10, s75, s6
	s_cselect_b32 s7, s61, s20
	s_cselect_b32 s6, s76, s77
	s_add_i32 s24, 0, 0x14000
	v_add_u32_e32 v110, s22, v163
	v_add_u32_e32 v160, s24, v163
	ds_read_b128 v[98:101], v110
	ds_read_b128 v[102:105], v110 offset:1024
	ds_read_b128 v[106:109], v110 offset:2048
	ds_read_b128 v[110:113], v110 offset:3072
	ds_read_b128 v[156:159], v160
	ds_read_b128 v[166:169], v160 offset:1024
	ds_read_b128 v[170:173], v160 offset:2048
	ds_read_b128 v[174:177], v160 offset:3072
	v_lshl_add_u64 v[160:161], s[90:91], 0, v[154:155]
	s_add_i32 m0, s17, 0xc000
	ds_read_b128 v[178:181], v165
	ds_read_b128 v[182:185], v165 offset:1024
	ds_read_b128 v[186:189], v165 offset:2048
	ds_read_b128 v[190:193], v165 offset:3072
	ds_read_b128 v[214:217], v165 offset:4096
	ds_read_b128 v[218:221], v165 offset:5120
	ds_read_b128 v[222:225], v165 offset:6144
	ds_read_b128 v[226:229], v165 offset:7168
	global_load_lds_dwordx4 v[160:161], off
	v_lshl_add_u64 v[160:161], s[90:91], 0, v[152:153]
	s_add_i32 m0, s17, 0xe000
	s_nop 0
	global_load_lds_dwordx4 v[160:161], off
	s_waitcnt vmcnt(8) lgkmcnt(0)
	s_barrier
	s_setprio 1
	v_mfma_f32_16x16x32_bf16 v[142:145], v[98:101], v[178:181], v[142:145]
	v_mfma_f32_16x16x32_bf16 v[138:141], v[106:109], v[178:181], v[138:141]
	v_mfma_f32_16x16x32_bf16 v[126:129], v[98:101], v[186:189], v[126:129]
	v_mfma_f32_16x16x32_bf16 v[122:125], v[106:109], v[186:189], v[122:125]
	v_mfma_f32_16x16x32_bf16 v[94:97], v[98:101], v[214:217], v[94:97]
	v_mfma_f32_16x16x32_bf16 v[90:93], v[106:109], v[214:217], v[90:93]
	v_mfma_f32_16x16x32_bf16 v[78:81], v[98:101], v[222:225], v[78:81]
	v_mfma_f32_16x16x32_bf16 v[74:77], v[106:109], v[222:225], v[74:77]
	v_mfma_f32_16x16x32_bf16 v[142:145], v[102:105], v[182:185], v[142:145]
	v_mfma_f32_16x16x32_bf16 v[138:141], v[110:113], v[182:185], v[138:141]
	v_mfma_f32_16x16x32_bf16 v[126:129], v[102:105], v[190:193], v[126:129]
	v_mfma_f32_16x16x32_bf16 v[122:125], v[110:113], v[190:193], v[122:125]
	v_mfma_f32_16x16x32_bf16 v[94:97], v[102:105], v[218:221], v[94:97]
	v_mfma_f32_16x16x32_bf16 v[90:93], v[110:113], v[218:221], v[90:93]
	v_mfma_f32_16x16x32_bf16 v[78:81], v[102:105], v[226:229], v[78:81]
	v_mfma_f32_16x16x32_bf16 v[74:77], v[110:113], v[226:229], v[74:77]
	s_setprio 0
	s_setprio 1
	v_mfma_f32_16x16x32_bf16 v[134:137], v[156:159], v[178:181], v[134:137]
	v_mfma_f32_16x16x32_bf16 v[130:133], v[170:173], v[178:181], v[130:133]
	v_mfma_f32_16x16x32_bf16 v[118:121], v[156:159], v[186:189], v[118:121]
	v_mfma_f32_16x16x32_bf16 v[114:117], v[170:173], v[186:189], v[114:117]
	v_mfma_f32_16x16x32_bf16 v[86:89], v[156:159], v[214:217], v[86:89]
	v_mfma_f32_16x16x32_bf16 v[82:85], v[170:173], v[214:217], v[82:85]
	v_mfma_f32_16x16x32_bf16 v[70:73], v[156:159], v[222:225], v[70:73]
	v_mfma_f32_16x16x32_bf16 v[66:69], v[170:173], v[222:225], v[66:69]
	v_mfma_f32_16x16x32_bf16 v[134:137], v[166:169], v[182:185], v[134:137]
	v_mfma_f32_16x16x32_bf16 v[130:133], v[174:177], v[182:185], v[130:133]
	v_mfma_f32_16x16x32_bf16 v[118:121], v[166:169], v[190:193], v[118:121]
	v_mfma_f32_16x16x32_bf16 v[114:117], v[174:177], v[190:193], v[114:117]
	v_mfma_f32_16x16x32_bf16 v[86:89], v[166:169], v[218:221], v[86:89]
	v_mfma_f32_16x16x32_bf16 v[82:85], v[174:177], v[218:221], v[82:85]
	v_mfma_f32_16x16x32_bf16 v[70:73], v[166:169], v[226:229], v[70:73]
	v_mfma_f32_16x16x32_bf16 v[66:69], v[174:177], v[226:229], v[66:69]
	s_setprio 0
	s_barrier
	s_add_i32 s22, s22, s19
	v_lshl_add_u64 v[160:161], s[6:7], 0, v[64:65]
	s_mov_b32 m0, s22
	ds_read_b128 v[178:181], v165 offset:16384
	ds_read_b128 v[182:185], v165 offset:17408
	ds_read_b128 v[186:189], v165 offset:18432
	ds_read_b128 v[190:193], v165 offset:19456
	ds_read_b128 v[214:217], v165 offset:20480
	ds_read_b128 v[218:221], v165 offset:21504
	ds_read_b128 v[222:225], v165 offset:22528
	ds_read_b128 v[226:229], v165 offset:23552
	global_load_lds_dwordx4 v[160:161], off
	s_add_i32 m0, s22, 0x2000
	s_add_u32 s22, s6, 0x40000
	v_lshl_add_u64 v[230:231], s[6:7], 0, v[150:151]
	s_addc_u32 s23, s7, 0
	s_add_i32 s24, s24, s19
	global_load_lds_dwordx4 v[230:231], off
	v_lshl_add_u64 v[232:233], s[22:23], 0, v[64:65]
	s_mov_b32 m0, s24
	v_lshl_add_u64 v[234:235], s[10:11], 0, v[148:149]
	global_load_lds_dwordx4 v[232:233], off
	v_lshl_add_u64 v[232:233], s[22:23], 0, v[150:151]
	s_add_i32 m0, s24, 0x2000
	s_nop 0
	global_load_lds_dwordx4 v[232:233], off
	v_lshl_add_u64 v[232:233], s[10:11], 0, v[146:147]
	s_mov_b32 m0, s17
	s_nop 0
	global_load_lds_dwordx4 v[232:233], off
	s_mov_b32 m0, s33
	s_nop 0
	global_load_lds_dwordx4 v[234:235], off
	s_waitcnt vmcnt(8) lgkmcnt(0)
	s_barrier
; #define PG8_STAGE(bufoff, gbase, voff) do { _Pragma("unroll") for (int _i = 0; _i < 2; ++_i) \
;         __builtin_amdgcn_global_load_lds((const unsigned*)((const char*)(gbase) + (voff)[_i]), (LAS unsigned*)(lds + (bufoff) + ldsw + _i * 8192), 16, 0, 0); } while (0)
; #define PG8_LDA(dst, b, h) do { _Pragma("unroll") for (int m = 0; m < 4; ++m) _Pragma("unroll") for (int k = 0; k < 2; ++k) dst[m][k] = *(const LAS bf16x8*)(lds + PG8_SA(b, h) + aoff + m * 2048 + k * 1024); } while (0)
; #define PG8_LDB(dst, b, h) do { _Pragma("unroll") for (int n = 0; n < 2; ++n) _Pragma("unroll") for (int k = 0; k < 2; ++k) dst[n][k] = *(const LAS bf16x8*)(lds + PG8_SB(b, h) + boff + n * 2048 + k * 1024); } while (0)
; #define PG8_MMA(ai, bj, At, Bt) do { __builtin_amdgcn_s_setprio(1); _Pragma("unroll") for (int m = 0; m < 4; ++m) _Pragma("unroll") for (int n = 0; n < 2; ++n) _Pragma("unroll") for (int k = 0; k < 2; ++k) \
;         acc[ai][bj][m][n] = __builtin_amdgcn_mfma_f32_16x16x32_bf16(Bt[n][k], At[m][k], acc[ai][bj][m][n], 0, 0, 0); __builtin_amdgcn_s_setprio(0); } while (0)
; #define PG8_WAIT_V(n) asm volatile("s_waitcnt vmcnt(" #n ")" ::: "memory")
; #define PG8_WAIT_L(n) asm volatile("s_waitcnt lgkmcnt(" #n ")" ::: "memory")
; #define PG8_BAR __builtin_amdgcn_s_barrier()
; #define PG8_SCHED __builtin_amdgcn_sched_barrier(0)
; template <class Epi, bool SP2, class Sched>
; __device__ __forceinline__ void gemm_phase(LAS unsigned char* lds, const Gemm g, const Sched& S, const Epi& E) {
;     ...
;             PG8_WAIT_V(8); PG8_WAIT_L(0); PG8_BAR; PG8_MMA(1, 0, At, B0); PG8_MMA(1, 1, At, B1); PG8_BAR; PG8_SCHED;
;             PG8_LDB(B0, 1, 0); PG8_LDB(B1, 1, 1); PG8_SCHED; PG8_LDA(At, 1, 0); PG8_STAGE(PG8_SA(0, 1), a2 + hstep, voffA);
;             PG8_WAIT_V(8); PG8_WAIT_L(0); PG8_BAR; PG8_MMA(0, 0, At, B0); PG8_MMA(0, 1, At, B1); PG8_BAR; PG8_SCHED;
	s_setprio 1
	v_mfma_f32_16x16x32_bf16 v[60:63], v[98:101], v[178:181], v[60:63]
	v_mfma_f32_16x16x32_bf16 v[56:59], v[106:109], v[178:181], v[56:59]
	v_mfma_f32_16x16x32_bf16 v[48:51], v[98:101], v[186:189], v[48:51]
	v_mfma_f32_16x16x32_bf16 v[40:43], v[106:109], v[186:189], v[40:43]
	v_mfma_f32_16x16x32_bf16 v[32:35], v[98:101], v[214:217], v[32:35]
	v_mfma_f32_16x16x32_bf16 v[24:27], v[106:109], v[214:217], v[24:27]
	v_mfma_f32_16x16x32_bf16 v[16:19], v[98:101], v[222:225], v[16:19]
	v_mfma_f32_16x16x32_bf16 v[8:11], v[106:109], v[222:225], v[8:11]
	v_mfma_f32_16x16x32_bf16 v[60:63], v[102:105], v[182:185], v[60:63]
	v_mfma_f32_16x16x32_bf16 v[56:59], v[110:113], v[182:185], v[56:59]
	v_mfma_f32_16x16x32_bf16 v[48:51], v[102:105], v[190:193], v[48:51]
	v_mfma_f32_16x16x32_bf16 v[40:43], v[110:113], v[190:193], v[40:43]
	v_mfma_f32_16x16x32_bf16 v[32:35], v[102:105], v[218:221], v[32:35]
	v_mfma_f32_16x16x32_bf16 v[24:27], v[110:113], v[218:221], v[24:27]
	v_mfma_f32_16x16x32_bf16 v[16:19], v[102:105], v[226:229], v[16:19]
	v_mfma_f32_16x16x32_bf16 v[8:11], v[110:113], v[226:229], v[8:11]
	s_setprio 0
	s_setprio 1
	v_mfma_f32_16x16x32_bf16 v[52:55], v[156:159], v[178:181], v[52:55]
	v_mfma_f32_16x16x32_bf16 v[44:47], v[170:173], v[178:181], v[44:47]
	v_mfma_f32_16x16x32_bf16 v[36:39], v[156:159], v[186:189], v[36:39]
	v_mfma_f32_16x16x32_bf16 v[28:31], v[170:173], v[186:189], v[28:31]
	v_mfma_f32_16x16x32_bf16 v[20:23], v[156:159], v[214:217], v[20:23]
	v_mfma_f32_16x16x32_bf16 v[12:15], v[170:173], v[214:217], v[12:15]
	v_mfma_f32_16x16x32_bf16 v[4:7], v[156:159], v[222:225], v[4:7]
	v_mfma_f32_16x16x32_bf16 v[0:3], v[170:173], v[222:225], v[0:3]
	v_mfma_f32_16x16x32_bf16 v[52:55], v[166:169], v[182:185], v[52:55]
	v_mfma_f32_16x16x32_bf16 v[44:47], v[174:177], v[182:185], v[44:47]
	v_mfma_f32_16x16x32_bf16 v[36:39], v[166:169], v[190:193], v[36:39]
	v_mfma_f32_16x16x32_bf16 v[28:31], v[174:177], v[190:193], v[28:31]
	v_mfma_f32_16x16x32_bf16 v[20:23], v[166:169], v[218:221], v[20:23]
	v_mfma_f32_16x16x32_bf16 v[12:15], v[174:177], v[218:221], v[12:15]
	v_mfma_f32_16x16x32_bf16 v[4:7], v[166:169], v[226:229], v[4:7]
	v_mfma_f32_16x16x32_bf16 v[0:3], v[174:177], v[226:229], v[0:3]
	s_setprio 0
	s_barrier
	s_add_i32 s22, 0, 0x18000
	s_add_i32 s23, 0, 0x1c000
	v_add_u32_e32 v110, s22, v163
	v_add_u32_e32 v174, s23, v163
	ds_read_b128 v[98:101], v110
	ds_read_b128 v[102:105], v110 offset:1024
	ds_read_b128 v[106:109], v110 offset:2048
	ds_read_b128 v[110:113], v110 offset:3072
	ds_read_b128 v[156:159], v174
	ds_read_b128 v[166:169], v174 offset:1024
	ds_read_b128 v[170:173], v174 offset:2048
	ds_read_b128 v[174:177], v174 offset:3072
	s_add_u32 s10, s10, 0x40000
	s_addc_u32 s11, s11, 0
	s_mov_b32 m0, s62
	v_lshl_add_u64 v[236:237], s[10:11], 0, v[146:147]
	ds_read_b128 v[178:181], v165 offset:32768
	ds_read_b128 v[182:185], v165 offset:33792
	ds_read_b128 v[186:189], v165 offset:34816
	ds_read_b128 v[190:193], v165 offset:35840
	ds_read_b128 v[214:217], v165 offset:36864
	ds_read_b128 v[218:221], v165 offset:37888
	ds_read_b128 v[222:225], v165 offset:38912
	ds_read_b128 v[226:229], v165 offset:39936
	global_load_lds_dwordx4 v[236:237], off
	v_lshl_add_u64 v[236:237], s[10:11], 0, v[148:149]
	s_mov_b32 m0, s64
	s_nop 0
	global_load_lds_dwordx4 v[236:237], off
	s_waitcnt vmcnt(8) lgkmcnt(0)
	s_barrier
	s_setprio 1
	v_mfma_f32_16x16x32_bf16 v[142:145], v[98:101], v[178:181], v[142:145]
	v_mfma_f32_16x16x32_bf16 v[138:141], v[106:109], v[178:181], v[138:141]
	v_mfma_f32_16x16x32_bf16 v[126:129], v[98:101], v[186:189], v[126:129]
	v_mfma_f32_16x16x32_bf16 v[122:125], v[106:109], v[186:189], v[122:125]
	v_mfma_f32_16x16x32_bf16 v[94:97], v[98:101], v[214:217], v[94:97]
	v_mfma_f32_16x16x32_bf16 v[90:93], v[106:109], v[214:217], v[90:93]
	v_mfma_f32_16x16x32_bf16 v[78:81], v[98:101], v[222:225], v[78:81]
	v_mfma_f32_16x16x32_bf16 v[74:77], v[106:109], v[222:225], v[74:77]
	v_mfma_f32_16x16x32_bf16 v[142:145], v[102:105], v[182:185], v[142:145]
	v_mfma_f32_16x16x32_bf16 v[138:141], v[110:113], v[182:185], v[138:141]
	v_mfma_f32_16x16x32_bf16 v[126:129], v[102:105], v[190:193], v[126:129]
	v_mfma_f32_16x16x32_bf16 v[122:125], v[110:113], v[190:193], v[122:125]
	v_mfma_f32_16x16x32_bf16 v[94:97], v[102:105], v[218:221], v[94:97]
	v_mfma_f32_16x16x32_bf16 v[90:93], v[110:113], v[218:221], v[90:93]
	v_mfma_f32_16x16x32_bf16 v[78:81], v[102:105], v[226:229], v[78:81]
	v_mfma_f32_16x16x32_bf16 v[74:77], v[110:113], v[226:229], v[74:77]
	s_setprio 0
	s_setprio 1
	v_mfma_f32_16x16x32_bf16 v[134:137], v[156:159], v[178:181], v[134:137]
	v_mfma_f32_16x16x32_bf16 v[130:133], v[170:173], v[178:181], v[130:133]
	v_mfma_f32_16x16x32_bf16 v[118:121], v[156:159], v[186:189], v[118:121]
	v_mfma_f32_16x16x32_bf16 v[114:117], v[170:173], v[186:189], v[114:117]
	v_mfma_f32_16x16x32_bf16 v[86:89], v[156:159], v[214:217], v[86:89]
	v_mfma_f32_16x16x32_bf16 v[82:85], v[170:173], v[214:217], v[82:85]
	v_mfma_f32_16x16x32_bf16 v[70:73], v[156:159], v[222:225], v[70:73]
	v_mfma_f32_16x16x32_bf16 v[66:69], v[170:173], v[222:225], v[66:69]
	v_mfma_f32_16x16x32_bf16 v[134:137], v[166:169], v[182:185], v[134:137]
	v_mfma_f32_16x16x32_bf16 v[130:133], v[174:177], v[182:185], v[130:133]
	v_mfma_f32_16x16x32_bf16 v[118:121], v[166:169], v[190:193], v[118:121]
	v_mfma_f32_16x16x32_bf16 v[114:117], v[174:177], v[190:193], v[114:117]
	v_mfma_f32_16x16x32_bf16 v[86:89], v[166:169], v[218:221], v[86:89]
	v_mfma_f32_16x16x32_bf16 v[82:85], v[174:177], v[218:221], v[82:85]
	v_mfma_f32_16x16x32_bf16 v[70:73], v[166:169], v[226:229], v[70:73]
	v_mfma_f32_16x16x32_bf16 v[66:69], v[174:177], v[226:229], v[66:69]
	s_setprio 0
	s_barrier
; #define PG8_STAGE(bufoff, gbase, voff) do { _Pragma("unroll") for (int _i = 0; _i < 2; ++_i) \
;         __builtin_amdgcn_global_load_lds((const unsigned*)((const char*)(gbase) + (voff)[_i]), (LAS unsigned*)(lds + (bufoff) + ldsw + _i * 8192), 16, 0, 0); } while (0)
; #define PG8_LDA(dst, b, h) do { _Pragma("unroll") for (int m = 0; m < 4; ++m) _Pragma("unroll") for (int k = 0; k < 2; ++k) dst[m][k] = *(const LAS bf16x8*)(lds + PG8_SA(b, h) + aoff + m * 2048 + k * 1024); } while (0)
; #define PG8_MMA(ai, bj, At, Bt) do { __builtin_amdgcn_s_setprio(1); _Pragma("unroll") for (int m = 0; m < 4; ++m) _Pragma("unroll") for (int n = 0; n < 2; ++n) _Pragma("unroll") for (int k = 0; k < 2; ++k) \
;         acc[ai][bj][m][n] = __builtin_amdgcn_mfma_f32_16x16x32_bf16(Bt[n][k], At[m][k], acc[ai][bj][m][n], 0, 0, 0); __builtin_amdgcn_s_setprio(0); } while (0)
; #define PG8_WAIT_V(n) asm volatile("s_waitcnt vmcnt(" #n ")" ::: "memory")
; #define PG8_WAIT_L(n) asm volatile("s_waitcnt lgkmcnt(" #n ")" ::: "memory")
; #define PG8_BAR __builtin_amdgcn_s_barrier()
; #define PG8_SCHED __builtin_amdgcn_sched_barrier(0)
; template <class Epi, bool SP2, class Sched>
; __device__ __forceinline__ void gemm_phase(LAS unsigned char* lds, const Gemm g, const Sched& S, const Epi& E) {
;     ...
;         for (int t = 0; t < nt; t += 2) {
;     ...
;             PG8_LDA(At, 1, 1); PG8_STAGE(PG8_SB(1, 0), b3, voffB); PG8_STAGE(PG8_SB(1, 1), b3 + hstepB, voffB); PG8_STAGE(PG8_SA(1, 0), a3, voffA);
;             PG8_WAIT_V(8); PG8_WAIT_L(0); PG8_BAR; PG8_MMA(1, 0, At, B0); PG8_MMA(1, 1, At, B1); PG8_BAR; PG8_SCHED;
;     ...
;         if (wr == 0) PG8_BAR;
	s_add_i32 s10, s22, s19
	v_lshl_add_u64 v[160:161], v[160:161], 0, s[66:67]
	s_mov_b32 m0, s10
	ds_read_b128 v[178:181], v165 offset:49152
	ds_read_b128 v[182:185], v165 offset:50176
	ds_read_b128 v[186:189], v165 offset:51200
	ds_read_b128 v[190:193], v165 offset:52224
	ds_read_b128 v[214:217], v165 offset:53248
	ds_read_b128 v[218:221], v165 offset:54272
	ds_read_b128 v[222:225], v165 offset:55296
	ds_read_b128 v[226:229], v165 offset:56320
	global_load_lds_dwordx4 v[160:161], off
	s_add_i32 m0, s10, 0x2000
	s_add_u32 s6, s6, 0x40080
	v_lshl_add_u64 v[160:161], v[230:231], 0, s[66:67]
	s_addc_u32 s7, s7, 0
	s_add_i32 s10, s23, s19
	global_load_lds_dwordx4 v[160:161], off
	v_lshl_add_u64 v[160:161], s[6:7], 0, v[64:65]
	s_mov_b32 m0, s10
	s_nop 0
	global_load_lds_dwordx4 v[160:161], off
	v_lshl_add_u64 v[160:161], s[6:7], 0, v[150:151]
	s_add_i32 m0, s10, 0x2000
	s_nop 0
	global_load_lds_dwordx4 v[160:161], off
	v_lshl_add_u64 v[160:161], v[232:233], 0, s[66:67]
	s_mov_b32 m0, s65
	s_nop 0
	global_load_lds_dwordx4 v[160:161], off
	v_lshl_add_u64 v[160:161], v[234:235], 0, s[66:67]
	s_mov_b32 m0, s68
	s_nop 0
	global_load_lds_dwordx4 v[160:161], off
	s_waitcnt vmcnt(8) lgkmcnt(0)
	s_barrier
	s_setprio 1
	v_mfma_f32_16x16x32_bf16 v[60:63], v[98:101], v[178:181], v[60:63]
	v_mfma_f32_16x16x32_bf16 v[56:59], v[106:109], v[178:181], v[56:59]
	v_mfma_f32_16x16x32_bf16 v[48:51], v[98:101], v[186:189], v[48:51]
	v_mfma_f32_16x16x32_bf16 v[40:43], v[106:109], v[186:189], v[40:43]
	v_mfma_f32_16x16x32_bf16 v[32:35], v[98:101], v[214:217], v[32:35]
	v_mfma_f32_16x16x32_bf16 v[24:27], v[106:109], v[214:217], v[24:27]
	v_mfma_f32_16x16x32_bf16 v[16:19], v[98:101], v[222:225], v[16:19]
	v_mfma_f32_16x16x32_bf16 v[8:11], v[106:109], v[222:225], v[8:11]
	v_mfma_f32_16x16x32_bf16 v[60:63], v[102:105], v[182:185], v[60:63]
	v_mfma_f32_16x16x32_bf16 v[56:59], v[110:113], v[182:185], v[56:59]
	v_mfma_f32_16x16x32_bf16 v[48:51], v[102:105], v[190:193], v[48:51]
	v_mfma_f32_16x16x32_bf16 v[40:43], v[110:113], v[190:193], v[40:43]
	v_mfma_f32_16x16x32_bf16 v[32:35], v[102:105], v[218:221], v[32:35]
	v_mfma_f32_16x16x32_bf16 v[24:27], v[110:113], v[218:221], v[24:27]
	v_mfma_f32_16x16x32_bf16 v[16:19], v[102:105], v[226:229], v[16:19]
	v_mfma_f32_16x16x32_bf16 v[8:11], v[110:113], v[226:229], v[8:11]
	s_setprio 0
	s_setprio 1
	v_mfma_f32_16x16x32_bf16 v[52:55], v[156:159], v[178:181], v[52:55]
	v_mfma_f32_16x16x32_bf16 v[44:47], v[170:173], v[178:181], v[44:47]
	v_mfma_f32_16x16x32_bf16 v[36:39], v[156:159], v[186:189], v[36:39]
	v_mfma_f32_16x16x32_bf16 v[28:31], v[170:173], v[186:189], v[28:31]
	v_mfma_f32_16x16x32_bf16 v[20:23], v[156:159], v[214:217], v[20:23]
	v_mfma_f32_16x16x32_bf16 v[12:15], v[170:173], v[214:217], v[12:15]
	v_mfma_f32_16x16x32_bf16 v[4:7], v[156:159], v[222:225], v[4:7]
	v_mfma_f32_16x16x32_bf16 v[0:3], v[170:173], v[222:225], v[0:3]
	v_mfma_f32_16x16x32_bf16 v[52:55], v[166:169], v[182:185], v[52:55]
	v_mfma_f32_16x16x32_bf16 v[44:47], v[174:177], v[182:185], v[44:47]
	v_mfma_f32_16x16x32_bf16 v[36:39], v[166:169], v[190:193], v[36:39]
	v_mfma_f32_16x16x32_bf16 v[28:31], v[174:177], v[190:193], v[28:31]
	v_mfma_f32_16x16x32_bf16 v[20:23], v[166:169], v[218:221], v[20:23]
	v_mfma_f32_16x16x32_bf16 v[12:15], v[174:177], v[218:221], v[12:15]
	v_mfma_f32_16x16x32_bf16 v[4:7], v[166:169], v[226:229], v[4:7]
	v_mfma_f32_16x16x32_bf16 v[0:3], v[174:177], v[226:229], v[0:3]
	s_setprio 0
	s_barrier
	s_add_i32 s21, s21, 2
	s_add_u32 s77, s77, 0x100
	s_addc_u32 s20, s20, 0
	s_add_u32 s90, s90, 0x100
	s_addc_u32 s91, s91, 0
	s_cmp_gt_u32 s21, 13
	s_cbranch_scc0 .LBB0_381
	s_and_b64 vcc, exec, s[58:59]
	s_cbranch_vccz .LBB0_384
	s_barrier

; #define PG8_STAGE(bufoff, gbase, voff) do { _Pragma("unroll") for (int _i = 0; _i < 2; ++_i) \
;         __builtin_amdgcn_global_load_lds((const unsigned*)((const char*)(gbase) + (voff)[_i]), (LAS unsigned*)(lds + (bufoff) + ldsw + _i * 8192), 16, 0, 0); } while (0)
; #define PG8_LDA(dst, b, h) do { _Pragma("unroll") for (int m = 0; m < 4; ++m) _Pragma("unroll") for (int k = 0; k < 2; ++k) dst[m][k] = *(const LAS bf16x8*)(lds + PG8_SA(b, h) + aoff + m * 2048 + k * 1024); } while (0)
; #define PG8_LDB(dst, b, h) do { _Pragma("unroll") for (int n = 0; n < 2; ++n) _Pragma("unroll") for (int k = 0; k < 2; ++k) dst[n][k] = *(const LAS bf16x8*)(lds + PG8_SB(b, h) + boff + n * 2048 + k * 1024); } while (0)
; #define PG8_MMA(ai, bj, At, Bt) do { __builtin_amdgcn_s_setprio(1); _Pragma("unroll") for (int m = 0; m < 4; ++m) _Pragma("unroll") for (int n = 0; n < 2; ++n) _Pragma("unroll") for (int k = 0; k < 2; ++k) \
;         acc[ai][bj][m][n] = __builtin_amdgcn_mfma_f32_16x16x32_bf16(Bt[n][k], At[m][k], acc[ai][bj][m][n], 0, 0, 0); __builtin_amdgcn_s_setprio(0); } while (0)
; #define PG8_BAR __builtin_amdgcn_s_barrier()
; template <class Epi, bool SP2, class Sched>
; __device__ __forceinline__ void gemm_phase(LAS unsigned char* lds, const Gemm g, const Sched& S, const Epi& E) {
;     ...
;         const bool has_next = S.next(ui + 1, nxt);
;         const char* nA = has_next ? (const char*)g.A + (size_t)nxt.pm * tstep + nxt.ko : cA; const char* nB = has_next ? (const char*)g.Bt + (size_t)nxt.pn * tstepB + nxt.ko : cB;
;         for (int t = 0; t < nt; t += 2) {
;             const bool last = (t == nt - 2);
;             const char* a1 = cA + (size_t)(t + 1) * kstep;
;             const char* a2 = last ? nA : cA + (size_t)(t + 2) * kstep; const char* b2 = last ? nB : cB + (size_t)(t + 2) * kstep;
;             const char* a3 = a2 + kstep; const char* b3 = b2 + kstep;
;             if constexpr (Epi::MID) { if (t == (nt >> 1)) E.mid(acc, cur, wr, fr); }
;             if constexpr (SP2) {
;             PG8_LDB(B0, 0, 0); PG8_LDB(B1, 0, 1); PG8_SCHED; PG8_LDA(At, 0, 0); PG8_STAGE(PG8_SA(1, 1), a1 + hstep, voffA);
;             PG8_WAIT_V(8); PG8_WAIT_L(0); PG8_BAR; PG8_MMA(0, 0, At, B0); PG8_MMA(0, 1, At, B1); PG8_BAR; PG8_SCHED;
;             PG8_LDA(At, 0, 1); PG8_STAGE(PG8_SB(0, 0), b2, voffB); PG8_STAGE(PG8_SB(0, 1), b2 + hstepB, voffB); PG8_STAGE(PG8_SA(0, 0), a2, voffA);
.LBB0_587:
	s_add_u32 s6, s94, 0xfffe0080
	s_addc_u32 s7, s95, -1
	s_add_i32 s20, 0, 0x10000
	s_cmp_eq_u32 s19, 4
	s_cselect_b32 s11, s5, s7
	s_cselect_b32 s10, s12, s6
	s_cselect_b32 s7, s13, s18
	s_cselect_b32 s6, s14, s15
	s_add_i32 s22, 0, 0x14000
	v_add_u32_e32 v156, s20, v145
	v_add_u32_e32 v172, s22, v145
	ds_read_b128 v[140:143], v156
	ds_read_b128 v[148:151], v156 offset:1024
	ds_read_b128 v[152:155], v156 offset:2048
	ds_read_b128 v[156:159], v156 offset:3072
	ds_read_b128 v[160:163], v172
	ds_read_b128 v[164:167], v172 offset:1024
	ds_read_b128 v[168:171], v172 offset:2048
	ds_read_b128 v[172:175], v172 offset:3072
	v_lshl_add_u64 v[192:193], s[94:95], 0, v[138:139]
	s_add_i32 m0, s17, 0xc000
	ds_read_b128 v[176:179], v147
	ds_read_b128 v[180:183], v147 offset:1024
	ds_read_b128 v[184:187], v147 offset:2048
	ds_read_b128 v[188:191], v147 offset:3072
	ds_read_b128 v[214:217], v147 offset:4096
	ds_read_b128 v[218:221], v147 offset:5120
	ds_read_b128 v[222:225], v147 offset:6144
	ds_read_b128 v[226:229], v147 offset:7168
	global_load_lds_dwordx4 v[192:193], off
	v_lshl_add_u64 v[192:193], s[94:95], 0, v[136:137]
	s_add_i32 m0, s17, 0xe000
	s_nop 0
	global_load_lds_dwordx4 v[192:193], off
	s_waitcnt vmcnt(8) lgkmcnt(0)
	s_barrier
	s_setprio 1
	v_mfma_f32_16x16x32_bf16 v[126:129], v[140:143], v[176:179], v[126:129]
	v_mfma_f32_16x16x32_bf16 v[122:125], v[152:155], v[176:179], v[122:125]
	v_mfma_f32_16x16x32_bf16 v[110:113], v[140:143], v[184:187], v[110:113]
	v_mfma_f32_16x16x32_bf16 v[106:109], v[152:155], v[184:187], v[106:109]
	v_mfma_f32_16x16x32_bf16 v[94:97], v[140:143], v[214:217], v[94:97]
	v_mfma_f32_16x16x32_bf16 v[90:93], v[152:155], v[214:217], v[90:93]
	v_mfma_f32_16x16x32_bf16 v[78:81], v[140:143], v[222:225], v[78:81]
	v_mfma_f32_16x16x32_bf16 v[74:77], v[152:155], v[222:225], v[74:77]
	v_mfma_f32_16x16x32_bf16 v[126:129], v[148:151], v[180:183], v[126:129]
	v_mfma_f32_16x16x32_bf16 v[122:125], v[156:159], v[180:183], v[122:125]
	v_mfma_f32_16x16x32_bf16 v[110:113], v[148:151], v[188:191], v[110:113]
	v_mfma_f32_16x16x32_bf16 v[106:109], v[156:159], v[188:191], v[106:109]
	v_mfma_f32_16x16x32_bf16 v[94:97], v[148:151], v[218:221], v[94:97]
	v_mfma_f32_16x16x32_bf16 v[90:93], v[156:159], v[218:221], v[90:93]
	v_mfma_f32_16x16x32_bf16 v[78:81], v[148:151], v[226:229], v[78:81]
	v_mfma_f32_16x16x32_bf16 v[74:77], v[156:159], v[226:229], v[74:77]
	s_setprio 0
	s_setprio 1
	v_mfma_f32_16x16x32_bf16 v[118:121], v[160:163], v[176:179], v[118:121]
	v_mfma_f32_16x16x32_bf16 v[114:117], v[168:171], v[176:179], v[114:117]
	v_mfma_f32_16x16x32_bf16 v[102:105], v[160:163], v[184:187], v[102:105]
	v_mfma_f32_16x16x32_bf16 v[98:101], v[168:171], v[184:187], v[98:101]
	v_mfma_f32_16x16x32_bf16 v[86:89], v[160:163], v[214:217], v[86:89]
	v_mfma_f32_16x16x32_bf16 v[82:85], v[168:171], v[214:217], v[82:85]
	v_mfma_f32_16x16x32_bf16 v[70:73], v[160:163], v[222:225], v[70:73]
	v_mfma_f32_16x16x32_bf16 v[66:69], v[168:171], v[222:225], v[66:69]
	v_mfma_f32_16x16x32_bf16 v[118:121], v[164:167], v[180:183], v[118:121]
	v_mfma_f32_16x16x32_bf16 v[114:117], v[172:175], v[180:183], v[114:117]
	v_mfma_f32_16x16x32_bf16 v[102:105], v[164:167], v[188:191], v[102:105]
	v_mfma_f32_16x16x32_bf16 v[98:101], v[172:175], v[188:191], v[98:101]
	v_mfma_f32_16x16x32_bf16 v[86:89], v[164:167], v[218:221], v[86:89]
	v_mfma_f32_16x16x32_bf16 v[82:85], v[172:175], v[218:221], v[82:85]
	v_mfma_f32_16x16x32_bf16 v[70:73], v[164:167], v[226:229], v[70:73]
	v_mfma_f32_16x16x32_bf16 v[66:69], v[172:175], v[226:229], v[66:69]
	s_setprio 0
	s_barrier
	s_add_i32 s20, s20, s65
	v_lshl_add_u64 v[192:193], s[6:7], 0, v[64:65]
	s_mov_b32 m0, s20
	ds_read_b128 v[176:179], v147 offset:16384
	ds_read_b128 v[180:183], v147 offset:17408
	ds_read_b128 v[184:187], v147 offset:18432
	ds_read_b128 v[188:191], v147 offset:19456
	ds_read_b128 v[214:217], v147 offset:20480
	ds_read_b128 v[218:221], v147 offset:21504
	ds_read_b128 v[222:225], v147 offset:22528
	ds_read_b128 v[226:229], v147 offset:23552
	global_load_lds_dwordx4 v[192:193], off
	s_add_i32 m0, s20, 0x2000
	s_add_u32 s20, s6, 0x20000
	v_lshl_add_u64 v[230:231], s[6:7], 0, v[134:135]
	s_addc_u32 s21, s7, 0
	s_add_i32 s22, s22, s65
	global_load_lds_dwordx4 v[230:231], off
	v_lshl_add_u64 v[232:233], s[20:21], 0, v[64:65]
	s_mov_b32 m0, s22
	v_lshl_add_u64 v[234:235], s[10:11], 0, v[132:133]
	global_load_lds_dwordx4 v[232:233], off
	v_lshl_add_u64 v[232:233], s[20:21], 0, v[134:135]
	s_add_i32 m0, s22, 0x2000
	s_nop 0
	global_load_lds_dwordx4 v[232:233], off
	v_lshl_add_u64 v[232:233], s[10:11], 0, v[130:131]
	s_mov_b32 m0, s17
	s_nop 0
	global_load_lds_dwordx4 v[232:233], off
	s_mov_b32 m0, s68
	s_nop 0
	global_load_lds_dwordx4 v[234:235], off
	s_waitcnt vmcnt(8) lgkmcnt(0)
	s_barrier
; #define PG8_STAGE(bufoff, gbase, voff) do { _Pragma("unroll") for (int _i = 0; _i < 2; ++_i) \
;         __builtin_amdgcn_global_load_lds((const unsigned*)((const char*)(gbase) + (voff)[_i]), (LAS unsigned*)(lds + (bufoff) + ldsw + _i * 8192), 16, 0, 0); } while (0)
; #define PG8_LDA(dst, b, h) do { _Pragma("unroll") for (int m = 0; m < 4; ++m) _Pragma("unroll") for (int k = 0; k < 2; ++k) dst[m][k] = *(const LAS bf16x8*)(lds + PG8_SA(b, h) + aoff + m * 2048 + k * 1024); } while (0)
; #define PG8_LDB(dst, b, h) do { _Pragma("unroll") for (int n = 0; n < 2; ++n) _Pragma("unroll") for (int k = 0; k < 2; ++k) dst[n][k] = *(const LAS bf16x8*)(lds + PG8_SB(b, h) + boff + n * 2048 + k * 1024); } while (0)
; #define PG8_MMA(ai, bj, At, Bt) do { __builtin_amdgcn_s_setprio(1); _Pragma("unroll") for (int m = 0; m < 4; ++m) _Pragma("unroll") for (int n = 0; n < 2; ++n) _Pragma("unroll") for (int k = 0; k < 2; ++k) \
;         acc[ai][bj][m][n] = __builtin_amdgcn_mfma_f32_16x16x32_bf16(Bt[n][k], At[m][k], acc[ai][bj][m][n], 0, 0, 0); __builtin_amdgcn_s_setprio(0); } while (0)
; #define PG8_WAIT_V(n) asm volatile("s_waitcnt vmcnt(" #n ")" ::: "memory")
; #define PG8_WAIT_L(n) asm volatile("s_waitcnt lgkmcnt(" #n ")" ::: "memory")
; #define PG8_BAR __builtin_amdgcn_s_barrier()
; #define PG8_SCHED __builtin_amdgcn_sched_barrier(0)
; template <class Epi, bool SP2, class Sched>
; __device__ __forceinline__ void gemm_phase(LAS unsigned char* lds, const Gemm g, const Sched& S, const Epi& E) {
;     ...
;             PG8_WAIT_V(8); PG8_WAIT_L(0); PG8_BAR; PG8_MMA(1, 0, At, B0); PG8_MMA(1, 1, At, B1); PG8_BAR; PG8_SCHED;
;             PG8_LDB(B0, 1, 0); PG8_LDB(B1, 1, 1); PG8_SCHED; PG8_LDA(At, 1, 0); PG8_STAGE(PG8_SA(0, 1), a2 + hstep, voffA);
;             PG8_WAIT_V(8); PG8_WAIT_L(0); PG8_BAR; PG8_MMA(0, 0, At, B0); PG8_MMA(0, 1, At, B1); PG8_BAR; PG8_SCHED;
	s_setprio 1
	v_mfma_f32_16x16x32_bf16 v[60:63], v[140:143], v[176:179], v[60:63]
	v_mfma_f32_16x16x32_bf16 v[56:59], v[152:155], v[176:179], v[56:59]
	v_mfma_f32_16x16x32_bf16 v[44:47], v[140:143], v[184:187], v[44:47]
	v_mfma_f32_16x16x32_bf16 v[40:43], v[152:155], v[184:187], v[40:43]
	v_mfma_f32_16x16x32_bf16 v[28:31], v[140:143], v[214:217], v[28:31]
	v_mfma_f32_16x16x32_bf16 v[24:27], v[152:155], v[214:217], v[24:27]
	v_mfma_f32_16x16x32_bf16 v[12:15], v[140:143], v[222:225], v[12:15]
	v_mfma_f32_16x16x32_bf16 v[8:11], v[152:155], v[222:225], v[8:11]
	v_mfma_f32_16x16x32_bf16 v[60:63], v[148:151], v[180:183], v[60:63]
	v_mfma_f32_16x16x32_bf16 v[56:59], v[156:159], v[180:183], v[56:59]
	v_mfma_f32_16x16x32_bf16 v[44:47], v[148:151], v[188:191], v[44:47]
	v_mfma_f32_16x16x32_bf16 v[40:43], v[156:159], v[188:191], v[40:43]
	v_mfma_f32_16x16x32_bf16 v[28:31], v[148:151], v[218:221], v[28:31]
	v_mfma_f32_16x16x32_bf16 v[24:27], v[156:159], v[218:221], v[24:27]
	v_mfma_f32_16x16x32_bf16 v[12:15], v[148:151], v[226:229], v[12:15]
	v_mfma_f32_16x16x32_bf16 v[8:11], v[156:159], v[226:229], v[8:11]
	s_setprio 0
	s_setprio 1
	v_mfma_f32_16x16x32_bf16 v[52:55], v[160:163], v[176:179], v[52:55]
	v_mfma_f32_16x16x32_bf16 v[48:51], v[168:171], v[176:179], v[48:51]
	v_mfma_f32_16x16x32_bf16 v[36:39], v[160:163], v[184:187], v[36:39]
	v_mfma_f32_16x16x32_bf16 v[32:35], v[168:171], v[184:187], v[32:35]
	v_mfma_f32_16x16x32_bf16 v[20:23], v[160:163], v[214:217], v[20:23]
	v_mfma_f32_16x16x32_bf16 v[16:19], v[168:171], v[214:217], v[16:19]
	v_mfma_f32_16x16x32_bf16 v[4:7], v[160:163], v[222:225], v[4:7]
	v_mfma_f32_16x16x32_bf16 v[0:3], v[168:171], v[222:225], v[0:3]
	v_mfma_f32_16x16x32_bf16 v[52:55], v[164:167], v[180:183], v[52:55]
	v_mfma_f32_16x16x32_bf16 v[48:51], v[172:175], v[180:183], v[48:51]
	v_mfma_f32_16x16x32_bf16 v[36:39], v[164:167], v[188:191], v[36:39]
	v_mfma_f32_16x16x32_bf16 v[32:35], v[172:175], v[188:191], v[32:35]
	v_mfma_f32_16x16x32_bf16 v[20:23], v[164:167], v[218:221], v[20:23]
	v_mfma_f32_16x16x32_bf16 v[16:19], v[172:175], v[218:221], v[16:19]
	v_mfma_f32_16x16x32_bf16 v[4:7], v[164:167], v[226:229], v[4:7]
	v_mfma_f32_16x16x32_bf16 v[0:3], v[172:175], v[226:229], v[0:3]
	s_setprio 0
	s_barrier
	s_add_i32 s20, 0, 0x18000
	s_add_i32 s21, 0, 0x1c000
	v_add_u32_e32 v156, s20, v145
	v_add_u32_e32 v172, s21, v145
	ds_read_b128 v[140:143], v156
	ds_read_b128 v[148:151], v156 offset:1024
	ds_read_b128 v[152:155], v156 offset:2048
	ds_read_b128 v[156:159], v156 offset:3072
	ds_read_b128 v[160:163], v172
	ds_read_b128 v[164:167], v172 offset:1024
	ds_read_b128 v[168:171], v172 offset:2048
	ds_read_b128 v[172:175], v172 offset:3072
	s_add_u32 s10, s10, 0x20000
	s_addc_u32 s11, s11, 0
	s_mov_b32 m0, s69
	v_lshl_add_u64 v[236:237], s[10:11], 0, v[130:131]
	ds_read_b128 v[176:179], v147 offset:32768
	ds_read_b128 v[180:183], v147 offset:33792
	ds_read_b128 v[184:187], v147 offset:34816
	ds_read_b128 v[188:191], v147 offset:35840
	ds_read_b128 v[214:217], v147 offset:36864
	ds_read_b128 v[218:221], v147 offset:37888
	ds_read_b128 v[222:225], v147 offset:38912
	ds_read_b128 v[226:229], v147 offset:39936
	global_load_lds_dwordx4 v[236:237], off
	v_lshl_add_u64 v[236:237], s[10:11], 0, v[132:133]
	s_mov_b32 m0, s72
	s_nop 0
	global_load_lds_dwordx4 v[236:237], off
	s_waitcnt vmcnt(8) lgkmcnt(0)
	s_barrier
	s_setprio 1
	v_mfma_f32_16x16x32_bf16 v[126:129], v[140:143], v[176:179], v[126:129]
	v_mfma_f32_16x16x32_bf16 v[122:125], v[152:155], v[176:179], v[122:125]
	v_mfma_f32_16x16x32_bf16 v[110:113], v[140:143], v[184:187], v[110:113]
	v_mfma_f32_16x16x32_bf16 v[106:109], v[152:155], v[184:187], v[106:109]
	v_mfma_f32_16x16x32_bf16 v[94:97], v[140:143], v[214:217], v[94:97]
	v_mfma_f32_16x16x32_bf16 v[90:93], v[152:155], v[214:217], v[90:93]
	v_mfma_f32_16x16x32_bf16 v[78:81], v[140:143], v[222:225], v[78:81]
	v_mfma_f32_16x16x32_bf16 v[74:77], v[152:155], v[222:225], v[74:77]
	v_mfma_f32_16x16x32_bf16 v[126:129], v[148:151], v[180:183], v[126:129]
	v_mfma_f32_16x16x32_bf16 v[122:125], v[156:159], v[180:183], v[122:125]
	v_mfma_f32_16x16x32_bf16 v[110:113], v[148:151], v[188:191], v[110:113]
	v_mfma_f32_16x16x32_bf16 v[106:109], v[156:159], v[188:191], v[106:109]
	v_mfma_f32_16x16x32_bf16 v[94:97], v[148:151], v[218:221], v[94:97]
	v_mfma_f32_16x16x32_bf16 v[90:93], v[156:159], v[218:221], v[90:93]
	v_mfma_f32_16x16x32_bf16 v[78:81], v[148:151], v[226:229], v[78:81]
	v_mfma_f32_16x16x32_bf16 v[74:77], v[156:159], v[226:229], v[74:77]
	s_setprio 0
	s_setprio 1
	v_mfma_f32_16x16x32_bf16 v[118:121], v[160:163], v[176:179], v[118:121]
	v_mfma_f32_16x16x32_bf16 v[114:117], v[168:171], v[176:179], v[114:117]
	v_mfma_f32_16x16x32_bf16 v[102:105], v[160:163], v[184:187], v[102:105]
	v_mfma_f32_16x16x32_bf16 v[98:101], v[168:171], v[184:187], v[98:101]
	v_mfma_f32_16x16x32_bf16 v[86:89], v[160:163], v[214:217], v[86:89]
	v_mfma_f32_16x16x32_bf16 v[82:85], v[168:171], v[214:217], v[82:85]
	v_mfma_f32_16x16x32_bf16 v[70:73], v[160:163], v[222:225], v[70:73]
	v_mfma_f32_16x16x32_bf16 v[66:69], v[168:171], v[222:225], v[66:69]
	v_mfma_f32_16x16x32_bf16 v[118:121], v[164:167], v[180:183], v[118:121]
	v_mfma_f32_16x16x32_bf16 v[114:117], v[172:175], v[180:183], v[114:117]
	v_mfma_f32_16x16x32_bf16 v[102:105], v[164:167], v[188:191], v[102:105]
	v_mfma_f32_16x16x32_bf16 v[98:101], v[172:175], v[188:191], v[98:101]
	v_mfma_f32_16x16x32_bf16 v[86:89], v[164:167], v[218:221], v[86:89]
	v_mfma_f32_16x16x32_bf16 v[82:85], v[172:175], v[218:221], v[82:85]
	v_mfma_f32_16x16x32_bf16 v[70:73], v[164:167], v[226:229], v[70:73]
	v_mfma_f32_16x16x32_bf16 v[66:69], v[172:175], v[226:229], v[66:69]
	s_setprio 0
	s_barrier
; #define PG8_STAGE(bufoff, gbase, voff) do { _Pragma("unroll") for (int _i = 0; _i < 2; ++_i) \
;         __builtin_amdgcn_global_load_lds((const unsigned*)((const char*)(gbase) + (voff)[_i]), (LAS unsigned*)(lds + (bufoff) + ldsw + _i * 8192), 16, 0, 0); } while (0)
; #define PG8_LDA(dst, b, h) do { _Pragma("unroll") for (int m = 0; m < 4; ++m) _Pragma("unroll") for (int k = 0; k < 2; ++k) dst[m][k] = *(const LAS bf16x8*)(lds + PG8_SA(b, h) + aoff + m * 2048 + k * 1024); } while (0)
; #define PG8_MMA(ai, bj, At, Bt) do { __builtin_amdgcn_s_setprio(1); _Pragma("unroll") for (int m = 0; m < 4; ++m) _Pragma("unroll") for (int n = 0; n < 2; ++n) _Pragma("unroll") for (int k = 0; k < 2; ++k) \
;         acc[ai][bj][m][n] = __builtin_amdgcn_mfma_f32_16x16x32_bf16(Bt[n][k], At[m][k], acc[ai][bj][m][n], 0, 0, 0); __builtin_amdgcn_s_setprio(0); } while (0)
; #define PG8_WAIT_V(n) asm volatile("s_waitcnt vmcnt(" #n ")" ::: "memory")
; #define PG8_WAIT_L(n) asm volatile("s_waitcnt lgkmcnt(" #n ")" ::: "memory")
; #define PG8_BAR __builtin_amdgcn_s_barrier()
; #define PG8_SCHED __builtin_amdgcn_sched_barrier(0)
; template <class Epi, bool SP2, class Sched>
; __device__ __forceinline__ void gemm_phase(LAS unsigned char* lds, const Gemm g, const Sched& S, const Epi& E) {
;     ...
;         for (int t = 0; t < nt; t += 2) {
;     ...
;             PG8_LDA(At, 1, 1); PG8_STAGE(PG8_SB(1, 0), b3, voffB); PG8_STAGE(PG8_SB(1, 1), b3 + hstepB, voffB); PG8_STAGE(PG8_SA(1, 0), a3, voffA);
;             PG8_WAIT_V(8); PG8_WAIT_L(0); PG8_BAR; PG8_MMA(1, 0, At, B0); PG8_MMA(1, 1, At, B1); PG8_BAR; PG8_SCHED;
;     ...
;         if (wr == 0) PG8_BAR;
	s_add_i32 s10, s20, s65
	v_lshl_add_u64 v[192:193], v[192:193], 0, s[66:67]
	s_mov_b32 m0, s10
	ds_read_b128 v[176:179], v147 offset:49152
	ds_read_b128 v[180:183], v147 offset:50176
	ds_read_b128 v[184:187], v147 offset:51200
	ds_read_b128 v[188:191], v147 offset:52224
	ds_read_b128 v[214:217], v147 offset:53248
	ds_read_b128 v[218:221], v147 offset:54272
	ds_read_b128 v[222:225], v147 offset:55296
	ds_read_b128 v[226:229], v147 offset:56320
	global_load_lds_dwordx4 v[192:193], off
	s_add_i32 m0, s10, 0x2000
	s_add_u32 s6, s6, 0x20080
	v_lshl_add_u64 v[192:193], v[230:231], 0, s[66:67]
	s_addc_u32 s7, s7, 0
	s_add_i32 s10, s21, s65
	global_load_lds_dwordx4 v[192:193], off
	v_lshl_add_u64 v[192:193], s[6:7], 0, v[64:65]
	s_mov_b32 m0, s10
	s_nop 0
	global_load_lds_dwordx4 v[192:193], off
	v_lshl_add_u64 v[192:193], s[6:7], 0, v[134:135]
	s_add_i32 m0, s10, 0x2000
	s_nop 0
	global_load_lds_dwordx4 v[192:193], off
	v_lshl_add_u64 v[192:193], v[232:233], 0, s[66:67]
	s_mov_b32 m0, s73
	s_nop 0
	global_load_lds_dwordx4 v[192:193], off
	v_lshl_add_u64 v[192:193], v[234:235], 0, s[66:67]
	s_mov_b32 m0, s74
	s_nop 0
	global_load_lds_dwordx4 v[192:193], off
	s_waitcnt vmcnt(8) lgkmcnt(0)
	s_barrier
	s_setprio 1
	v_mfma_f32_16x16x32_bf16 v[60:63], v[140:143], v[176:179], v[60:63]
	v_mfma_f32_16x16x32_bf16 v[56:59], v[152:155], v[176:179], v[56:59]
	v_mfma_f32_16x16x32_bf16 v[44:47], v[140:143], v[184:187], v[44:47]
	v_mfma_f32_16x16x32_bf16 v[40:43], v[152:155], v[184:187], v[40:43]
	v_mfma_f32_16x16x32_bf16 v[28:31], v[140:143], v[214:217], v[28:31]
	v_mfma_f32_16x16x32_bf16 v[24:27], v[152:155], v[214:217], v[24:27]
	v_mfma_f32_16x16x32_bf16 v[12:15], v[140:143], v[222:225], v[12:15]
	v_mfma_f32_16x16x32_bf16 v[8:11], v[152:155], v[222:225], v[8:11]
	v_mfma_f32_16x16x32_bf16 v[60:63], v[148:151], v[180:183], v[60:63]
	v_mfma_f32_16x16x32_bf16 v[56:59], v[156:159], v[180:183], v[56:59]
	v_mfma_f32_16x16x32_bf16 v[44:47], v[148:151], v[188:191], v[44:47]
	v_mfma_f32_16x16x32_bf16 v[40:43], v[156:159], v[188:191], v[40:43]
	v_mfma_f32_16x16x32_bf16 v[28:31], v[148:151], v[218:221], v[28:31]
	v_mfma_f32_16x16x32_bf16 v[24:27], v[156:159], v[218:221], v[24:27]
	v_mfma_f32_16x16x32_bf16 v[12:15], v[148:151], v[226:229], v[12:15]
	v_mfma_f32_16x16x32_bf16 v[8:11], v[156:159], v[226:229], v[8:11]
	s_setprio 0
	s_setprio 1
	v_mfma_f32_16x16x32_bf16 v[52:55], v[160:163], v[176:179], v[52:55]
	v_mfma_f32_16x16x32_bf16 v[48:51], v[168:171], v[176:179], v[48:51]
	v_mfma_f32_16x16x32_bf16 v[36:39], v[160:163], v[184:187], v[36:39]
	v_mfma_f32_16x16x32_bf16 v[32:35], v[168:171], v[184:187], v[32:35]
	v_mfma_f32_16x16x32_bf16 v[20:23], v[160:163], v[214:217], v[20:23]
	v_mfma_f32_16x16x32_bf16 v[16:19], v[168:171], v[214:217], v[16:19]
	v_mfma_f32_16x16x32_bf16 v[4:7], v[160:163], v[222:225], v[4:7]
	v_mfma_f32_16x16x32_bf16 v[0:3], v[168:171], v[222:225], v[0:3]
	v_mfma_f32_16x16x32_bf16 v[52:55], v[164:167], v[180:183], v[52:55]
	v_mfma_f32_16x16x32_bf16 v[48:51], v[172:175], v[180:183], v[48:51]
	v_mfma_f32_16x16x32_bf16 v[36:39], v[164:167], v[188:191], v[36:39]
	v_mfma_f32_16x16x32_bf16 v[32:35], v[172:175], v[188:191], v[32:35]
	v_mfma_f32_16x16x32_bf16 v[20:23], v[164:167], v[218:221], v[20:23]
	v_mfma_f32_16x16x32_bf16 v[16:19], v[172:175], v[218:221], v[16:19]
	v_mfma_f32_16x16x32_bf16 v[4:7], v[164:167], v[226:229], v[4:7]
	v_mfma_f32_16x16x32_bf16 v[0:3], v[172:175], v[226:229], v[0:3]
	s_setprio 0
	s_barrier
	s_add_i32 s19, s19, 2
	s_add_u32 s15, s15, 0x100
	s_addc_u32 s18, s18, 0
	s_add_u32 s94, s94, 0x100
	s_addc_u32 s95, s95, 0
	s_cmp_gt_u32 s19, 5
	s_cbranch_scc0 .LBB0_587
	s_and_b64 vcc, exec, s[84:85]
	s_cbranch_vccz .LBB0_590
	s_barrier

; #define PG8_STAGE(bufoff, gbase, voff) do { _Pragma("unroll") for (int _i = 0; _i < 2; ++_i) \
;         __builtin_amdgcn_global_load_lds((const unsigned*)((const char*)(gbase) + (voff)[_i]), (LAS unsigned*)(lds + (bufoff) + ldsw + _i * 8192), 16, 0, 0); } while (0)
; #define PG8_LDA(dst, b, h) do { _Pragma("unroll") for (int m = 0; m < 4; ++m) _Pragma("unroll") for (int k = 0; k < 2; ++k) dst[m][k] = *(const LAS bf16x8*)(lds + PG8_SA(b, h) + aoff + m * 2048 + k * 1024); } while (0)
; #define PG8_LDB(dst, b, h) do { _Pragma("unroll") for (int n = 0; n < 2; ++n) _Pragma("unroll") for (int k = 0; k < 2; ++k) dst[n][k] = *(const LAS bf16x8*)(lds + PG8_SB(b, h) + boff + n * 2048 + k * 1024); } while (0)
; #define PG8_MMA(ai, bj, At, Bt) do { __builtin_amdgcn_s_setprio(1); _Pragma("unroll") for (int m = 0; m < 4; ++m) _Pragma("unroll") for (int n = 0; n < 2; ++n) _Pragma("unroll") for (int k = 0; k < 2; ++k) \
;         acc[ai][bj][m][n] = __builtin_amdgcn_mfma_f32_16x16x32_bf16(Bt[n][k], At[m][k], acc[ai][bj][m][n], 0, 0, 0); __builtin_amdgcn_s_setprio(0); } while (0)
; #define PG8_BAR __builtin_amdgcn_s_barrier()
; template <class Epi, bool SP2, class Sched>
; __device__ __forceinline__ void gemm_phase(LAS unsigned char* lds, const Gemm g, const Sched& S, const Epi& E) {
;     ...
;         const bool has_next = S.next(ui + 1, nxt);
;         const char* nA = has_next ? (const char*)g.A + (size_t)nxt.pm * tstep + nxt.ko : cA; const char* nB = has_next ? (const char*)g.Bt + (size_t)nxt.pn * tstepB + nxt.ko : cB;
;         for (int t = 0; t < nt; t += 2) {
;             const bool last = (t == nt - 2);
;             const char* a1 = cA + (size_t)(t + 1) * kstep;
;             const char* a2 = last ? nA : cA + (size_t)(t + 2) * kstep; const char* b2 = last ? nB : cB + (size_t)(t + 2) * kstep;
;             const char* a3 = a2 + kstep; const char* b3 = b2 + kstep;
;             if constexpr (Epi::MID) { if (t == (nt >> 1)) E.mid(acc, cur, wr, fr); }
;             if constexpr (SP2) {
;             PG8_LDB(B0, 0, 0); PG8_LDB(B1, 0, 1); PG8_SCHED; PG8_LDA(At, 0, 0); PG8_STAGE(PG8_SA(1, 1), a1 + hstep, voffA);
;             PG8_WAIT_V(8); PG8_WAIT_L(0); PG8_BAR; PG8_MMA(0, 0, At, B0); PG8_MMA(0, 1, At, B1); PG8_BAR; PG8_SCHED;
;             PG8_LDA(At, 0, 1); PG8_STAGE(PG8_SB(0, 0), b2, voffB); PG8_STAGE(PG8_SB(0, 1), b2 + hstepB, voffB); PG8_STAGE(PG8_SA(0, 0), a2, voffA);
.LBB0_673:
	s_add_u32 s6, s94, s96
	s_addc_u32 s7, s95, s97
	s_add_u32 s6, s6, 0x100
	s_addc_u32 s7, s7, 0
	s_add_u32 s19, s15, s96
	s_addc_u32 s20, s16, s97
	s_cmpk_eq_i32 s96, 0x700
	s_cselect_b32 s11, s5, s7
	s_cselect_b32 s10, s12, s6
	s_cselect_b32 s7, s13, s20
	s_cselect_b32 s6, s14, s19
	s_add_i32 s19, 0, 0x10000
	v_add_u32_e32 v64, s19, v153
	s_add_i32 s22, 0, 0x14000
	ds_read_b128 v[156:159], v64
	ds_read_b128 v[160:163], v64 offset:1024
	ds_read_b128 v[164:167], v64 offset:2048
	ds_read_b128 v[168:171], v64 offset:3072
	v_add_u32_e32 v64, s22, v153
	ds_read_b128 v[172:175], v64
	ds_read_b128 v[176:179], v64 offset:1024
	ds_read_b128 v[180:183], v64 offset:2048
	ds_read_b128 v[184:187], v64 offset:3072
	v_lshl_add_u64 v[66:67], v[150:151], 0, s[96:97]
	s_add_i32 m0, s17, 0xc000
	ds_read_b128 v[188:191], v155
	ds_read_b128 v[214:217], v155 offset:1024
	ds_read_b128 v[218:221], v155 offset:2048
	ds_read_b128 v[222:225], v155 offset:3072
	ds_read_b128 v[226:229], v155 offset:4096
	ds_read_b128 v[230:233], v155 offset:5120
	ds_read_b128 v[234:237], v155 offset:6144
	ds_read_b128 v[238:241], v155 offset:7168
	global_load_lds_dwordx4 v[66:67], off
	v_lshl_add_u64 v[66:67], v[148:149], 0, s[96:97]
	s_add_i32 m0, s17, 0xe000
	s_nop 0
	global_load_lds_dwordx4 v[66:67], off
	s_waitcnt vmcnt(8) lgkmcnt(0)
	s_barrier
	s_setprio 1
	v_mfma_f32_16x16x32_bf16 v[128:131], v[156:159], v[188:191], v[128:131]
	v_mfma_f32_16x16x32_bf16 v[124:127], v[164:167], v[188:191], v[124:127]
	v_mfma_f32_16x16x32_bf16 v[112:115], v[156:159], v[218:221], v[112:115]
	v_mfma_f32_16x16x32_bf16 v[108:111], v[164:167], v[218:221], v[108:111]
	v_mfma_f32_16x16x32_bf16 v[96:99], v[156:159], v[226:229], v[96:99]
	v_mfma_f32_16x16x32_bf16 v[92:95], v[164:167], v[226:229], v[92:95]
	v_mfma_f32_16x16x32_bf16 v[80:83], v[156:159], v[234:237], v[80:83]
	v_mfma_f32_16x16x32_bf16 v[76:79], v[164:167], v[234:237], v[76:79]
	v_mfma_f32_16x16x32_bf16 v[128:131], v[160:163], v[214:217], v[128:131]
	v_mfma_f32_16x16x32_bf16 v[124:127], v[168:171], v[214:217], v[124:127]
	v_mfma_f32_16x16x32_bf16 v[112:115], v[160:163], v[222:225], v[112:115]
	v_mfma_f32_16x16x32_bf16 v[108:111], v[168:171], v[222:225], v[108:111]
	v_mfma_f32_16x16x32_bf16 v[96:99], v[160:163], v[230:233], v[96:99]
	v_mfma_f32_16x16x32_bf16 v[92:95], v[168:171], v[230:233], v[92:95]
	v_mfma_f32_16x16x32_bf16 v[80:83], v[160:163], v[238:241], v[80:83]
	v_mfma_f32_16x16x32_bf16 v[76:79], v[168:171], v[238:241], v[76:79]
	s_setprio 0
	s_setprio 1
	v_mfma_f32_16x16x32_bf16 v[120:123], v[172:175], v[188:191], v[120:123]
	v_mfma_f32_16x16x32_bf16 v[116:119], v[180:183], v[188:191], v[116:119]
	v_mfma_f32_16x16x32_bf16 v[104:107], v[172:175], v[218:221], v[104:107]
	v_mfma_f32_16x16x32_bf16 v[100:103], v[180:183], v[218:221], v[100:103]
	v_mfma_f32_16x16x32_bf16 v[88:91], v[172:175], v[226:229], v[88:91]
	v_mfma_f32_16x16x32_bf16 v[84:87], v[180:183], v[226:229], v[84:87]
	v_mfma_f32_16x16x32_bf16 v[72:75], v[172:175], v[234:237], v[72:75]
	v_mfma_f32_16x16x32_bf16 v[66:69], v[180:183], v[234:237], v[68:71]
	v_mfma_f32_16x16x32_bf16 v[120:123], v[176:179], v[214:217], v[120:123]
	v_mfma_f32_16x16x32_bf16 v[116:119], v[184:187], v[214:217], v[116:119]
	v_mfma_f32_16x16x32_bf16 v[104:107], v[176:179], v[222:225], v[104:107]
	v_mfma_f32_16x16x32_bf16 v[100:103], v[184:187], v[222:225], v[100:103]
	v_mfma_f32_16x16x32_bf16 v[88:91], v[176:179], v[230:233], v[88:91]
	v_mfma_f32_16x16x32_bf16 v[84:87], v[184:187], v[230:233], v[84:87]
	v_mfma_f32_16x16x32_bf16 v[72:75], v[176:179], v[238:241], v[72:75]
	v_mfma_f32_16x16x32_bf16 v[66:69], v[184:187], v[238:241], v[66:69]
	s_setprio 0
	s_barrier
	s_add_i32 s19, s19, s73
	v_lshl_add_u64 v[192:193], s[6:7], 0, v[134:135]
	s_mov_b32 m0, s19
	ds_read_b128 v[188:191], v155 offset:16384
	ds_read_b128 v[214:217], v155 offset:17408
	ds_read_b128 v[218:221], v155 offset:18432
	ds_read_b128 v[222:225], v155 offset:19456
	ds_read_b128 v[226:229], v155 offset:20480
	ds_read_b128 v[230:233], v155 offset:21504
	ds_read_b128 v[234:237], v155 offset:22528
	ds_read_b128 v[238:241], v155 offset:23552
	global_load_lds_dwordx4 v[192:193], off
	s_add_i32 m0, s19, 0x2000
	s_add_u32 s20, s6, 0x40000
	v_lshl_add_u64 v[248:249], s[6:7], 0, v[138:139]
	s_addc_u32 s21, s7, 0
	s_add_i32 s19, s22, s73
	global_load_lds_dwordx4 v[248:249], off
	v_lshl_add_u64 v[70:71], s[20:21], 0, v[134:135]
	s_mov_b32 m0, s19
	v_lshl_add_u64 v[250:251], s[10:11], 0, v[132:133]
	global_load_lds_dwordx4 v[70:71], off
	v_lshl_add_u64 v[70:71], s[20:21], 0, v[138:139]
	s_add_i32 m0, s19, 0x2000
	v_lshl_add_u64 v[252:253], s[10:11], 0, v[136:137]
	global_load_lds_dwordx4 v[70:71], off
	s_mov_b32 m0, s17
	s_nop 0
	global_load_lds_dwordx4 v[250:251], off
	s_mov_b32 m0, s79
	s_nop 0
	global_load_lds_dwordx4 v[252:253], off
	s_waitcnt vmcnt(8) lgkmcnt(0)
	s_barrier
; #define PG8_STAGE(bufoff, gbase, voff) do { _Pragma("unroll") for (int _i = 0; _i < 2; ++_i) \
;         __builtin_amdgcn_global_load_lds((const unsigned*)((const char*)(gbase) + (voff)[_i]), (LAS unsigned*)(lds + (bufoff) + ldsw + _i * 8192), 16, 0, 0); } while (0)
; #define PG8_LDA(dst, b, h) do { _Pragma("unroll") for (int m = 0; m < 4; ++m) _Pragma("unroll") for (int k = 0; k < 2; ++k) dst[m][k] = *(const LAS bf16x8*)(lds + PG8_SA(b, h) + aoff + m * 2048 + k * 1024); } while (0)
; #define PG8_LDB(dst, b, h) do { _Pragma("unroll") for (int n = 0; n < 2; ++n) _Pragma("unroll") for (int k = 0; k < 2; ++k) dst[n][k] = *(const LAS bf16x8*)(lds + PG8_SB(b, h) + boff + n * 2048 + k * 1024); } while (0)
; #define PG8_MMA(ai, bj, At, Bt) do { __builtin_amdgcn_s_setprio(1); _Pragma("unroll") for (int m = 0; m < 4; ++m) _Pragma("unroll") for (int n = 0; n < 2; ++n) _Pragma("unroll") for (int k = 0; k < 2; ++k) \
;         acc[ai][bj][m][n] = __builtin_amdgcn_mfma_f32_16x16x32_bf16(Bt[n][k], At[m][k], acc[ai][bj][m][n], 0, 0, 0); __builtin_amdgcn_s_setprio(0); } while (0)
; #define PG8_WAIT_V(n) asm volatile("s_waitcnt vmcnt(" #n ")" ::: "memory")
; #define PG8_WAIT_L(n) asm volatile("s_waitcnt lgkmcnt(" #n ")" ::: "memory")
; #define PG8_BAR __builtin_amdgcn_s_barrier()
; #define PG8_SCHED __builtin_amdgcn_sched_barrier(0)
; template <class Epi, bool SP2, class Sched>
; __device__ __forceinline__ void gemm_phase(LAS unsigned char* lds, const Gemm g, const Sched& S, const Epi& E) {
;     ...
;             PG8_WAIT_V(8); PG8_WAIT_L(0); PG8_BAR; PG8_MMA(1, 0, At, B0); PG8_MMA(1, 1, At, B1); PG8_BAR; PG8_SCHED;
;             PG8_LDB(B0, 1, 0); PG8_LDB(B1, 1, 1); PG8_SCHED; PG8_LDA(At, 1, 0); PG8_STAGE(PG8_SA(0, 1), a2 + hstep, voffA);
;             PG8_WAIT_V(8); PG8_WAIT_L(0); PG8_BAR; PG8_MMA(0, 0, At, B0); PG8_MMA(0, 1, At, B1); PG8_BAR; PG8_SCHED;
	s_setprio 1
	v_mfma_f32_16x16x32_bf16 v[60:63], v[156:159], v[188:191], v[60:63]
	v_mfma_f32_16x16x32_bf16 v[56:59], v[164:167], v[188:191], v[56:59]
	v_mfma_f32_16x16x32_bf16 v[44:47], v[156:159], v[218:221], v[44:47]
	v_mfma_f32_16x16x32_bf16 v[40:43], v[164:167], v[218:221], v[40:43]
	v_mfma_f32_16x16x32_bf16 v[28:31], v[156:159], v[226:229], v[28:31]
	v_mfma_f32_16x16x32_bf16 v[24:27], v[164:167], v[226:229], v[24:27]
	v_mfma_f32_16x16x32_bf16 v[12:15], v[156:159], v[234:237], v[12:15]
	v_mfma_f32_16x16x32_bf16 v[8:11], v[164:167], v[234:237], v[8:11]
	v_mfma_f32_16x16x32_bf16 v[60:63], v[160:163], v[214:217], v[60:63]
	v_mfma_f32_16x16x32_bf16 v[56:59], v[168:171], v[214:217], v[56:59]
	v_mfma_f32_16x16x32_bf16 v[44:47], v[160:163], v[222:225], v[44:47]
	v_mfma_f32_16x16x32_bf16 v[40:43], v[168:171], v[222:225], v[40:43]
	v_mfma_f32_16x16x32_bf16 v[28:31], v[160:163], v[230:233], v[28:31]
	v_mfma_f32_16x16x32_bf16 v[24:27], v[168:171], v[230:233], v[24:27]
	v_mfma_f32_16x16x32_bf16 v[12:15], v[160:163], v[238:241], v[12:15]
	v_mfma_f32_16x16x32_bf16 v[8:11], v[168:171], v[238:241], v[8:11]
	s_setprio 0
	s_setprio 1
	v_mfma_f32_16x16x32_bf16 v[52:55], v[172:175], v[188:191], v[52:55]
	v_mfma_f32_16x16x32_bf16 v[48:51], v[180:183], v[188:191], v[48:51]
	v_mfma_f32_16x16x32_bf16 v[36:39], v[172:175], v[218:221], v[36:39]
	v_mfma_f32_16x16x32_bf16 v[32:35], v[180:183], v[218:221], v[32:35]
	v_mfma_f32_16x16x32_bf16 v[20:23], v[172:175], v[226:229], v[20:23]
	v_mfma_f32_16x16x32_bf16 v[16:19], v[180:183], v[226:229], v[16:19]
	v_mfma_f32_16x16x32_bf16 v[4:7], v[172:175], v[234:237], v[4:7]
	v_mfma_f32_16x16x32_bf16 v[0:3], v[180:183], v[234:237], v[0:3]
	v_mfma_f32_16x16x32_bf16 v[52:55], v[176:179], v[214:217], v[52:55]
	v_mfma_f32_16x16x32_bf16 v[48:51], v[184:187], v[214:217], v[48:51]
	v_mfma_f32_16x16x32_bf16 v[36:39], v[176:179], v[222:225], v[36:39]
	v_mfma_f32_16x16x32_bf16 v[32:35], v[184:187], v[222:225], v[32:35]
	v_mfma_f32_16x16x32_bf16 v[20:23], v[176:179], v[230:233], v[20:23]
	v_mfma_f32_16x16x32_bf16 v[16:19], v[184:187], v[230:233], v[16:19]
	v_mfma_f32_16x16x32_bf16 v[4:7], v[176:179], v[238:241], v[4:7]
	v_mfma_f32_16x16x32_bf16 v[0:3], v[184:187], v[238:241], v[0:3]
	s_setprio 0
	s_barrier
	s_add_i32 s19, 0, 0x18000
	v_add_u32_e32 v64, s19, v153
	s_add_i32 s20, 0, 0x1c000
	ds_read_b128 v[156:159], v64
	ds_read_b128 v[160:163], v64 offset:1024
	ds_read_b128 v[164:167], v64 offset:2048
	ds_read_b128 v[168:171], v64 offset:3072
	v_add_u32_e32 v64, s20, v153
	ds_read_b128 v[172:175], v64
	ds_read_b128 v[176:179], v64 offset:1024
	ds_read_b128 v[180:183], v64 offset:2048
	ds_read_b128 v[184:187], v64 offset:3072
	s_add_u32 s10, s10, 0x40000
	s_addc_u32 s11, s11, 0
	s_mov_b32 m0, s83
	v_lshl_add_u64 v[70:71], s[10:11], 0, v[132:133]
	ds_read_b128 v[188:191], v155 offset:32768
	ds_read_b128 v[214:217], v155 offset:33792
	ds_read_b128 v[218:221], v155 offset:34816
	ds_read_b128 v[222:225], v155 offset:35840
	ds_read_b128 v[226:229], v155 offset:36864
	ds_read_b128 v[230:233], v155 offset:37888
	ds_read_b128 v[234:237], v155 offset:38912
	ds_read_b128 v[238:241], v155 offset:39936
	global_load_lds_dwordx4 v[70:71], off
	v_lshl_add_u64 v[70:71], s[10:11], 0, v[136:137]
	s_mov_b32 m0, s74
	s_nop 0
	global_load_lds_dwordx4 v[70:71], off
	s_waitcnt vmcnt(8) lgkmcnt(0)
	s_barrier
	s_setprio 1
	v_mfma_f32_16x16x32_bf16 v[128:131], v[156:159], v[188:191], v[128:131]
	v_mfma_f32_16x16x32_bf16 v[124:127], v[164:167], v[188:191], v[124:127]
	v_mfma_f32_16x16x32_bf16 v[112:115], v[156:159], v[218:221], v[112:115]
	v_mfma_f32_16x16x32_bf16 v[108:111], v[164:167], v[218:221], v[108:111]
	v_mfma_f32_16x16x32_bf16 v[96:99], v[156:159], v[226:229], v[96:99]
	v_mfma_f32_16x16x32_bf16 v[92:95], v[164:167], v[226:229], v[92:95]
	v_mfma_f32_16x16x32_bf16 v[80:83], v[156:159], v[234:237], v[80:83]
	v_mfma_f32_16x16x32_bf16 v[76:79], v[164:167], v[234:237], v[76:79]
	v_mfma_f32_16x16x32_bf16 v[128:131], v[160:163], v[214:217], v[128:131]
	v_mfma_f32_16x16x32_bf16 v[124:127], v[168:171], v[214:217], v[124:127]
	v_mfma_f32_16x16x32_bf16 v[112:115], v[160:163], v[222:225], v[112:115]
	v_mfma_f32_16x16x32_bf16 v[108:111], v[168:171], v[222:225], v[108:111]
	v_mfma_f32_16x16x32_bf16 v[96:99], v[160:163], v[230:233], v[96:99]
	v_mfma_f32_16x16x32_bf16 v[92:95], v[168:171], v[230:233], v[92:95]
	v_mfma_f32_16x16x32_bf16 v[80:83], v[160:163], v[238:241], v[80:83]
	v_mfma_f32_16x16x32_bf16 v[76:79], v[168:171], v[238:241], v[76:79]
	s_setprio 0
	s_setprio 1
	v_mfma_f32_16x16x32_bf16 v[120:123], v[172:175], v[188:191], v[120:123]
	v_mfma_f32_16x16x32_bf16 v[116:119], v[180:183], v[188:191], v[116:119]
	v_mfma_f32_16x16x32_bf16 v[104:107], v[172:175], v[218:221], v[104:107]
	v_mfma_f32_16x16x32_bf16 v[100:103], v[180:183], v[218:221], v[100:103]
	v_mfma_f32_16x16x32_bf16 v[88:91], v[172:175], v[226:229], v[88:91]
	v_mfma_f32_16x16x32_bf16 v[84:87], v[180:183], v[226:229], v[84:87]
	v_mfma_f32_16x16x32_bf16 v[70:73], v[172:175], v[234:237], v[72:75]
	v_mfma_f32_16x16x32_bf16 v[66:69], v[180:183], v[234:237], v[66:69]
	v_mfma_f32_16x16x32_bf16 v[120:123], v[176:179], v[214:217], v[120:123]
	v_mfma_f32_16x16x32_bf16 v[116:119], v[184:187], v[214:217], v[116:119]
	v_mfma_f32_16x16x32_bf16 v[104:107], v[176:179], v[222:225], v[104:107]
	v_mfma_f32_16x16x32_bf16 v[100:103], v[184:187], v[222:225], v[100:103]
	v_mfma_f32_16x16x32_bf16 v[88:91], v[176:179], v[230:233], v[88:91]
	v_mfma_f32_16x16x32_bf16 v[84:87], v[184:187], v[230:233], v[84:87]
	v_mfma_f32_16x16x32_bf16 v[72:75], v[176:179], v[238:241], v[70:73]
	v_mfma_f32_16x16x32_bf16 v[68:71], v[184:187], v[238:241], v[66:69]
	s_setprio 0
	s_barrier
; #define PG8_STAGE(bufoff, gbase, voff) do { _Pragma("unroll") for (int _i = 0; _i < 2; ++_i) \
;         __builtin_amdgcn_global_load_lds((const unsigned*)((const char*)(gbase) + (voff)[_i]), (LAS unsigned*)(lds + (bufoff) + ldsw + _i * 8192), 16, 0, 0); } while (0)
; #define PG8_LDA(dst, b, h) do { _Pragma("unroll") for (int m = 0; m < 4; ++m) _Pragma("unroll") for (int k = 0; k < 2; ++k) dst[m][k] = *(const LAS bf16x8*)(lds + PG8_SA(b, h) + aoff + m * 2048 + k * 1024); } while (0)
; #define PG8_MMA(ai, bj, At, Bt) do { __builtin_amdgcn_s_setprio(1); _Pragma("unroll") for (int m = 0; m < 4; ++m) _Pragma("unroll") for (int n = 0; n < 2; ++n) _Pragma("unroll") for (int k = 0; k < 2; ++k) \
;         acc[ai][bj][m][n] = __builtin_amdgcn_mfma_f32_16x16x32_bf16(Bt[n][k], At[m][k], acc[ai][bj][m][n], 0, 0, 0); __builtin_amdgcn_s_setprio(0); } while (0)
; #define PG8_WAIT_V(n) asm volatile("s_waitcnt vmcnt(" #n ")" ::: "memory")
; #define PG8_WAIT_L(n) asm volatile("s_waitcnt lgkmcnt(" #n ")" ::: "memory")
; #define PG8_BAR __builtin_amdgcn_s_barrier()
; #define PG8_SCHED __builtin_amdgcn_sched_barrier(0)
; template <class Epi, bool SP2, class Sched>
; __device__ __forceinline__ void gemm_phase(LAS unsigned char* lds, const Gemm g, const Sched& S, const Epi& E) {
;     ...
;         for (int t = 0; t < nt; t += 2) {
;     ...
;             PG8_LDA(At, 1, 1); PG8_STAGE(PG8_SB(1, 0), b3, voffB); PG8_STAGE(PG8_SB(1, 1), b3 + hstepB, voffB); PG8_STAGE(PG8_SA(1, 0), a3, voffA);
;             PG8_WAIT_V(8); PG8_WAIT_L(0); PG8_BAR; PG8_MMA(1, 0, At, B0); PG8_MMA(1, 1, At, B1); PG8_BAR; PG8_SCHED;
	s_add_i32 s10, s19, s73
	v_lshl_add_u64 v[66:67], v[192:193], 0, s[66:67]
	s_mov_b32 m0, s10
	ds_read_b128 v[188:191], v155 offset:49152
	ds_read_b128 v[214:217], v155 offset:50176
	ds_read_b128 v[218:221], v155 offset:51200
	ds_read_b128 v[222:225], v155 offset:52224
	ds_read_b128 v[226:229], v155 offset:53248
	ds_read_b128 v[230:233], v155 offset:54272
	ds_read_b128 v[234:237], v155 offset:55296
	ds_read_b128 v[238:241], v155 offset:56320
	global_load_lds_dwordx4 v[66:67], off
	s_add_i32 m0, s10, 0x2000
	s_add_u32 s6, s6, 0x40080
	v_lshl_add_u64 v[66:67], v[248:249], 0, s[66:67]
	s_addc_u32 s7, s7, 0
	s_add_i32 s10, s20, s73
	global_load_lds_dwordx4 v[66:67], off
	v_lshl_add_u64 v[66:67], s[6:7], 0, v[134:135]
	s_mov_b32 m0, s10
	s_nop 0
	global_load_lds_dwordx4 v[66:67], off
	v_lshl_add_u64 v[66:67], s[6:7], 0, v[138:139]
	s_add_i32 m0, s10, 0x2000
	s_nop 0
	global_load_lds_dwordx4 v[66:67], off
	v_lshl_add_u64 v[66:67], v[250:251], 0, s[66:67]
	s_mov_b32 m0, s75
	s_nop 0
	global_load_lds_dwordx4 v[66:67], off
	v_lshl_add_u64 v[66:67], v[252:253], 0, s[66:67]
	s_mov_b32 m0, s76
	s_nop 0
	global_load_lds_dwordx4 v[66:67], off
	s_waitcnt vmcnt(8) lgkmcnt(0)
	s_barrier
	s_setprio 1
	v_mfma_f32_16x16x32_bf16 v[60:63], v[156:159], v[188:191], v[60:63]
	v_mfma_f32_16x16x32_bf16 v[56:59], v[164:167], v[188:191], v[56:59]
	v_mfma_f32_16x16x32_bf16 v[44:47], v[156:159], v[218:221], v[44:47]
	v_mfma_f32_16x16x32_bf16 v[40:43], v[164:167], v[218:221], v[40:43]
	v_mfma_f32_16x16x32_bf16 v[28:31], v[156:159], v[226:229], v[28:31]
	v_mfma_f32_16x16x32_bf16 v[24:27], v[164:167], v[226:229], v[24:27]
	v_mfma_f32_16x16x32_bf16 v[12:15], v[156:159], v[234:237], v[12:15]
	v_mfma_f32_16x16x32_bf16 v[8:11], v[164:167], v[234:237], v[8:11]
	v_mfma_f32_16x16x32_bf16 v[60:63], v[160:163], v[214:217], v[60:63]
	v_mfma_f32_16x16x32_bf16 v[56:59], v[168:171], v[214:217], v[56:59]
	v_mfma_f32_16x16x32_bf16 v[44:47], v[160:163], v[222:225], v[44:47]
	v_mfma_f32_16x16x32_bf16 v[40:43], v[168:171], v[222:225], v[40:43]
	v_mfma_f32_16x16x32_bf16 v[28:31], v[160:163], v[230:233], v[28:31]
	v_mfma_f32_16x16x32_bf16 v[24:27], v[168:171], v[230:233], v[24:27]
	v_mfma_f32_16x16x32_bf16 v[12:15], v[160:163], v[238:241], v[12:15]
	v_mfma_f32_16x16x32_bf16 v[8:11], v[168:171], v[238:241], v[8:11]
	s_setprio 0
	s_setprio 1
	v_mfma_f32_16x16x32_bf16 v[52:55], v[172:175], v[188:191], v[52:55]
	v_mfma_f32_16x16x32_bf16 v[48:51], v[180:183], v[188:191], v[48:51]
	v_mfma_f32_16x16x32_bf16 v[36:39], v[172:175], v[218:221], v[36:39]
	v_mfma_f32_16x16x32_bf16 v[32:35], v[180:183], v[218:221], v[32:35]
	v_mfma_f32_16x16x32_bf16 v[20:23], v[172:175], v[226:229], v[20:23]
	v_mfma_f32_16x16x32_bf16 v[16:19], v[180:183], v[226:229], v[16:19]
	v_mfma_f32_16x16x32_bf16 v[4:7], v[172:175], v[234:237], v[4:7]
	v_mfma_f32_16x16x32_bf16 v[0:3], v[180:183], v[234:237], v[0:3]
	v_mfma_f32_16x16x32_bf16 v[52:55], v[176:179], v[214:217], v[52:55]
	v_mfma_f32_16x16x32_bf16 v[48:51], v[184:187], v[214:217], v[48:51]
	v_mfma_f32_16x16x32_bf16 v[36:39], v[176:179], v[222:225], v[36:39]
	v_mfma_f32_16x16x32_bf16 v[32:35], v[184:187], v[222:225], v[32:35]
	v_mfma_f32_16x16x32_bf16 v[20:23], v[176:179], v[230:233], v[20:23]
	v_mfma_f32_16x16x32_bf16 v[16:19], v[184:187], v[230:233], v[16:19]
	v_mfma_f32_16x16x32_bf16 v[4:7], v[176:179], v[238:241], v[4:7]
	v_mfma_f32_16x16x32_bf16 v[0:3], v[184:187], v[238:241], v[0:3]
	s_setprio 0
	s_barrier
	s_add_i32 s18, s18, 2
	s_add_u32 s96, s96, 0x100
	s_addc_u32 s97, s97, 0
	s_cmp_gt_u32 s18, 13
	s_cbranch_scc1 .LBB0_676

; #define PG8_STAGE(bufoff, gbase, voff) do { _Pragma("unroll") for (int _i = 0; _i < 2; ++_i) \
;         __builtin_amdgcn_global_load_lds((const unsigned*)((const char*)(gbase) + (voff)[_i]), (LAS unsigned*)(lds + (bufoff) + ldsw + _i * 8192), 16, 0, 0); } while (0)
; #define PG8_LDA(dst, b, h) do { _Pragma("unroll") for (int m = 0; m < 4; ++m) _Pragma("unroll") for (int k = 0; k < 2; ++k) dst[m][k] = *(const LAS bf16x8*)(lds + PG8_SA(b, h) + aoff + m * 2048 + k * 1024); } while (0)
; #define PG8_LDB(dst, b, h) do { _Pragma("unroll") for (int n = 0; n < 2; ++n) _Pragma("unroll") for (int k = 0; k < 2; ++k) dst[n][k] = *(const LAS bf16x8*)(lds + PG8_SB(b, h) + boff + n * 2048 + k * 1024); } while (0)
; #define PG8_MMA(ai, bj, At, Bt) do { __builtin_amdgcn_s_setprio(1); _Pragma("unroll") for (int m = 0; m < 4; ++m) _Pragma("unroll") for (int n = 0; n < 2; ++n) _Pragma("unroll") for (int k = 0; k < 2; ++k) \
;         acc[ai][bj][m][n] = __builtin_amdgcn_mfma_f32_16x16x32_bf16(Bt[n][k], At[m][k], acc[ai][bj][m][n], 0, 0, 0); __builtin_amdgcn_s_setprio(0); } while (0)
; #define PG8_BAR __builtin_amdgcn_s_barrier()
; template <class Epi, bool SP2, class Sched>
; __device__ __forceinline__ void gemm_phase(LAS unsigned char* lds, const Gemm g, const Sched& S, const Epi& E) {
;     ...
;         const bool has_next = S.next(ui + 1, nxt);
;         const char* nA = has_next ? (const char*)g.A + (size_t)nxt.pm * tstep + nxt.ko : cA; const char* nB = has_next ? (const char*)g.Bt + (size_t)nxt.pn * tstepB + nxt.ko : cB;
;         for (int t = 0; t < nt; t += 2) {
;             const bool last = (t == nt - 2);
;             const char* a1 = cA + (size_t)(t + 1) * kstep;
;             const char* a2 = last ? nA : cA + (size_t)(t + 2) * kstep; const char* b2 = last ? nB : cB + (size_t)(t + 2) * kstep;
;             const char* a3 = a2 + kstep; const char* b3 = b2 + kstep;
;             if constexpr (Epi::MID) { if (t == (nt >> 1)) E.mid(acc, cur, wr, fr); }
;             if constexpr (SP2) {
;             PG8_LDB(B0, 0, 0); PG8_LDB(B1, 0, 1); PG8_SCHED; PG8_LDA(At, 0, 0); PG8_STAGE(PG8_SA(1, 1), a1 + hstep, voffA);
;             PG8_WAIT_V(8); PG8_WAIT_L(0); PG8_BAR; PG8_MMA(0, 0, At, B0); PG8_MMA(0, 1, At, B1); PG8_BAR; PG8_SCHED;
;             PG8_LDA(At, 0, 1); PG8_STAGE(PG8_SB(0, 0), b2, voffB); PG8_STAGE(PG8_SB(0, 1), b2 + hstepB, voffB); PG8_STAGE(PG8_SA(0, 0), a2, voffA);
.LBB0_715:
	s_add_u32 s6, s90, 0xfffc0080
	s_addc_u32 s7, s91, -1
	s_add_i32 s22, 0, 0x10000
	s_cmp_eq_u32 s21, 12
	s_cselect_b32 s11, s19, s7
	s_cselect_b32 s10, s33, s6
	v_add_u32_e32 v140, s22, v143
	s_cselect_b32 s7, s76, s20
	s_cselect_b32 s6, s77, s79
	s_add_i32 s24, 0, 0x14000
	ds_read_b128 v[136:139], v140
	ds_read_b128 v[146:149], v140 offset:1024
	ds_read_b128 v[150:153], v140 offset:2048
	ds_read_b128 v[154:157], v140 offset:3072
	v_add_u32_e32 v140, s24, v143
	ds_read_b128 v[158:161], v140
	ds_read_b128 v[162:165], v140 offset:1024
	ds_read_b128 v[166:169], v140 offset:2048
	ds_read_b128 v[170:173], v140 offset:3072
	v_lshl_add_u64 v[140:141], s[90:91], 0, v[134:135]
	s_add_i32 m0, s17, 0xc000
	ds_read_b128 v[174:177], v145
	ds_read_b128 v[178:181], v145 offset:1024
	ds_read_b128 v[182:185], v145 offset:2048
	ds_read_b128 v[186:189], v145 offset:3072
	ds_read_b128 v[190:193], v145 offset:4096
	ds_read_b128 v[214:217], v145 offset:5120
	ds_read_b128 v[218:221], v145 offset:6144
	ds_read_b128 v[222:225], v145 offset:7168
	global_load_lds_dwordx4 v[140:141], off
	v_lshl_add_u64 v[140:141], s[90:91], 0, v[132:133]
	s_add_i32 m0, s17, 0xe000
	s_nop 0
	global_load_lds_dwordx4 v[140:141], off
	s_waitcnt vmcnt(8) lgkmcnt(0)
	s_barrier
	s_setprio 1
	v_mfma_f32_16x16x32_bf16 v[126:129], v[136:139], v[174:177], v[126:129]
	v_mfma_f32_16x16x32_bf16 v[122:125], v[150:153], v[174:177], v[122:125]
	v_mfma_f32_16x16x32_bf16 v[110:113], v[136:139], v[182:185], v[110:113]
	v_mfma_f32_16x16x32_bf16 v[106:109], v[150:153], v[182:185], v[106:109]
	v_mfma_f32_16x16x32_bf16 v[94:97], v[136:139], v[190:193], v[94:97]
	v_mfma_f32_16x16x32_bf16 v[90:93], v[150:153], v[190:193], v[90:93]
	v_mfma_f32_16x16x32_bf16 v[78:81], v[136:139], v[218:221], v[78:81]
	v_mfma_f32_16x16x32_bf16 v[74:77], v[150:153], v[218:221], v[74:77]
	v_mfma_f32_16x16x32_bf16 v[126:129], v[146:149], v[178:181], v[126:129]
	v_mfma_f32_16x16x32_bf16 v[122:125], v[154:157], v[178:181], v[122:125]
	v_mfma_f32_16x16x32_bf16 v[110:113], v[146:149], v[186:189], v[110:113]
	v_mfma_f32_16x16x32_bf16 v[106:109], v[154:157], v[186:189], v[106:109]
	v_mfma_f32_16x16x32_bf16 v[94:97], v[146:149], v[214:217], v[94:97]
	v_mfma_f32_16x16x32_bf16 v[90:93], v[154:157], v[214:217], v[90:93]
	v_mfma_f32_16x16x32_bf16 v[78:81], v[146:149], v[222:225], v[78:81]
	v_mfma_f32_16x16x32_bf16 v[74:77], v[154:157], v[222:225], v[74:77]
	s_setprio 0
	s_setprio 1
	v_mfma_f32_16x16x32_bf16 v[118:121], v[158:161], v[174:177], v[118:121]
	v_mfma_f32_16x16x32_bf16 v[114:117], v[166:169], v[174:177], v[114:117]
	v_mfma_f32_16x16x32_bf16 v[102:105], v[158:161], v[182:185], v[102:105]
	v_mfma_f32_16x16x32_bf16 v[98:101], v[166:169], v[182:185], v[98:101]
	v_mfma_f32_16x16x32_bf16 v[86:89], v[158:161], v[190:193], v[86:89]
	v_mfma_f32_16x16x32_bf16 v[82:85], v[166:169], v[190:193], v[82:85]
	v_mfma_f32_16x16x32_bf16 v[70:73], v[158:161], v[218:221], v[70:73]
	v_mfma_f32_16x16x32_bf16 v[66:69], v[166:169], v[218:221], v[66:69]
	v_mfma_f32_16x16x32_bf16 v[118:121], v[162:165], v[178:181], v[118:121]
	v_mfma_f32_16x16x32_bf16 v[114:117], v[170:173], v[178:181], v[114:117]
	v_mfma_f32_16x16x32_bf16 v[102:105], v[162:165], v[186:189], v[102:105]
	v_mfma_f32_16x16x32_bf16 v[98:101], v[170:173], v[186:189], v[98:101]
	v_mfma_f32_16x16x32_bf16 v[86:89], v[162:165], v[214:217], v[86:89]
	v_mfma_f32_16x16x32_bf16 v[82:85], v[170:173], v[214:217], v[82:85]
	v_mfma_f32_16x16x32_bf16 v[70:73], v[162:165], v[222:225], v[70:73]
	v_mfma_f32_16x16x32_bf16 v[66:69], v[170:173], v[222:225], v[66:69]
	s_setprio 0
	s_barrier
	s_add_i32 s22, s22, s72
	v_lshl_add_u64 v[140:141], s[6:7], 0, v[64:65]
	s_mov_b32 m0, s22
	ds_read_b128 v[174:177], v145 offset:16384
	ds_read_b128 v[178:181], v145 offset:17408
	ds_read_b128 v[182:185], v145 offset:18432
	ds_read_b128 v[186:189], v145 offset:19456
	ds_read_b128 v[190:193], v145 offset:20480
	ds_read_b128 v[214:217], v145 offset:21504
	ds_read_b128 v[218:221], v145 offset:22528
	ds_read_b128 v[222:225], v145 offset:23552
	global_load_lds_dwordx4 v[140:141], off
	s_add_i32 m0, s22, 0x2000
	s_add_u32 s22, s6, 0x40000
	v_lshl_add_u64 v[226:227], s[6:7], 0, v[130:131]
	s_addc_u32 s23, s7, 0
	s_add_i32 s24, s24, s72
	global_load_lds_dwordx4 v[226:227], off
	v_lshl_add_u64 v[228:229], s[22:23], 0, v[64:65]
	s_mov_b32 m0, s24
	v_lshl_add_u64 v[230:231], s[10:11], 0, v[130:131]
	global_load_lds_dwordx4 v[228:229], off
	v_lshl_add_u64 v[228:229], s[22:23], 0, v[130:131]
	s_add_i32 m0, s24, 0x2000
	s_nop 0
	global_load_lds_dwordx4 v[228:229], off
	v_lshl_add_u64 v[228:229], s[10:11], 0, v[64:65]
	s_mov_b32 m0, s17
	s_nop 0
	global_load_lds_dwordx4 v[228:229], off
	s_mov_b32 m0, s73
	s_nop 0
	global_load_lds_dwordx4 v[230:231], off
	s_waitcnt vmcnt(8) lgkmcnt(0)
	s_barrier
; #define PG8_STAGE(bufoff, gbase, voff) do { _Pragma("unroll") for (int _i = 0; _i < 2; ++_i) \
;         __builtin_amdgcn_global_load_lds((const unsigned*)((const char*)(gbase) + (voff)[_i]), (LAS unsigned*)(lds + (bufoff) + ldsw + _i * 8192), 16, 0, 0); } while (0)
; #define PG8_LDA(dst, b, h) do { _Pragma("unroll") for (int m = 0; m < 4; ++m) _Pragma("unroll") for (int k = 0; k < 2; ++k) dst[m][k] = *(const LAS bf16x8*)(lds + PG8_SA(b, h) + aoff + m * 2048 + k * 1024); } while (0)
; #define PG8_LDB(dst, b, h) do { _Pragma("unroll") for (int n = 0; n < 2; ++n) _Pragma("unroll") for (int k = 0; k < 2; ++k) dst[n][k] = *(const LAS bf16x8*)(lds + PG8_SB(b, h) + boff + n * 2048 + k * 1024); } while (0)
; #define PG8_MMA(ai, bj, At, Bt) do { __builtin_amdgcn_s_setprio(1); _Pragma("unroll") for (int m = 0; m < 4; ++m) _Pragma("unroll") for (int n = 0; n < 2; ++n) _Pragma("unroll") for (int k = 0; k < 2; ++k) \
;         acc[ai][bj][m][n] = __builtin_amdgcn_mfma_f32_16x16x32_bf16(Bt[n][k], At[m][k], acc[ai][bj][m][n], 0, 0, 0); __builtin_amdgcn_s_setprio(0); } while (0)
; #define PG8_WAIT_V(n) asm volatile("s_waitcnt vmcnt(" #n ")" ::: "memory")
; #define PG8_WAIT_L(n) asm volatile("s_waitcnt lgkmcnt(" #n ")" ::: "memory")
; #define PG8_BAR __builtin_amdgcn_s_barrier()
; #define PG8_SCHED __builtin_amdgcn_sched_barrier(0)
; template <class Epi, bool SP2, class Sched>
; __device__ __forceinline__ void gemm_phase(LAS unsigned char* lds, const Gemm g, const Sched& S, const Epi& E) {
;     ...
;             PG8_WAIT_V(8); PG8_WAIT_L(0); PG8_BAR; PG8_MMA(1, 0, At, B0); PG8_MMA(1, 1, At, B1); PG8_BAR; PG8_SCHED;
;             PG8_LDB(B0, 1, 0); PG8_LDB(B1, 1, 1); PG8_SCHED; PG8_LDA(At, 1, 0); PG8_STAGE(PG8_SA(0, 1), a2 + hstep, voffA);
;             PG8_WAIT_V(8); PG8_WAIT_L(0); PG8_BAR; PG8_MMA(0, 0, At, B0); PG8_MMA(0, 1, At, B1); PG8_BAR; PG8_SCHED;
	s_setprio 1
	v_mfma_f32_16x16x32_bf16 v[60:63], v[136:139], v[174:177], v[60:63]
	v_mfma_f32_16x16x32_bf16 v[56:59], v[150:153], v[174:177], v[56:59]
	v_mfma_f32_16x16x32_bf16 v[44:47], v[136:139], v[182:185], v[44:47]
	v_mfma_f32_16x16x32_bf16 v[40:43], v[150:153], v[182:185], v[40:43]
	v_mfma_f32_16x16x32_bf16 v[28:31], v[136:139], v[190:193], v[28:31]
	v_mfma_f32_16x16x32_bf16 v[24:27], v[150:153], v[190:193], v[24:27]
	v_mfma_f32_16x16x32_bf16 v[12:15], v[136:139], v[218:221], v[12:15]
	v_mfma_f32_16x16x32_bf16 v[8:11], v[150:153], v[218:221], v[8:11]
	v_mfma_f32_16x16x32_bf16 v[60:63], v[146:149], v[178:181], v[60:63]
	v_mfma_f32_16x16x32_bf16 v[56:59], v[154:157], v[178:181], v[56:59]
	v_mfma_f32_16x16x32_bf16 v[44:47], v[146:149], v[186:189], v[44:47]
	v_mfma_f32_16x16x32_bf16 v[40:43], v[154:157], v[186:189], v[40:43]
	v_mfma_f32_16x16x32_bf16 v[28:31], v[146:149], v[214:217], v[28:31]
	v_mfma_f32_16x16x32_bf16 v[24:27], v[154:157], v[214:217], v[24:27]
	v_mfma_f32_16x16x32_bf16 v[12:15], v[146:149], v[222:225], v[12:15]
	v_mfma_f32_16x16x32_bf16 v[8:11], v[154:157], v[222:225], v[8:11]
	s_setprio 0
	s_setprio 1
	v_mfma_f32_16x16x32_bf16 v[52:55], v[158:161], v[174:177], v[52:55]
	v_mfma_f32_16x16x32_bf16 v[48:51], v[166:169], v[174:177], v[48:51]
	v_mfma_f32_16x16x32_bf16 v[36:39], v[158:161], v[182:185], v[36:39]
	v_mfma_f32_16x16x32_bf16 v[32:35], v[166:169], v[182:185], v[32:35]
	v_mfma_f32_16x16x32_bf16 v[20:23], v[158:161], v[190:193], v[20:23]
	v_mfma_f32_16x16x32_bf16 v[16:19], v[166:169], v[190:193], v[16:19]
	v_mfma_f32_16x16x32_bf16 v[4:7], v[158:161], v[218:221], v[4:7]
	v_mfma_f32_16x16x32_bf16 v[0:3], v[166:169], v[218:221], v[0:3]
	v_mfma_f32_16x16x32_bf16 v[52:55], v[162:165], v[178:181], v[52:55]
	v_mfma_f32_16x16x32_bf16 v[48:51], v[170:173], v[178:181], v[48:51]
	v_mfma_f32_16x16x32_bf16 v[36:39], v[162:165], v[186:189], v[36:39]
	v_mfma_f32_16x16x32_bf16 v[32:35], v[170:173], v[186:189], v[32:35]
	v_mfma_f32_16x16x32_bf16 v[20:23], v[162:165], v[214:217], v[20:23]
	v_mfma_f32_16x16x32_bf16 v[16:19], v[170:173], v[214:217], v[16:19]
	v_mfma_f32_16x16x32_bf16 v[4:7], v[162:165], v[222:225], v[4:7]
	v_mfma_f32_16x16x32_bf16 v[0:3], v[170:173], v[222:225], v[0:3]
	s_setprio 0
	s_barrier
	s_add_i32 s22, 0, 0x18000
	s_add_i32 s23, 0, 0x1c000
	v_add_u32_e32 v154, s22, v143
	v_add_u32_e32 v170, s23, v143
	ds_read_b128 v[136:139], v154
	ds_read_b128 v[146:149], v154 offset:1024
	ds_read_b128 v[150:153], v154 offset:2048
	ds_read_b128 v[154:157], v154 offset:3072
	ds_read_b128 v[158:161], v170
	ds_read_b128 v[162:165], v170 offset:1024
	ds_read_b128 v[166:169], v170 offset:2048
	ds_read_b128 v[170:173], v170 offset:3072
	s_add_u32 s10, s10, 0x40000
	s_addc_u32 s11, s11, 0
	s_mov_b32 m0, s74
	v_lshl_add_u64 v[232:233], s[10:11], 0, v[64:65]
	ds_read_b128 v[174:177], v145 offset:32768
	ds_read_b128 v[178:181], v145 offset:33792
	ds_read_b128 v[182:185], v145 offset:34816
	ds_read_b128 v[186:189], v145 offset:35840
	ds_read_b128 v[190:193], v145 offset:36864
	ds_read_b128 v[214:217], v145 offset:37888
	ds_read_b128 v[218:221], v145 offset:38912
	ds_read_b128 v[222:225], v145 offset:39936
	global_load_lds_dwordx4 v[232:233], off
	v_lshl_add_u64 v[232:233], s[10:11], 0, v[130:131]
	s_mov_b32 m0, s75
	s_nop 0
	global_load_lds_dwordx4 v[232:233], off
	s_waitcnt vmcnt(8) lgkmcnt(0)
	s_barrier
	s_setprio 1
	v_mfma_f32_16x16x32_bf16 v[126:129], v[136:139], v[174:177], v[126:129]
	v_mfma_f32_16x16x32_bf16 v[122:125], v[150:153], v[174:177], v[122:125]
	v_mfma_f32_16x16x32_bf16 v[110:113], v[136:139], v[182:185], v[110:113]
	v_mfma_f32_16x16x32_bf16 v[106:109], v[150:153], v[182:185], v[106:109]
	v_mfma_f32_16x16x32_bf16 v[94:97], v[136:139], v[190:193], v[94:97]
	v_mfma_f32_16x16x32_bf16 v[90:93], v[150:153], v[190:193], v[90:93]
	v_mfma_f32_16x16x32_bf16 v[78:81], v[136:139], v[218:221], v[78:81]
	v_mfma_f32_16x16x32_bf16 v[74:77], v[150:153], v[218:221], v[74:77]
	v_mfma_f32_16x16x32_bf16 v[126:129], v[146:149], v[178:181], v[126:129]
	v_mfma_f32_16x16x32_bf16 v[122:125], v[154:157], v[178:181], v[122:125]
	v_mfma_f32_16x16x32_bf16 v[110:113], v[146:149], v[186:189], v[110:113]
	v_mfma_f32_16x16x32_bf16 v[106:109], v[154:157], v[186:189], v[106:109]
	v_mfma_f32_16x16x32_bf16 v[94:97], v[146:149], v[214:217], v[94:97]
	v_mfma_f32_16x16x32_bf16 v[90:93], v[154:157], v[214:217], v[90:93]
	v_mfma_f32_16x16x32_bf16 v[78:81], v[146:149], v[222:225], v[78:81]
	v_mfma_f32_16x16x32_bf16 v[74:77], v[154:157], v[222:225], v[74:77]
	s_setprio 0
	s_setprio 1
	v_mfma_f32_16x16x32_bf16 v[118:121], v[158:161], v[174:177], v[118:121]
	v_mfma_f32_16x16x32_bf16 v[114:117], v[166:169], v[174:177], v[114:117]
	v_mfma_f32_16x16x32_bf16 v[102:105], v[158:161], v[182:185], v[102:105]
	v_mfma_f32_16x16x32_bf16 v[98:101], v[166:169], v[182:185], v[98:101]
	v_mfma_f32_16x16x32_bf16 v[86:89], v[158:161], v[190:193], v[86:89]
	v_mfma_f32_16x16x32_bf16 v[82:85], v[166:169], v[190:193], v[82:85]
	v_mfma_f32_16x16x32_bf16 v[70:73], v[158:161], v[218:221], v[70:73]
	v_mfma_f32_16x16x32_bf16 v[66:69], v[166:169], v[218:221], v[66:69]
	v_mfma_f32_16x16x32_bf16 v[118:121], v[162:165], v[178:181], v[118:121]
	v_mfma_f32_16x16x32_bf16 v[114:117], v[170:173], v[178:181], v[114:117]
	v_mfma_f32_16x16x32_bf16 v[102:105], v[162:165], v[186:189], v[102:105]
	v_mfma_f32_16x16x32_bf16 v[98:101], v[170:173], v[186:189], v[98:101]
	v_mfma_f32_16x16x32_bf16 v[86:89], v[162:165], v[214:217], v[86:89]
	v_mfma_f32_16x16x32_bf16 v[82:85], v[170:173], v[214:217], v[82:85]
	v_mfma_f32_16x16x32_bf16 v[70:73], v[162:165], v[222:225], v[70:73]
	v_mfma_f32_16x16x32_bf16 v[66:69], v[170:173], v[222:225], v[66:69]
	s_setprio 0
	s_barrier
; #define PG8_STAGE(bufoff, gbase, voff) do { _Pragma("unroll") for (int _i = 0; _i < 2; ++_i) \
;         __builtin_amdgcn_global_load_lds((const unsigned*)((const char*)(gbase) + (voff)[_i]), (LAS unsigned*)(lds + (bufoff) + ldsw + _i * 8192), 16, 0, 0); } while (0)
; #define PG8_LDA(dst, b, h) do { _Pragma("unroll") for (int m = 0; m < 4; ++m) _Pragma("unroll") for (int k = 0; k < 2; ++k) dst[m][k] = *(const LAS bf16x8*)(lds + PG8_SA(b, h) + aoff + m * 2048 + k * 1024); } while (0)
; #define PG8_MMA(ai, bj, At, Bt) do { __builtin_amdgcn_s_setprio(1); _Pragma("unroll") for (int m = 0; m < 4; ++m) _Pragma("unroll") for (int n = 0; n < 2; ++n) _Pragma("unroll") for (int k = 0; k < 2; ++k) \
;         acc[ai][bj][m][n] = __builtin_amdgcn_mfma_f32_16x16x32_bf16(Bt[n][k], At[m][k], acc[ai][bj][m][n], 0, 0, 0); __builtin_amdgcn_s_setprio(0); } while (0)
; #define PG8_WAIT_V(n) asm volatile("s_waitcnt vmcnt(" #n ")" ::: "memory")
; #define PG8_WAIT_L(n) asm volatile("s_waitcnt lgkmcnt(" #n ")" ::: "memory")
; #define PG8_BAR __builtin_amdgcn_s_barrier()
; #define PG8_SCHED __builtin_amdgcn_sched_barrier(0)
; template <class Epi, bool SP2, class Sched>
; __device__ __forceinline__ void gemm_phase(LAS unsigned char* lds, const Gemm g, const Sched& S, const Epi& E) {
;     ...
;         for (int t = 0; t < nt; t += 2) {
;     ...
;             PG8_LDA(At, 1, 1); PG8_STAGE(PG8_SB(1, 0), b3, voffB); PG8_STAGE(PG8_SB(1, 1), b3 + hstepB, voffB); PG8_STAGE(PG8_SA(1, 0), a3, voffA);
;             PG8_WAIT_V(8); PG8_WAIT_L(0); PG8_BAR; PG8_MMA(1, 0, At, B0); PG8_MMA(1, 1, At, B1); PG8_BAR; PG8_SCHED;
;     ...
;         if (wr == 0) PG8_BAR;
	s_add_i32 s10, s22, s72
	v_lshl_add_u64 v[140:141], v[140:141], 0, s[66:67]
	s_mov_b32 m0, s10
	ds_read_b128 v[174:177], v145 offset:49152
	ds_read_b128 v[178:181], v145 offset:50176
	ds_read_b128 v[182:185], v145 offset:51200
	ds_read_b128 v[186:189], v145 offset:52224
	ds_read_b128 v[190:193], v145 offset:53248
	ds_read_b128 v[214:217], v145 offset:54272
	ds_read_b128 v[218:221], v145 offset:55296
	ds_read_b128 v[222:225], v145 offset:56320
	global_load_lds_dwordx4 v[140:141], off
	s_add_i32 m0, s10, 0x2000
	s_add_u32 s6, s6, 0x40080
	v_lshl_add_u64 v[140:141], v[226:227], 0, s[66:67]
	s_addc_u32 s7, s7, 0
	s_add_i32 s10, s23, s72
	global_load_lds_dwordx4 v[140:141], off
	v_lshl_add_u64 v[140:141], s[6:7], 0, v[64:65]
	s_mov_b32 m0, s10
	s_nop 0
	global_load_lds_dwordx4 v[140:141], off
	v_lshl_add_u64 v[140:141], s[6:7], 0, v[130:131]
	s_add_i32 m0, s10, 0x2000
	s_nop 0
	global_load_lds_dwordx4 v[140:141], off
	v_lshl_add_u64 v[140:141], v[228:229], 0, s[66:67]
	s_mov_b32 m0, s12
	s_nop 0
	global_load_lds_dwordx4 v[140:141], off
	v_lshl_add_u64 v[140:141], v[230:231], 0, s[66:67]
	s_mov_b32 m0, s13
	s_nop 0
	global_load_lds_dwordx4 v[140:141], off
	s_waitcnt vmcnt(8) lgkmcnt(0)
	s_barrier
	s_setprio 1
	v_mfma_f32_16x16x32_bf16 v[60:63], v[136:139], v[174:177], v[60:63]
	v_mfma_f32_16x16x32_bf16 v[56:59], v[150:153], v[174:177], v[56:59]
	v_mfma_f32_16x16x32_bf16 v[44:47], v[136:139], v[182:185], v[44:47]
	v_mfma_f32_16x16x32_bf16 v[40:43], v[150:153], v[182:185], v[40:43]
	v_mfma_f32_16x16x32_bf16 v[28:31], v[136:139], v[190:193], v[28:31]
	v_mfma_f32_16x16x32_bf16 v[24:27], v[150:153], v[190:193], v[24:27]
	v_mfma_f32_16x16x32_bf16 v[12:15], v[136:139], v[218:221], v[12:15]
	v_mfma_f32_16x16x32_bf16 v[8:11], v[150:153], v[218:221], v[8:11]
	v_mfma_f32_16x16x32_bf16 v[60:63], v[146:149], v[178:181], v[60:63]
	v_mfma_f32_16x16x32_bf16 v[56:59], v[154:157], v[178:181], v[56:59]
	v_mfma_f32_16x16x32_bf16 v[44:47], v[146:149], v[186:189], v[44:47]
	v_mfma_f32_16x16x32_bf16 v[40:43], v[154:157], v[186:189], v[40:43]
	v_mfma_f32_16x16x32_bf16 v[28:31], v[146:149], v[214:217], v[28:31]
	v_mfma_f32_16x16x32_bf16 v[24:27], v[154:157], v[214:217], v[24:27]
	v_mfma_f32_16x16x32_bf16 v[12:15], v[146:149], v[222:225], v[12:15]
	v_mfma_f32_16x16x32_bf16 v[8:11], v[154:157], v[222:225], v[8:11]
	s_setprio 0
	s_setprio 1
	v_mfma_f32_16x16x32_bf16 v[52:55], v[158:161], v[174:177], v[52:55]
	v_mfma_f32_16x16x32_bf16 v[48:51], v[166:169], v[174:177], v[48:51]
	v_mfma_f32_16x16x32_bf16 v[36:39], v[158:161], v[182:185], v[36:39]
	v_mfma_f32_16x16x32_bf16 v[32:35], v[166:169], v[182:185], v[32:35]
	v_mfma_f32_16x16x32_bf16 v[20:23], v[158:161], v[190:193], v[20:23]
	v_mfma_f32_16x16x32_bf16 v[16:19], v[166:169], v[190:193], v[16:19]
	v_mfma_f32_16x16x32_bf16 v[4:7], v[158:161], v[218:221], v[4:7]
	v_mfma_f32_16x16x32_bf16 v[0:3], v[166:169], v[218:221], v[0:3]
	v_mfma_f32_16x16x32_bf16 v[52:55], v[162:165], v[178:181], v[52:55]
	v_mfma_f32_16x16x32_bf16 v[48:51], v[170:173], v[178:181], v[48:51]
	v_mfma_f32_16x16x32_bf16 v[36:39], v[162:165], v[186:189], v[36:39]
	v_mfma_f32_16x16x32_bf16 v[32:35], v[170:173], v[186:189], v[32:35]
	v_mfma_f32_16x16x32_bf16 v[20:23], v[162:165], v[214:217], v[20:23]
	v_mfma_f32_16x16x32_bf16 v[16:19], v[170:173], v[214:217], v[16:19]
	v_mfma_f32_16x16x32_bf16 v[4:7], v[162:165], v[222:225], v[4:7]
	v_mfma_f32_16x16x32_bf16 v[0:3], v[170:173], v[222:225], v[0:3]
	s_setprio 0
	s_barrier
	s_add_i32 s21, s21, 2
	s_add_u32 s79, s79, 0x100
	s_addc_u32 s20, s20, 0
	s_add_u32 s90, s90, 0x100
	s_addc_u32 s91, s91, 0
	s_cmp_gt_u32 s21, 13
	s_cbranch_scc0 .LBB0_715
	s_and_b64 vcc, exec, s[60:61]
	s_cbranch_vccz .LBB0_718
	s_barrier

; #define PG8_STAGE(bufoff, gbase, voff) do { _Pragma("unroll") for (int _i = 0; _i < 2; ++_i) \
;         __builtin_amdgcn_global_load_lds((const unsigned*)((const char*)(gbase) + (voff)[_i]), (LAS unsigned*)(lds + (bufoff) + ldsw + _i * 8192), 16, 0, 0); } while (0)
; #define PG8_LDA(dst, b, h) do { _Pragma("unroll") for (int m = 0; m < 4; ++m) _Pragma("unroll") for (int k = 0; k < 2; ++k) dst[m][k] = *(const LAS bf16x8*)(lds + PG8_SA(b, h) + aoff + m * 2048 + k * 1024); } while (0)
; #define PG8_LDB(dst, b, h) do { _Pragma("unroll") for (int n = 0; n < 2; ++n) _Pragma("unroll") for (int k = 0; k < 2; ++k) dst[n][k] = *(const LAS bf16x8*)(lds + PG8_SB(b, h) + boff + n * 2048 + k * 1024); } while (0)
; #define PG8_MMA(ai, bj, At, Bt) do { __builtin_amdgcn_s_setprio(1); _Pragma("unroll") for (int m = 0; m < 4; ++m) _Pragma("unroll") for (int n = 0; n < 2; ++n) _Pragma("unroll") for (int k = 0; k < 2; ++k) \
;         acc[ai][bj][m][n] = __builtin_amdgcn_mfma_f32_16x16x32_bf16(Bt[n][k], At[m][k], acc[ai][bj][m][n], 0, 0, 0); __builtin_amdgcn_s_setprio(0); } while (0)
; #define PG8_BAR __builtin_amdgcn_s_barrier()
; template <class Epi, bool SP2, class Sched>
; __device__ __forceinline__ void gemm_phase(LAS unsigned char* lds, const Gemm g, const Sched& S, const Epi& E) {
;     ...
;         const bool has_next = S.next(ui + 1, nxt);
;         const char* nA = has_next ? (const char*)g.A + (size_t)nxt.pm * tstep + nxt.ko : cA; const char* nB = has_next ? (const char*)g.Bt + (size_t)nxt.pn * tstepB + nxt.ko : cB;
;         for (int t = 0; t < nt; t += 2) {
;             const bool last = (t == nt - 2);
;             const char* a1 = cA + (size_t)(t + 1) * kstep;
;             const char* a2 = last ? nA : cA + (size_t)(t + 2) * kstep; const char* b2 = last ? nB : cB + (size_t)(t + 2) * kstep;
;             const char* a3 = a2 + kstep; const char* b3 = b2 + kstep;
;             if constexpr (Epi::MID) { if (t == (nt >> 1)) E.mid(acc, cur, wr, fr); }
;             if constexpr (SP2) {
;             PG8_LDB(B0, 0, 0); PG8_LDB(B1, 0, 1); PG8_SCHED; PG8_LDA(At, 0, 0); PG8_STAGE(PG8_SA(1, 1), a1 + hstep, voffA);
;             PG8_WAIT_V(8); PG8_WAIT_L(0); PG8_BAR; PG8_MMA(0, 0, At, B0); PG8_MMA(0, 1, At, B1); PG8_BAR; PG8_SCHED;
;             PG8_LDA(At, 0, 1); PG8_STAGE(PG8_SB(0, 0), b2, voffB); PG8_STAGE(PG8_SB(0, 1), b2 + hstepB, voffB); PG8_STAGE(PG8_SA(0, 0), a2, voffA);
.LBB0_783:
	s_add_u32 s6, s88, 0xfffc0080
	s_addc_u32 s7, s89, -1
	s_add_i32 s22, 0, 0x10000
	s_cmp_eq_u32 s21, 12
	s_cselect_b32 s11, s61, s7
	s_cselect_b32 s10, s74, s6
	s_cselect_b32 s7, s59, s20
	s_cselect_b32 s6, s75, s76
	s_add_i32 s24, 0, 0x14000
	v_add_u32_e32 v156, s22, v145
	v_add_u32_e32 v172, s24, v145
	ds_read_b128 v[140:143], v156
	ds_read_b128 v[148:151], v156 offset:1024
	ds_read_b128 v[152:155], v156 offset:2048
	ds_read_b128 v[156:159], v156 offset:3072
	ds_read_b128 v[160:163], v172
	ds_read_b128 v[164:167], v172 offset:1024
	ds_read_b128 v[168:171], v172 offset:2048
	ds_read_b128 v[172:175], v172 offset:3072
	v_lshl_add_u64 v[192:193], s[88:89], 0, v[138:139]
	s_add_i32 m0, s12, 0xc000
	ds_read_b128 v[176:179], v147
	ds_read_b128 v[180:183], v147 offset:1024
	ds_read_b128 v[184:187], v147 offset:2048
	ds_read_b128 v[188:191], v147 offset:3072
	ds_read_b128 v[214:217], v147 offset:4096
	ds_read_b128 v[218:221], v147 offset:5120
	ds_read_b128 v[222:225], v147 offset:6144
	ds_read_b128 v[226:229], v147 offset:7168
	global_load_lds_dwordx4 v[192:193], off
	v_lshl_add_u64 v[192:193], s[88:89], 0, v[136:137]
	s_add_i32 m0, s12, 0xe000
	s_nop 0
	global_load_lds_dwordx4 v[192:193], off
	s_waitcnt vmcnt(8) lgkmcnt(0)
	s_barrier
	s_setprio 1
	v_mfma_f32_16x16x32_bf16 v[126:129], v[140:143], v[176:179], v[126:129]
	v_mfma_f32_16x16x32_bf16 v[122:125], v[152:155], v[176:179], v[122:125]
	v_mfma_f32_16x16x32_bf16 v[110:113], v[140:143], v[184:187], v[110:113]
	v_mfma_f32_16x16x32_bf16 v[106:109], v[152:155], v[184:187], v[106:109]
	v_mfma_f32_16x16x32_bf16 v[94:97], v[140:143], v[214:217], v[94:97]
	v_mfma_f32_16x16x32_bf16 v[90:93], v[152:155], v[214:217], v[90:93]
	v_mfma_f32_16x16x32_bf16 v[78:81], v[140:143], v[222:225], v[78:81]
	v_mfma_f32_16x16x32_bf16 v[74:77], v[152:155], v[222:225], v[74:77]
	v_mfma_f32_16x16x32_bf16 v[126:129], v[148:151], v[180:183], v[126:129]
	v_mfma_f32_16x16x32_bf16 v[122:125], v[156:159], v[180:183], v[122:125]
	v_mfma_f32_16x16x32_bf16 v[110:113], v[148:151], v[188:191], v[110:113]
	v_mfma_f32_16x16x32_bf16 v[106:109], v[156:159], v[188:191], v[106:109]
	v_mfma_f32_16x16x32_bf16 v[94:97], v[148:151], v[218:221], v[94:97]
	v_mfma_f32_16x16x32_bf16 v[90:93], v[156:159], v[218:221], v[90:93]
	v_mfma_f32_16x16x32_bf16 v[78:81], v[148:151], v[226:229], v[78:81]
	v_mfma_f32_16x16x32_bf16 v[74:77], v[156:159], v[226:229], v[74:77]
	s_setprio 0
	s_setprio 1
	v_mfma_f32_16x16x32_bf16 v[118:121], v[160:163], v[176:179], v[118:121]
	v_mfma_f32_16x16x32_bf16 v[114:117], v[168:171], v[176:179], v[114:117]
	v_mfma_f32_16x16x32_bf16 v[102:105], v[160:163], v[184:187], v[102:105]
	v_mfma_f32_16x16x32_bf16 v[98:101], v[168:171], v[184:187], v[98:101]
	v_mfma_f32_16x16x32_bf16 v[86:89], v[160:163], v[214:217], v[86:89]
	v_mfma_f32_16x16x32_bf16 v[82:85], v[168:171], v[214:217], v[82:85]
	v_mfma_f32_16x16x32_bf16 v[70:73], v[160:163], v[222:225], v[70:73]
	v_mfma_f32_16x16x32_bf16 v[66:69], v[168:171], v[222:225], v[66:69]
	v_mfma_f32_16x16x32_bf16 v[118:121], v[164:167], v[180:183], v[118:121]
	v_mfma_f32_16x16x32_bf16 v[114:117], v[172:175], v[180:183], v[114:117]
	v_mfma_f32_16x16x32_bf16 v[102:105], v[164:167], v[188:191], v[102:105]
	v_mfma_f32_16x16x32_bf16 v[98:101], v[172:175], v[188:191], v[98:101]
	v_mfma_f32_16x16x32_bf16 v[86:89], v[164:167], v[218:221], v[86:89]
	v_mfma_f32_16x16x32_bf16 v[82:85], v[172:175], v[218:221], v[82:85]
	v_mfma_f32_16x16x32_bf16 v[70:73], v[164:167], v[226:229], v[70:73]
	v_mfma_f32_16x16x32_bf16 v[66:69], v[172:175], v[226:229], v[66:69]
	s_setprio 0
	s_barrier
	s_add_i32 s22, s22, s69
	v_lshl_add_u64 v[192:193], s[6:7], 0, v[64:65]
	s_mov_b32 m0, s22
	ds_read_b128 v[176:179], v147 offset:16384
	ds_read_b128 v[180:183], v147 offset:17408
	ds_read_b128 v[184:187], v147 offset:18432
	ds_read_b128 v[188:191], v147 offset:19456
	ds_read_b128 v[214:217], v147 offset:20480
	ds_read_b128 v[218:221], v147 offset:21504
	ds_read_b128 v[222:225], v147 offset:22528
	ds_read_b128 v[226:229], v147 offset:23552
	global_load_lds_dwordx4 v[192:193], off
	s_add_i32 m0, s22, 0x2000
	s_add_u32 s22, s6, 0x40000
	v_lshl_add_u64 v[230:231], s[6:7], 0, v[130:131]
	s_addc_u32 s23, s7, 0
	s_add_i32 s24, s24, s69
	global_load_lds_dwordx4 v[230:231], off
	v_lshl_add_u64 v[232:233], s[22:23], 0, v[64:65]
	s_mov_b32 m0, s24
	v_lshl_add_u64 v[234:235], s[10:11], 0, v[132:133]
	global_load_lds_dwordx4 v[232:233], off
	v_lshl_add_u64 v[232:233], s[22:23], 0, v[130:131]
	s_add_i32 m0, s24, 0x2000
	s_nop 0
	global_load_lds_dwordx4 v[232:233], off
	v_lshl_add_u64 v[232:233], s[10:11], 0, v[134:135]
	s_mov_b32 m0, s12
	s_nop 0
	global_load_lds_dwordx4 v[232:233], off
	s_mov_b32 m0, s13
	s_nop 0
	global_load_lds_dwordx4 v[234:235], off
	s_waitcnt vmcnt(8) lgkmcnt(0)
	s_barrier
; #define PG8_STAGE(bufoff, gbase, voff) do { _Pragma("unroll") for (int _i = 0; _i < 2; ++_i) \
;         __builtin_amdgcn_global_load_lds((const unsigned*)((const char*)(gbase) + (voff)[_i]), (LAS unsigned*)(lds + (bufoff) + ldsw + _i * 8192), 16, 0, 0); } while (0)
; #define PG8_LDA(dst, b, h) do { _Pragma("unroll") for (int m = 0; m < 4; ++m) _Pragma("unroll") for (int k = 0; k < 2; ++k) dst[m][k] = *(const LAS bf16x8*)(lds + PG8_SA(b, h) + aoff + m * 2048 + k * 1024); } while (0)
; #define PG8_LDB(dst, b, h) do { _Pragma("unroll") for (int n = 0; n < 2; ++n) _Pragma("unroll") for (int k = 0; k < 2; ++k) dst[n][k] = *(const LAS bf16x8*)(lds + PG8_SB(b, h) + boff + n * 2048 + k * 1024); } while (0)
; #define PG8_MMA(ai, bj, At, Bt) do { __builtin_amdgcn_s_setprio(1); _Pragma("unroll") for (int m = 0; m < 4; ++m) _Pragma("unroll") for (int n = 0; n < 2; ++n) _Pragma("unroll") for (int k = 0; k < 2; ++k) \
;         acc[ai][bj][m][n] = __builtin_amdgcn_mfma_f32_16x16x32_bf16(Bt[n][k], At[m][k], acc[ai][bj][m][n], 0, 0, 0); __builtin_amdgcn_s_setprio(0); } while (0)
; #define PG8_WAIT_V(n) asm volatile("s_waitcnt vmcnt(" #n ")" ::: "memory")
; #define PG8_WAIT_L(n) asm volatile("s_waitcnt lgkmcnt(" #n ")" ::: "memory")
; #define PG8_BAR __builtin_amdgcn_s_barrier()
; #define PG8_SCHED __builtin_amdgcn_sched_barrier(0)
; template <class Epi, bool SP2, class Sched>
; __device__ __forceinline__ void gemm_phase(LAS unsigned char* lds, const Gemm g, const Sched& S, const Epi& E) {
;     ...
;             PG8_WAIT_V(8); PG8_WAIT_L(0); PG8_BAR; PG8_MMA(1, 0, At, B0); PG8_MMA(1, 1, At, B1); PG8_BAR; PG8_SCHED;
;             PG8_LDB(B0, 1, 0); PG8_LDB(B1, 1, 1); PG8_SCHED; PG8_LDA(At, 1, 0); PG8_STAGE(PG8_SA(0, 1), a2 + hstep, voffA);
;             PG8_WAIT_V(8); PG8_WAIT_L(0); PG8_BAR; PG8_MMA(0, 0, At, B0); PG8_MMA(0, 1, At, B1); PG8_BAR; PG8_SCHED;
	s_setprio 1
	v_mfma_f32_16x16x32_bf16 v[60:63], v[140:143], v[176:179], v[60:63]
	v_mfma_f32_16x16x32_bf16 v[56:59], v[152:155], v[176:179], v[56:59]
	v_mfma_f32_16x16x32_bf16 v[44:47], v[140:143], v[184:187], v[44:47]
	v_mfma_f32_16x16x32_bf16 v[40:43], v[152:155], v[184:187], v[40:43]
	v_mfma_f32_16x16x32_bf16 v[28:31], v[140:143], v[214:217], v[28:31]
	v_mfma_f32_16x16x32_bf16 v[24:27], v[152:155], v[214:217], v[24:27]
	v_mfma_f32_16x16x32_bf16 v[12:15], v[140:143], v[222:225], v[12:15]
	v_mfma_f32_16x16x32_bf16 v[8:11], v[152:155], v[222:225], v[8:11]
	v_mfma_f32_16x16x32_bf16 v[60:63], v[148:151], v[180:183], v[60:63]
	v_mfma_f32_16x16x32_bf16 v[56:59], v[156:159], v[180:183], v[56:59]
	v_mfma_f32_16x16x32_bf16 v[44:47], v[148:151], v[188:191], v[44:47]
	v_mfma_f32_16x16x32_bf16 v[40:43], v[156:159], v[188:191], v[40:43]
	v_mfma_f32_16x16x32_bf16 v[28:31], v[148:151], v[218:221], v[28:31]
	v_mfma_f32_16x16x32_bf16 v[24:27], v[156:159], v[218:221], v[24:27]
	v_mfma_f32_16x16x32_bf16 v[12:15], v[148:151], v[226:229], v[12:15]
	v_mfma_f32_16x16x32_bf16 v[8:11], v[156:159], v[226:229], v[8:11]
	s_setprio 0
	s_setprio 1
	v_mfma_f32_16x16x32_bf16 v[52:55], v[160:163], v[176:179], v[52:55]
	v_mfma_f32_16x16x32_bf16 v[48:51], v[168:171], v[176:179], v[48:51]
	v_mfma_f32_16x16x32_bf16 v[36:39], v[160:163], v[184:187], v[36:39]
	v_mfma_f32_16x16x32_bf16 v[32:35], v[168:171], v[184:187], v[32:35]
	v_mfma_f32_16x16x32_bf16 v[20:23], v[160:163], v[214:217], v[20:23]
	v_mfma_f32_16x16x32_bf16 v[16:19], v[168:171], v[214:217], v[16:19]
	v_mfma_f32_16x16x32_bf16 v[4:7], v[160:163], v[222:225], v[4:7]
	v_mfma_f32_16x16x32_bf16 v[0:3], v[168:171], v[222:225], v[0:3]
	v_mfma_f32_16x16x32_bf16 v[52:55], v[164:167], v[180:183], v[52:55]
	v_mfma_f32_16x16x32_bf16 v[48:51], v[172:175], v[180:183], v[48:51]
	v_mfma_f32_16x16x32_bf16 v[36:39], v[164:167], v[188:191], v[36:39]
	v_mfma_f32_16x16x32_bf16 v[32:35], v[172:175], v[188:191], v[32:35]
	v_mfma_f32_16x16x32_bf16 v[20:23], v[164:167], v[218:221], v[20:23]
	v_mfma_f32_16x16x32_bf16 v[16:19], v[172:175], v[218:221], v[16:19]
	v_mfma_f32_16x16x32_bf16 v[4:7], v[164:167], v[226:229], v[4:7]
	v_mfma_f32_16x16x32_bf16 v[0:3], v[172:175], v[226:229], v[0:3]
	s_setprio 0
	s_barrier
	s_add_i32 s22, 0, 0x18000
	s_add_i32 s23, 0, 0x1c000
	v_add_u32_e32 v156, s22, v145
	v_add_u32_e32 v172, s23, v145
	ds_read_b128 v[140:143], v156
	ds_read_b128 v[148:151], v156 offset:1024
	ds_read_b128 v[152:155], v156 offset:2048
	ds_read_b128 v[156:159], v156 offset:3072
	ds_read_b128 v[160:163], v172
	ds_read_b128 v[164:167], v172 offset:1024
	ds_read_b128 v[168:171], v172 offset:2048
	ds_read_b128 v[172:175], v172 offset:3072
	s_add_u32 s10, s10, 0x40000
	s_addc_u32 s11, s11, 0
	s_mov_b32 m0, s14
	v_lshl_add_u64 v[236:237], s[10:11], 0, v[134:135]
	ds_read_b128 v[176:179], v147 offset:32768
	ds_read_b128 v[180:183], v147 offset:33792
	ds_read_b128 v[184:187], v147 offset:34816
	ds_read_b128 v[188:191], v147 offset:35840
	ds_read_b128 v[214:217], v147 offset:36864
	ds_read_b128 v[218:221], v147 offset:37888
	ds_read_b128 v[222:225], v147 offset:38912
	ds_read_b128 v[226:229], v147 offset:39936
	global_load_lds_dwordx4 v[236:237], off
	v_lshl_add_u64 v[236:237], s[10:11], 0, v[132:133]
	s_mov_b32 m0, s15
	s_nop 0
	global_load_lds_dwordx4 v[236:237], off
	s_waitcnt vmcnt(8) lgkmcnt(0)
	s_barrier
	s_setprio 1
	v_mfma_f32_16x16x32_bf16 v[126:129], v[140:143], v[176:179], v[126:129]
	v_mfma_f32_16x16x32_bf16 v[122:125], v[152:155], v[176:179], v[122:125]
	v_mfma_f32_16x16x32_bf16 v[110:113], v[140:143], v[184:187], v[110:113]
	v_mfma_f32_16x16x32_bf16 v[106:109], v[152:155], v[184:187], v[106:109]
	v_mfma_f32_16x16x32_bf16 v[94:97], v[140:143], v[214:217], v[94:97]
	v_mfma_f32_16x16x32_bf16 v[90:93], v[152:155], v[214:217], v[90:93]
	v_mfma_f32_16x16x32_bf16 v[78:81], v[140:143], v[222:225], v[78:81]
	v_mfma_f32_16x16x32_bf16 v[74:77], v[152:155], v[222:225], v[74:77]
	v_mfma_f32_16x16x32_bf16 v[126:129], v[148:151], v[180:183], v[126:129]
	v_mfma_f32_16x16x32_bf16 v[122:125], v[156:159], v[180:183], v[122:125]
	v_mfma_f32_16x16x32_bf16 v[110:113], v[148:151], v[188:191], v[110:113]
	v_mfma_f32_16x16x32_bf16 v[106:109], v[156:159], v[188:191], v[106:109]
	v_mfma_f32_16x16x32_bf16 v[94:97], v[148:151], v[218:221], v[94:97]
	v_mfma_f32_16x16x32_bf16 v[90:93], v[156:159], v[218:221], v[90:93]
	v_mfma_f32_16x16x32_bf16 v[78:81], v[148:151], v[226:229], v[78:81]
	v_mfma_f32_16x16x32_bf16 v[74:77], v[156:159], v[226:229], v[74:77]
	s_setprio 0
	s_setprio 1
	v_mfma_f32_16x16x32_bf16 v[118:121], v[160:163], v[176:179], v[118:121]
	v_mfma_f32_16x16x32_bf16 v[114:117], v[168:171], v[176:179], v[114:117]
	v_mfma_f32_16x16x32_bf16 v[102:105], v[160:163], v[184:187], v[102:105]
	v_mfma_f32_16x16x32_bf16 v[98:101], v[168:171], v[184:187], v[98:101]
	v_mfma_f32_16x16x32_bf16 v[86:89], v[160:163], v[214:217], v[86:89]
	v_mfma_f32_16x16x32_bf16 v[82:85], v[168:171], v[214:217], v[82:85]
	v_mfma_f32_16x16x32_bf16 v[70:73], v[160:163], v[222:225], v[70:73]
	v_mfma_f32_16x16x32_bf16 v[66:69], v[168:171], v[222:225], v[66:69]
	v_mfma_f32_16x16x32_bf16 v[118:121], v[164:167], v[180:183], v[118:121]
	v_mfma_f32_16x16x32_bf16 v[114:117], v[172:175], v[180:183], v[114:117]
	v_mfma_f32_16x16x32_bf16 v[102:105], v[164:167], v[188:191], v[102:105]
	v_mfma_f32_16x16x32_bf16 v[98:101], v[172:175], v[188:191], v[98:101]
	v_mfma_f32_16x16x32_bf16 v[86:89], v[164:167], v[218:221], v[86:89]
	v_mfma_f32_16x16x32_bf16 v[82:85], v[172:175], v[218:221], v[82:85]
	v_mfma_f32_16x16x32_bf16 v[70:73], v[164:167], v[226:229], v[70:73]
	v_mfma_f32_16x16x32_bf16 v[66:69], v[172:175], v[226:229], v[66:69]
	s_setprio 0
	s_barrier
; #define PG8_STAGE(bufoff, gbase, voff) do { _Pragma("unroll") for (int _i = 0; _i < 2; ++_i) \
;         __builtin_amdgcn_global_load_lds((const unsigned*)((const char*)(gbase) + (voff)[_i]), (LAS unsigned*)(lds + (bufoff) + ldsw + _i * 8192), 16, 0, 0); } while (0)
; #define PG8_LDA(dst, b, h) do { _Pragma("unroll") for (int m = 0; m < 4; ++m) _Pragma("unroll") for (int k = 0; k < 2; ++k) dst[m][k] = *(const LAS bf16x8*)(lds + PG8_SA(b, h) + aoff + m * 2048 + k * 1024); } while (0)
; #define PG8_MMA(ai, bj, At, Bt) do { __builtin_amdgcn_s_setprio(1); _Pragma("unroll") for (int m = 0; m < 4; ++m) _Pragma("unroll") for (int n = 0; n < 2; ++n) _Pragma("unroll") for (int k = 0; k < 2; ++k) \
;         acc[ai][bj][m][n] = __builtin_amdgcn_mfma_f32_16x16x32_bf16(Bt[n][k], At[m][k], acc[ai][bj][m][n], 0, 0, 0); __builtin_amdgcn_s_setprio(0); } while (0)
; #define PG8_WAIT_V(n) asm volatile("s_waitcnt vmcnt(" #n ")" ::: "memory")
; #define PG8_WAIT_L(n) asm volatile("s_waitcnt lgkmcnt(" #n ")" ::: "memory")
; #define PG8_BAR __builtin_amdgcn_s_barrier()
; #define PG8_SCHED __builtin_amdgcn_sched_barrier(0)
; template <class Epi, bool SP2, class Sched>
; __device__ __forceinline__ void gemm_phase(LAS unsigned char* lds, const Gemm g, const Sched& S, const Epi& E) {
;     ...
;         for (int t = 0; t < nt; t += 2) {
;     ...
;             PG8_LDA(At, 1, 1); PG8_STAGE(PG8_SB(1, 0), b3, voffB); PG8_STAGE(PG8_SB(1, 1), b3 + hstepB, voffB); PG8_STAGE(PG8_SA(1, 0), a3, voffA);
;             PG8_WAIT_V(8); PG8_WAIT_L(0); PG8_BAR; PG8_MMA(1, 0, At, B0); PG8_MMA(1, 1, At, B1); PG8_BAR; PG8_SCHED;
;     ...
;         if (wr == 0) PG8_BAR;
	s_add_i32 s10, s22, s69
	v_lshl_add_u64 v[192:193], v[192:193], 0, s[66:67]
	s_mov_b32 m0, s10
	ds_read_b128 v[176:179], v147 offset:49152
	ds_read_b128 v[180:183], v147 offset:50176
	ds_read_b128 v[184:187], v147 offset:51200
	ds_read_b128 v[188:191], v147 offset:52224
	ds_read_b128 v[214:217], v147 offset:53248
	ds_read_b128 v[218:221], v147 offset:54272
	ds_read_b128 v[222:225], v147 offset:55296
	ds_read_b128 v[226:229], v147 offset:56320
	global_load_lds_dwordx4 v[192:193], off
	s_add_i32 m0, s10, 0x2000
	s_add_u32 s6, s6, 0x40080
	v_lshl_add_u64 v[192:193], v[230:231], 0, s[66:67]
	s_addc_u32 s7, s7, 0
	s_add_i32 s10, s23, s69
	global_load_lds_dwordx4 v[192:193], off
	v_lshl_add_u64 v[192:193], s[6:7], 0, v[64:65]
	s_mov_b32 m0, s10
	s_nop 0
	global_load_lds_dwordx4 v[192:193], off
	v_lshl_add_u64 v[192:193], s[6:7], 0, v[130:131]
	s_add_i32 m0, s10, 0x2000
	s_nop 0
	global_load_lds_dwordx4 v[192:193], off
	v_lshl_add_u64 v[192:193], v[232:233], 0, s[66:67]
	s_mov_b32 m0, s17
	s_nop 0
	global_load_lds_dwordx4 v[192:193], off
	v_lshl_add_u64 v[192:193], v[234:235], 0, s[66:67]
	s_mov_b32 m0, s18
	s_nop 0
	global_load_lds_dwordx4 v[192:193], off
	s_waitcnt vmcnt(8) lgkmcnt(0)
	s_barrier
	s_setprio 1
	v_mfma_f32_16x16x32_bf16 v[60:63], v[140:143], v[176:179], v[60:63]
	v_mfma_f32_16x16x32_bf16 v[56:59], v[152:155], v[176:179], v[56:59]
	v_mfma_f32_16x16x32_bf16 v[44:47], v[140:143], v[184:187], v[44:47]
	v_mfma_f32_16x16x32_bf16 v[40:43], v[152:155], v[184:187], v[40:43]
	v_mfma_f32_16x16x32_bf16 v[28:31], v[140:143], v[214:217], v[28:31]
	v_mfma_f32_16x16x32_bf16 v[24:27], v[152:155], v[214:217], v[24:27]
	v_mfma_f32_16x16x32_bf16 v[12:15], v[140:143], v[222:225], v[12:15]
	v_mfma_f32_16x16x32_bf16 v[8:11], v[152:155], v[222:225], v[8:11]
	v_mfma_f32_16x16x32_bf16 v[60:63], v[148:151], v[180:183], v[60:63]
	v_mfma_f32_16x16x32_bf16 v[56:59], v[156:159], v[180:183], v[56:59]
	v_mfma_f32_16x16x32_bf16 v[44:47], v[148:151], v[188:191], v[44:47]
	v_mfma_f32_16x16x32_bf16 v[40:43], v[156:159], v[188:191], v[40:43]
	v_mfma_f32_16x16x32_bf16 v[28:31], v[148:151], v[218:221], v[28:31]
	v_mfma_f32_16x16x32_bf16 v[24:27], v[156:159], v[218:221], v[24:27]
	v_mfma_f32_16x16x32_bf16 v[12:15], v[148:151], v[226:229], v[12:15]
	v_mfma_f32_16x16x32_bf16 v[8:11], v[156:159], v[226:229], v[8:11]
	s_setprio 0
	s_setprio 1
	v_mfma_f32_16x16x32_bf16 v[52:55], v[160:163], v[176:179], v[52:55]
	v_mfma_f32_16x16x32_bf16 v[48:51], v[168:171], v[176:179], v[48:51]
	v_mfma_f32_16x16x32_bf16 v[36:39], v[160:163], v[184:187], v[36:39]
	v_mfma_f32_16x16x32_bf16 v[32:35], v[168:171], v[184:187], v[32:35]
	v_mfma_f32_16x16x32_bf16 v[20:23], v[160:163], v[214:217], v[20:23]
	v_mfma_f32_16x16x32_bf16 v[16:19], v[168:171], v[214:217], v[16:19]
	v_mfma_f32_16x16x32_bf16 v[4:7], v[160:163], v[222:225], v[4:7]
	v_mfma_f32_16x16x32_bf16 v[0:3], v[168:171], v[222:225], v[0:3]
	v_mfma_f32_16x16x32_bf16 v[52:55], v[164:167], v[180:183], v[52:55]
	v_mfma_f32_16x16x32_bf16 v[48:51], v[172:175], v[180:183], v[48:51]
	v_mfma_f32_16x16x32_bf16 v[36:39], v[164:167], v[188:191], v[36:39]
	v_mfma_f32_16x16x32_bf16 v[32:35], v[172:175], v[188:191], v[32:35]
	v_mfma_f32_16x16x32_bf16 v[20:23], v[164:167], v[218:221], v[20:23]
	v_mfma_f32_16x16x32_bf16 v[16:19], v[172:175], v[218:221], v[16:19]
	v_mfma_f32_16x16x32_bf16 v[4:7], v[164:167], v[226:229], v[4:7]
	v_mfma_f32_16x16x32_bf16 v[0:3], v[172:175], v[226:229], v[0:3]
	s_setprio 0
	s_barrier
	s_add_i32 s21, s21, 2
	s_add_u32 s76, s76, 0x100
	s_addc_u32 s20, s20, 0
	s_add_u32 s88, s88, 0x100
	s_addc_u32 s89, s89, 0
	s_cmp_gt_u32 s21, 13
	s_cbranch_scc0 .LBB0_783
	s_and_b64 vcc, exec, s[4:5]
	s_cbranch_vccz .LBB0_786
	s_barrier

; #define PG8_STAGE(bufoff, gbase, voff) do { _Pragma("unroll") for (int _i = 0; _i < 2; ++_i) \
;         __builtin_amdgcn_global_load_lds((const unsigned*)((const char*)(gbase) + (voff)[_i]), (LAS unsigned*)(lds + (bufoff) + ldsw + _i * 8192), 16, 0, 0); } while (0)
; #define PG8_LDA(dst, b, h) do { _Pragma("unroll") for (int m = 0; m < 4; ++m) _Pragma("unroll") for (int k = 0; k < 2; ++k) dst[m][k] = *(const LAS bf16x8*)(lds + PG8_SA(b, h) + aoff + m * 2048 + k * 1024); } while (0)
; #define PG8_LDB(dst, b, h) do { _Pragma("unroll") for (int n = 0; n < 2; ++n) _Pragma("unroll") for (int k = 0; k < 2; ++k) dst[n][k] = *(const LAS bf16x8*)(lds + PG8_SB(b, h) + boff + n * 2048 + k * 1024); } while (0)
; #define PG8_MMA(ai, bj, At, Bt) do { __builtin_amdgcn_s_setprio(1); _Pragma("unroll") for (int m = 0; m < 4; ++m) _Pragma("unroll") for (int n = 0; n < 2; ++n) _Pragma("unroll") for (int k = 0; k < 2; ++k) \
;         acc[ai][bj][m][n] = __builtin_amdgcn_mfma_f32_16x16x32_bf16(Bt[n][k], At[m][k], acc[ai][bj][m][n], 0, 0, 0); __builtin_amdgcn_s_setprio(0); } while (0)
; #define PG8_BAR __builtin_amdgcn_s_barrier()
; template <class Epi, bool SP2, class Sched>
; __device__ __forceinline__ void gemm_phase(LAS unsigned char* lds, const Gemm g, const Sched& S, const Epi& E) {
;     ...
;         const bool has_next = S.next(ui + 1, nxt);
;         const char* nA = has_next ? (const char*)g.A + (size_t)nxt.pm * tstep + nxt.ko : cA; const char* nB = has_next ? (const char*)g.Bt + (size_t)nxt.pn * tstepB + nxt.ko : cB;
;         for (int t = 0; t < nt; t += 2) {
;             const bool last = (t == nt - 2);
;             const char* a1 = cA + (size_t)(t + 1) * kstep;
;             const char* a2 = last ? nA : cA + (size_t)(t + 2) * kstep; const char* b2 = last ? nB : cB + (size_t)(t + 2) * kstep;
;             const char* a3 = a2 + kstep; const char* b3 = b2 + kstep;
;             if constexpr (Epi::MID) { if (t == (nt >> 1)) E.mid(acc, cur, wr, fr); }
;             if constexpr (SP2) {
;             PG8_LDB(B0, 0, 0); PG8_LDB(B1, 0, 1); PG8_SCHED; PG8_LDA(At, 0, 0); PG8_STAGE(PG8_SA(1, 1), a1 + hstep, voffA);
;             PG8_WAIT_V(8); PG8_WAIT_L(0); PG8_BAR; PG8_MMA(0, 0, At, B0); PG8_MMA(0, 1, At, B1); PG8_BAR; PG8_SCHED;
;             PG8_LDA(At, 0, 1); PG8_STAGE(PG8_SB(0, 0), b2, voffB); PG8_STAGE(PG8_SB(0, 1), b2 + hstepB, voffB); PG8_STAGE(PG8_SA(0, 0), a2, voffA);
.LBB0_807:
	s_add_u32 s6, s88, 0xfffc0080
	s_addc_u32 s7, s89, -1
	s_add_i32 s22, 0, 0x10000
	s_cmp_eq_u32 s21, 12
	s_cselect_b32 s11, s59, s7
	s_cselect_b32 s10, s75, s6
	v_add_u32_e32 v64, s22, v143
	s_cselect_b32 s7, s57, s20
	s_cselect_b32 s6, s76, s77
	s_add_i32 s24, 0, 0x14000
	ds_read_b128 v[138:141], v64
	ds_read_b128 v[146:149], v64 offset:1024
	ds_read_b128 v[150:153], v64 offset:2048
	ds_read_b128 v[154:157], v64 offset:3072
	v_add_u32_e32 v64, s24, v143
	ds_read_b128 v[158:161], v64
	ds_read_b128 v[162:165], v64 offset:1024
	ds_read_b128 v[166:169], v64 offset:2048
	ds_read_b128 v[170:173], v64 offset:3072
	v_lshl_add_u64 v[226:227], s[88:89], 0, v[136:137]
	s_add_i32 m0, s33, 0xc000
	ds_read_b128 v[174:177], v145
	ds_read_b128 v[178:181], v145 offset:1024
	ds_read_b128 v[182:185], v145 offset:2048
	ds_read_b128 v[186:189], v145 offset:3072
	ds_read_b128 v[190:193], v145 offset:4096
	ds_read_b128 v[214:217], v145 offset:5120
	ds_read_b128 v[218:221], v145 offset:6144
	ds_read_b128 v[222:225], v145 offset:7168
	global_load_lds_dwordx4 v[226:227], off
	v_lshl_add_u64 v[226:227], s[88:89], 0, v[134:135]
	s_add_i32 m0, s33, 0xe000
	s_nop 0
	global_load_lds_dwordx4 v[226:227], off
	s_waitcnt vmcnt(8) lgkmcnt(0)
	s_barrier
	s_setprio 1
	v_mfma_f32_16x16x32_bf16 v[126:129], v[138:141], v[174:177], v[126:129]
	v_mfma_f32_16x16x32_bf16 v[122:125], v[150:153], v[174:177], v[122:125]
	v_mfma_f32_16x16x32_bf16 v[114:117], v[138:141], v[182:185], v[114:117]
	v_mfma_f32_16x16x32_bf16 v[106:109], v[150:153], v[182:185], v[106:109]
	v_mfma_f32_16x16x32_bf16 v[98:101], v[138:141], v[190:193], v[98:101]
	v_mfma_f32_16x16x32_bf16 v[90:93], v[150:153], v[190:193], v[90:93]
	v_mfma_f32_16x16x32_bf16 v[82:85], v[138:141], v[218:221], v[82:85]
	v_mfma_f32_16x16x32_bf16 v[74:77], v[150:153], v[218:221], v[74:77]
	v_mfma_f32_16x16x32_bf16 v[126:129], v[146:149], v[178:181], v[126:129]
	v_mfma_f32_16x16x32_bf16 v[122:125], v[154:157], v[178:181], v[122:125]
	v_mfma_f32_16x16x32_bf16 v[114:117], v[146:149], v[186:189], v[114:117]
	v_mfma_f32_16x16x32_bf16 v[106:109], v[154:157], v[186:189], v[106:109]
	v_mfma_f32_16x16x32_bf16 v[98:101], v[146:149], v[214:217], v[98:101]
	v_mfma_f32_16x16x32_bf16 v[90:93], v[154:157], v[214:217], v[90:93]
	v_mfma_f32_16x16x32_bf16 v[82:85], v[146:149], v[222:225], v[82:85]
	v_mfma_f32_16x16x32_bf16 v[74:77], v[154:157], v[222:225], v[74:77]
	s_setprio 0
	s_setprio 1
	v_mfma_f32_16x16x32_bf16 v[118:121], v[158:161], v[174:177], v[118:121]
	v_mfma_f32_16x16x32_bf16 v[110:113], v[166:169], v[174:177], v[110:113]
	v_mfma_f32_16x16x32_bf16 v[102:105], v[158:161], v[182:185], v[102:105]
	v_mfma_f32_16x16x32_bf16 v[94:97], v[166:169], v[182:185], v[94:97]
	v_mfma_f32_16x16x32_bf16 v[86:89], v[158:161], v[190:193], v[86:89]
	v_mfma_f32_16x16x32_bf16 v[78:81], v[166:169], v[190:193], v[78:81]
	v_mfma_f32_16x16x32_bf16 v[70:73], v[158:161], v[218:221], v[70:73]
	v_mfma_f32_16x16x32_bf16 v[66:69], v[166:169], v[218:221], v[66:69]
	v_mfma_f32_16x16x32_bf16 v[118:121], v[162:165], v[178:181], v[118:121]
	v_mfma_f32_16x16x32_bf16 v[110:113], v[170:173], v[178:181], v[110:113]
	v_mfma_f32_16x16x32_bf16 v[102:105], v[162:165], v[186:189], v[102:105]
	v_mfma_f32_16x16x32_bf16 v[94:97], v[170:173], v[186:189], v[94:97]
	v_mfma_f32_16x16x32_bf16 v[86:89], v[162:165], v[214:217], v[86:89]
	v_mfma_f32_16x16x32_bf16 v[78:81], v[170:173], v[214:217], v[78:81]
	v_mfma_f32_16x16x32_bf16 v[70:73], v[162:165], v[222:225], v[70:73]
	v_mfma_f32_16x16x32_bf16 v[66:69], v[170:173], v[222:225], v[66:69]
	s_setprio 0
	s_barrier
	s_add_i32 s22, s22, s19
	v_lshl_add_u64 v[226:227], s[6:7], 0, v[130:131]
	s_mov_b32 m0, s22
	ds_read_b128 v[174:177], v145 offset:16384
	ds_read_b128 v[178:181], v145 offset:17408
	ds_read_b128 v[182:185], v145 offset:18432
	ds_read_b128 v[186:189], v145 offset:19456
	ds_read_b128 v[190:193], v145 offset:20480
	ds_read_b128 v[214:217], v145 offset:21504
	ds_read_b128 v[218:221], v145 offset:22528
	ds_read_b128 v[222:225], v145 offset:23552
	global_load_lds_dwordx4 v[226:227], off
	s_add_i32 m0, s22, 0x2000
	s_add_u32 s22, s6, 0x40000
	v_lshl_add_u64 v[228:229], s[6:7], 0, v[132:133]
	s_addc_u32 s23, s7, 0
	s_add_i32 s24, s24, s19
	global_load_lds_dwordx4 v[228:229], off
	v_lshl_add_u64 v[230:231], s[22:23], 0, v[130:131]
	s_mov_b32 m0, s24
	v_lshl_add_u64 v[232:233], s[10:11], 0, v[132:133]
	global_load_lds_dwordx4 v[230:231], off
	v_lshl_add_u64 v[230:231], s[22:23], 0, v[132:133]
	s_add_i32 m0, s24, 0x2000
	s_nop 0
	global_load_lds_dwordx4 v[230:231], off
	v_lshl_add_u64 v[230:231], s[10:11], 0, v[130:131]
	s_mov_b32 m0, s33
	s_nop 0
	global_load_lds_dwordx4 v[230:231], off
	s_mov_b32 m0, s62
	s_nop 0
	global_load_lds_dwordx4 v[232:233], off
	s_waitcnt vmcnt(8) lgkmcnt(0)
	s_barrier
; #define PG8_STAGE(bufoff, gbase, voff) do { _Pragma("unroll") for (int _i = 0; _i < 2; ++_i) \
;         __builtin_amdgcn_global_load_lds((const unsigned*)((const char*)(gbase) + (voff)[_i]), (LAS unsigned*)(lds + (bufoff) + ldsw + _i * 8192), 16, 0, 0); } while (0)
; #define PG8_LDA(dst, b, h) do { _Pragma("unroll") for (int m = 0; m < 4; ++m) _Pragma("unroll") for (int k = 0; k < 2; ++k) dst[m][k] = *(const LAS bf16x8*)(lds + PG8_SA(b, h) + aoff + m * 2048 + k * 1024); } while (0)
; #define PG8_LDB(dst, b, h) do { _Pragma("unroll") for (int n = 0; n < 2; ++n) _Pragma("unroll") for (int k = 0; k < 2; ++k) dst[n][k] = *(const LAS bf16x8*)(lds + PG8_SB(b, h) + boff + n * 2048 + k * 1024); } while (0)
; #define PG8_MMA(ai, bj, At, Bt) do { __builtin_amdgcn_s_setprio(1); _Pragma("unroll") for (int m = 0; m < 4; ++m) _Pragma("unroll") for (int n = 0; n < 2; ++n) _Pragma("unroll") for (int k = 0; k < 2; ++k) \
;         acc[ai][bj][m][n] = __builtin_amdgcn_mfma_f32_16x16x32_bf16(Bt[n][k], At[m][k], acc[ai][bj][m][n], 0, 0, 0); __builtin_amdgcn_s_setprio(0); } while (0)
; #define PG8_WAIT_V(n) asm volatile("s_waitcnt vmcnt(" #n ")" ::: "memory")
; #define PG8_WAIT_L(n) asm volatile("s_waitcnt lgkmcnt(" #n ")" ::: "memory")
; #define PG8_BAR __builtin_amdgcn_s_barrier()
; #define PG8_SCHED __builtin_amdgcn_sched_barrier(0)
; template <class Epi, bool SP2, class Sched>
; __device__ __forceinline__ void gemm_phase(LAS unsigned char* lds, const Gemm g, const Sched& S, const Epi& E) {
;     ...
;             PG8_WAIT_V(8); PG8_WAIT_L(0); PG8_BAR; PG8_MMA(1, 0, At, B0); PG8_MMA(1, 1, At, B1); PG8_BAR; PG8_SCHED;
;             PG8_LDB(B0, 1, 0); PG8_LDB(B1, 1, 1); PG8_SCHED; PG8_LDA(At, 1, 0); PG8_STAGE(PG8_SA(0, 1), a2 + hstep, voffA);
;             PG8_WAIT_V(8); PG8_WAIT_L(0); PG8_BAR; PG8_MMA(0, 0, At, B0); PG8_MMA(0, 1, At, B1); PG8_BAR; PG8_SCHED;
	s_setprio 1
	v_mfma_f32_16x16x32_bf16 v[60:63], v[138:141], v[174:177], v[60:63]
	v_mfma_f32_16x16x32_bf16 v[56:59], v[150:153], v[174:177], v[56:59]
	v_mfma_f32_16x16x32_bf16 v[48:51], v[138:141], v[182:185], v[48:51]
	v_mfma_f32_16x16x32_bf16 v[40:43], v[150:153], v[182:185], v[40:43]
	v_mfma_f32_16x16x32_bf16 v[32:35], v[138:141], v[190:193], v[32:35]
	v_mfma_f32_16x16x32_bf16 v[24:27], v[150:153], v[190:193], v[24:27]
	v_mfma_f32_16x16x32_bf16 v[12:15], v[138:141], v[218:221], v[12:15]
	v_mfma_f32_16x16x32_bf16 v[8:11], v[150:153], v[218:221], v[8:11]
	v_mfma_f32_16x16x32_bf16 v[60:63], v[146:149], v[178:181], v[60:63]
	v_mfma_f32_16x16x32_bf16 v[56:59], v[154:157], v[178:181], v[56:59]
	v_mfma_f32_16x16x32_bf16 v[48:51], v[146:149], v[186:189], v[48:51]
	v_mfma_f32_16x16x32_bf16 v[40:43], v[154:157], v[186:189], v[40:43]
	v_mfma_f32_16x16x32_bf16 v[32:35], v[146:149], v[214:217], v[32:35]
	v_mfma_f32_16x16x32_bf16 v[24:27], v[154:157], v[214:217], v[24:27]
	v_mfma_f32_16x16x32_bf16 v[12:15], v[146:149], v[222:225], v[12:15]
	v_mfma_f32_16x16x32_bf16 v[8:11], v[154:157], v[222:225], v[8:11]
	s_setprio 0
	s_setprio 1
	v_mfma_f32_16x16x32_bf16 v[52:55], v[158:161], v[174:177], v[52:55]
	v_mfma_f32_16x16x32_bf16 v[44:47], v[166:169], v[174:177], v[44:47]
	v_mfma_f32_16x16x32_bf16 v[36:39], v[158:161], v[182:185], v[36:39]
	v_mfma_f32_16x16x32_bf16 v[28:31], v[166:169], v[182:185], v[28:31]
	v_mfma_f32_16x16x32_bf16 v[20:23], v[158:161], v[190:193], v[20:23]
	v_mfma_f32_16x16x32_bf16 v[16:19], v[166:169], v[190:193], v[16:19]
	v_mfma_f32_16x16x32_bf16 v[4:7], v[158:161], v[218:221], v[4:7]
	v_mfma_f32_16x16x32_bf16 v[0:3], v[166:169], v[218:221], v[0:3]
	v_mfma_f32_16x16x32_bf16 v[52:55], v[162:165], v[178:181], v[52:55]
	v_mfma_f32_16x16x32_bf16 v[44:47], v[170:173], v[178:181], v[44:47]
	v_mfma_f32_16x16x32_bf16 v[36:39], v[162:165], v[186:189], v[36:39]
	v_mfma_f32_16x16x32_bf16 v[28:31], v[170:173], v[186:189], v[28:31]
	v_mfma_f32_16x16x32_bf16 v[20:23], v[162:165], v[214:217], v[20:23]
	v_mfma_f32_16x16x32_bf16 v[16:19], v[170:173], v[214:217], v[16:19]
	v_mfma_f32_16x16x32_bf16 v[4:7], v[162:165], v[222:225], v[4:7]
	v_mfma_f32_16x16x32_bf16 v[0:3], v[170:173], v[222:225], v[0:3]
	s_setprio 0
	s_barrier
	s_add_i32 s22, 0, 0x18000
	v_add_u32_e32 v64, s22, v143
	s_add_i32 s23, 0, 0x1c000
	ds_read_b128 v[138:141], v64
	ds_read_b128 v[146:149], v64 offset:1024
	ds_read_b128 v[150:153], v64 offset:2048
	ds_read_b128 v[154:157], v64 offset:3072
	v_add_u32_e32 v64, s23, v143
	ds_read_b128 v[158:161], v64
	ds_read_b128 v[162:165], v64 offset:1024
	ds_read_b128 v[166:169], v64 offset:2048
	ds_read_b128 v[170:173], v64 offset:3072
	s_add_u32 s10, s10, 0x40000
	s_addc_u32 s11, s11, 0
	s_mov_b32 m0, s64
	v_lshl_add_u64 v[234:235], s[10:11], 0, v[130:131]
	ds_read_b128 v[174:177], v145 offset:32768
	ds_read_b128 v[178:181], v145 offset:33792
	ds_read_b128 v[182:185], v145 offset:34816
	ds_read_b128 v[186:189], v145 offset:35840
	ds_read_b128 v[190:193], v145 offset:36864
	ds_read_b128 v[214:217], v145 offset:37888
	ds_read_b128 v[218:221], v145 offset:38912
	ds_read_b128 v[222:225], v145 offset:39936
	global_load_lds_dwordx4 v[234:235], off
	v_lshl_add_u64 v[234:235], s[10:11], 0, v[132:133]
	s_mov_b32 m0, s65
	s_nop 0
	global_load_lds_dwordx4 v[234:235], off
	s_waitcnt vmcnt(8) lgkmcnt(0)
	s_barrier
	s_setprio 1
	v_mfma_f32_16x16x32_bf16 v[126:129], v[138:141], v[174:177], v[126:129]
	v_mfma_f32_16x16x32_bf16 v[122:125], v[150:153], v[174:177], v[122:125]
	v_mfma_f32_16x16x32_bf16 v[114:117], v[138:141], v[182:185], v[114:117]
	v_mfma_f32_16x16x32_bf16 v[106:109], v[150:153], v[182:185], v[106:109]
	v_mfma_f32_16x16x32_bf16 v[98:101], v[138:141], v[190:193], v[98:101]
	v_mfma_f32_16x16x32_bf16 v[90:93], v[150:153], v[190:193], v[90:93]
	v_mfma_f32_16x16x32_bf16 v[82:85], v[138:141], v[218:221], v[82:85]
	v_mfma_f32_16x16x32_bf16 v[74:77], v[150:153], v[218:221], v[74:77]
	v_mfma_f32_16x16x32_bf16 v[126:129], v[146:149], v[178:181], v[126:129]
	v_mfma_f32_16x16x32_bf16 v[122:125], v[154:157], v[178:181], v[122:125]
	v_mfma_f32_16x16x32_bf16 v[114:117], v[146:149], v[186:189], v[114:117]
	v_mfma_f32_16x16x32_bf16 v[106:109], v[154:157], v[186:189], v[106:109]
	v_mfma_f32_16x16x32_bf16 v[98:101], v[146:149], v[214:217], v[98:101]
	v_mfma_f32_16x16x32_bf16 v[90:93], v[154:157], v[214:217], v[90:93]
	v_mfma_f32_16x16x32_bf16 v[82:85], v[146:149], v[222:225], v[82:85]
	v_mfma_f32_16x16x32_bf16 v[74:77], v[154:157], v[222:225], v[74:77]
	s_setprio 0
	s_setprio 1
	v_mfma_f32_16x16x32_bf16 v[118:121], v[158:161], v[174:177], v[118:121]
	v_mfma_f32_16x16x32_bf16 v[110:113], v[166:169], v[174:177], v[110:113]
	v_mfma_f32_16x16x32_bf16 v[102:105], v[158:161], v[182:185], v[102:105]
	v_mfma_f32_16x16x32_bf16 v[94:97], v[166:169], v[182:185], v[94:97]
	v_mfma_f32_16x16x32_bf16 v[86:89], v[158:161], v[190:193], v[86:89]
	v_mfma_f32_16x16x32_bf16 v[78:81], v[166:169], v[190:193], v[78:81]
	v_mfma_f32_16x16x32_bf16 v[70:73], v[158:161], v[218:221], v[70:73]
	v_mfma_f32_16x16x32_bf16 v[66:69], v[166:169], v[218:221], v[66:69]
	v_mfma_f32_16x16x32_bf16 v[118:121], v[162:165], v[178:181], v[118:121]
	v_mfma_f32_16x16x32_bf16 v[110:113], v[170:173], v[178:181], v[110:113]
	v_mfma_f32_16x16x32_bf16 v[102:105], v[162:165], v[186:189], v[102:105]
	v_mfma_f32_16x16x32_bf16 v[94:97], v[170:173], v[186:189], v[94:97]
	v_mfma_f32_16x16x32_bf16 v[86:89], v[162:165], v[214:217], v[86:89]
	v_mfma_f32_16x16x32_bf16 v[78:81], v[170:173], v[214:217], v[78:81]
	v_mfma_f32_16x16x32_bf16 v[70:73], v[162:165], v[222:225], v[70:73]
	v_mfma_f32_16x16x32_bf16 v[66:69], v[170:173], v[222:225], v[66:69]
	s_setprio 0
	s_barrier
; #define PG8_STAGE(bufoff, gbase, voff) do { _Pragma("unroll") for (int _i = 0; _i < 2; ++_i) \
;         __builtin_amdgcn_global_load_lds((const unsigned*)((const char*)(gbase) + (voff)[_i]), (LAS unsigned*)(lds + (bufoff) + ldsw + _i * 8192), 16, 0, 0); } while (0)
; #define PG8_LDA(dst, b, h) do { _Pragma("unroll") for (int m = 0; m < 4; ++m) _Pragma("unroll") for (int k = 0; k < 2; ++k) dst[m][k] = *(const LAS bf16x8*)(lds + PG8_SA(b, h) + aoff + m * 2048 + k * 1024); } while (0)
; #define PG8_MMA(ai, bj, At, Bt) do { __builtin_amdgcn_s_setprio(1); _Pragma("unroll") for (int m = 0; m < 4; ++m) _Pragma("unroll") for (int n = 0; n < 2; ++n) _Pragma("unroll") for (int k = 0; k < 2; ++k) \
;         acc[ai][bj][m][n] = __builtin_amdgcn_mfma_f32_16x16x32_bf16(Bt[n][k], At[m][k], acc[ai][bj][m][n], 0, 0, 0); __builtin_amdgcn_s_setprio(0); } while (0)
; #define PG8_WAIT_V(n) asm volatile("s_waitcnt vmcnt(" #n ")" ::: "memory")
; #define PG8_WAIT_L(n) asm volatile("s_waitcnt lgkmcnt(" #n ")" ::: "memory")
; #define PG8_BAR __builtin_amdgcn_s_barrier()
; #define PG8_SCHED __builtin_amdgcn_sched_barrier(0)
; template <class Epi, bool SP2, class Sched>
; __device__ __forceinline__ void gemm_phase(LAS unsigned char* lds, const Gemm g, const Sched& S, const Epi& E) {
;     ...
;         for (int t = 0; t < nt; t += 2) {
;     ...
;             PG8_LDA(At, 1, 1); PG8_STAGE(PG8_SB(1, 0), b3, voffB); PG8_STAGE(PG8_SB(1, 1), b3 + hstepB, voffB); PG8_STAGE(PG8_SA(1, 0), a3, voffA);
;             PG8_WAIT_V(8); PG8_WAIT_L(0); PG8_BAR; PG8_MMA(1, 0, At, B0); PG8_MMA(1, 1, At, B1); PG8_BAR; PG8_SCHED;
;     ...
;         if (wr == 0) PG8_BAR;
	s_add_i32 s10, s22, s19
	v_lshl_add_u64 v[226:227], v[226:227], 0, s[66:67]
	s_mov_b32 m0, s10
	ds_read_b128 v[174:177], v145 offset:49152
	ds_read_b128 v[178:181], v145 offset:50176
	ds_read_b128 v[182:185], v145 offset:51200
	ds_read_b128 v[186:189], v145 offset:52224
	ds_read_b128 v[190:193], v145 offset:53248
	ds_read_b128 v[214:217], v145 offset:54272
	ds_read_b128 v[218:221], v145 offset:55296
	ds_read_b128 v[222:225], v145 offset:56320
	global_load_lds_dwordx4 v[226:227], off
	s_add_i32 m0, s10, 0x2000
	s_add_u32 s6, s6, 0x40080
	v_lshl_add_u64 v[226:227], v[228:229], 0, s[66:67]
	s_addc_u32 s7, s7, 0
	s_add_i32 s10, s23, s19
	global_load_lds_dwordx4 v[226:227], off
	v_lshl_add_u64 v[226:227], s[6:7], 0, v[130:131]
	s_mov_b32 m0, s10
	s_nop 0
	global_load_lds_dwordx4 v[226:227], off
	v_lshl_add_u64 v[226:227], s[6:7], 0, v[132:133]
	s_add_i32 m0, s10, 0x2000
	s_nop 0
	global_load_lds_dwordx4 v[226:227], off
	v_lshl_add_u64 v[226:227], v[230:231], 0, s[66:67]
	s_mov_b32 m0, s68
	s_nop 0
	global_load_lds_dwordx4 v[226:227], off
	v_lshl_add_u64 v[226:227], v[232:233], 0, s[66:67]
	s_mov_b32 m0, s69
	s_nop 0
	global_load_lds_dwordx4 v[226:227], off
	s_waitcnt vmcnt(8) lgkmcnt(0)
	s_barrier
	s_setprio 1
	v_mfma_f32_16x16x32_bf16 v[60:63], v[138:141], v[174:177], v[60:63]
	v_mfma_f32_16x16x32_bf16 v[56:59], v[150:153], v[174:177], v[56:59]
	v_mfma_f32_16x16x32_bf16 v[48:51], v[138:141], v[182:185], v[48:51]
	v_mfma_f32_16x16x32_bf16 v[40:43], v[150:153], v[182:185], v[40:43]
	v_mfma_f32_16x16x32_bf16 v[32:35], v[138:141], v[190:193], v[32:35]
	v_mfma_f32_16x16x32_bf16 v[24:27], v[150:153], v[190:193], v[24:27]
	v_mfma_f32_16x16x32_bf16 v[12:15], v[138:141], v[218:221], v[12:15]
	v_mfma_f32_16x16x32_bf16 v[8:11], v[150:153], v[218:221], v[8:11]
	v_mfma_f32_16x16x32_bf16 v[60:63], v[146:149], v[178:181], v[60:63]
	v_mfma_f32_16x16x32_bf16 v[56:59], v[154:157], v[178:181], v[56:59]
	v_mfma_f32_16x16x32_bf16 v[48:51], v[146:149], v[186:189], v[48:51]
	v_mfma_f32_16x16x32_bf16 v[40:43], v[154:157], v[186:189], v[40:43]
	v_mfma_f32_16x16x32_bf16 v[32:35], v[146:149], v[214:217], v[32:35]
	v_mfma_f32_16x16x32_bf16 v[24:27], v[154:157], v[214:217], v[24:27]
	v_mfma_f32_16x16x32_bf16 v[12:15], v[146:149], v[222:225], v[12:15]
	v_mfma_f32_16x16x32_bf16 v[8:11], v[154:157], v[222:225], v[8:11]
	s_setprio 0
	s_setprio 1
	v_mfma_f32_16x16x32_bf16 v[52:55], v[158:161], v[174:177], v[52:55]
	v_mfma_f32_16x16x32_bf16 v[44:47], v[166:169], v[174:177], v[44:47]
	v_mfma_f32_16x16x32_bf16 v[36:39], v[158:161], v[182:185], v[36:39]
	v_mfma_f32_16x16x32_bf16 v[28:31], v[166:169], v[182:185], v[28:31]
	v_mfma_f32_16x16x32_bf16 v[20:23], v[158:161], v[190:193], v[20:23]
	v_mfma_f32_16x16x32_bf16 v[16:19], v[166:169], v[190:193], v[16:19]
	v_mfma_f32_16x16x32_bf16 v[4:7], v[158:161], v[218:221], v[4:7]
	v_mfma_f32_16x16x32_bf16 v[0:3], v[166:169], v[218:221], v[0:3]
	v_mfma_f32_16x16x32_bf16 v[52:55], v[162:165], v[178:181], v[52:55]
	v_mfma_f32_16x16x32_bf16 v[44:47], v[170:173], v[178:181], v[44:47]
	v_mfma_f32_16x16x32_bf16 v[36:39], v[162:165], v[186:189], v[36:39]
	v_mfma_f32_16x16x32_bf16 v[28:31], v[170:173], v[186:189], v[28:31]
	v_mfma_f32_16x16x32_bf16 v[20:23], v[162:165], v[214:217], v[20:23]
	v_mfma_f32_16x16x32_bf16 v[16:19], v[170:173], v[214:217], v[16:19]
	v_mfma_f32_16x16x32_bf16 v[4:7], v[162:165], v[222:225], v[4:7]
	v_mfma_f32_16x16x32_bf16 v[0:3], v[170:173], v[222:225], v[0:3]
	s_setprio 0
	s_barrier
	s_add_i32 s21, s21, 2
	s_add_u32 s77, s77, 0x100
	s_addc_u32 s20, s20, 0
	s_add_u32 s88, s88, 0x100
	s_addc_u32 s89, s89, 0
	s_cmp_gt_u32 s21, 13
	s_cbranch_scc0 .LBB0_807
	s_and_b64 vcc, exec, s[16:17]
	s_cbranch_vccz .LBB0_810
	s_barrier

; #define PG8_STAGE(bufoff, gbase, voff) do { _Pragma("unroll") for (int _i = 0; _i < 2; ++_i) \
;         __builtin_amdgcn_global_load_lds((const unsigned*)((const char*)(gbase) + (voff)[_i]), (LAS unsigned*)(lds + (bufoff) + ldsw + _i * 8192), 16, 0, 0); } while (0)
; #define PG8_LDA(dst, b, h) do { _Pragma("unroll") for (int m = 0; m < 4; ++m) _Pragma("unroll") for (int k = 0; k < 2; ++k) dst[m][k] = *(const LAS bf16x8*)(lds + PG8_SA(b, h) + aoff + m * 2048 + k * 1024); } while (0)
; #define PG8_LDB(dst, b, h) do { _Pragma("unroll") for (int n = 0; n < 2; ++n) _Pragma("unroll") for (int k = 0; k < 2; ++k) dst[n][k] = *(const LAS bf16x8*)(lds + PG8_SB(b, h) + boff + n * 2048 + k * 1024); } while (0)
; #define PG8_MMA(ai, bj, At, Bt) do { __builtin_amdgcn_s_setprio(1); _Pragma("unroll") for (int m = 0; m < 4; ++m) _Pragma("unroll") for (int n = 0; n < 2; ++n) _Pragma("unroll") for (int k = 0; k < 2; ++k) \
;         acc[ai][bj][m][n] = __builtin_amdgcn_mfma_f32_16x16x32_bf16(Bt[n][k], At[m][k], acc[ai][bj][m][n], 0, 0, 0); __builtin_amdgcn_s_setprio(0); } while (0)
; #define PG8_BAR __builtin_amdgcn_s_barrier()
; template <class Epi, bool SP2, class Sched>
; __device__ __forceinline__ void gemm_phase(LAS unsigned char* lds, const Gemm g, const Sched& S, const Epi& E) {
;     ...
;         const bool has_next = S.next(ui + 1, nxt);
;         const char* nA = has_next ? (const char*)g.A + (size_t)nxt.pm * tstep + nxt.ko : cA; const char* nB = has_next ? (const char*)g.Bt + (size_t)nxt.pn * tstepB + nxt.ko : cB;
;         for (int t = 0; t < nt; t += 2) {
;             const bool last = (t == nt - 2);
;             const char* a1 = cA + (size_t)(t + 1) * kstep;
;             const char* a2 = last ? nA : cA + (size_t)(t + 2) * kstep; const char* b2 = last ? nB : cB + (size_t)(t + 2) * kstep;
;             const char* a3 = a2 + kstep; const char* b3 = b2 + kstep;
;             if constexpr (Epi::MID) { if (t == (nt >> 1)) E.mid(acc, cur, wr, fr); }
;             if constexpr (SP2) {
;             PG8_LDB(B0, 0, 0); PG8_LDB(B1, 0, 1); PG8_SCHED; PG8_LDA(At, 0, 0); PG8_STAGE(PG8_SA(1, 1), a1 + hstep, voffA);
;             PG8_WAIT_V(8); PG8_WAIT_L(0); PG8_BAR; PG8_MMA(0, 0, At, B0); PG8_MMA(0, 1, At, B1); PG8_BAR; PG8_SCHED;
;             PG8_LDA(At, 0, 1); PG8_STAGE(PG8_SB(0, 0), b2, voffB); PG8_STAGE(PG8_SB(0, 1), b2 + hstepB, voffB); PG8_STAGE(PG8_SA(0, 0), a2, voffA);
.LBB0_955:
	s_add_u32 s6, s92, 0xfffc0080
	s_addc_u32 s7, s93, -1
	s_add_i32 s22, 0, 0x10000
	s_cmp_eq_u32 s21, 12
	s_cselect_b32 s11, s73, s7
	s_cselect_b32 s10, s74, s6
	v_add_u32_e32 v144, s22, v147
	s_cselect_b32 s7, s5, s20
	s_cselect_b32 s6, s75, s76
	s_add_i32 s24, 0, 0x14000
	ds_read_b128 v[140:143], v144
	ds_read_b128 v[150:153], v144 offset:1024
	ds_read_b128 v[154:157], v144 offset:2048
	ds_read_b128 v[158:161], v144 offset:3072
	v_add_u32_e32 v144, s24, v147
	ds_read_b128 v[162:165], v144
	ds_read_b128 v[166:169], v144 offset:1024
	ds_read_b128 v[170:173], v144 offset:2048
	ds_read_b128 v[174:177], v144 offset:3072
	v_lshl_add_u64 v[144:145], s[92:93], 0, v[138:139]
	s_add_i32 m0, s13, 0xc000
	ds_read_b128 v[178:181], v149
	ds_read_b128 v[182:185], v149 offset:1024
	ds_read_b128 v[186:189], v149 offset:2048
	ds_read_b128 v[190:193], v149 offset:3072
	ds_read_b128 v[214:217], v149 offset:4096
	ds_read_b128 v[218:221], v149 offset:5120
	ds_read_b128 v[222:225], v149 offset:6144
	ds_read_b128 v[226:229], v149 offset:7168
	global_load_lds_dwordx4 v[144:145], off
	v_lshl_add_u64 v[144:145], s[92:93], 0, v[136:137]
	s_add_i32 m0, s13, 0xe000
	s_nop 0
	global_load_lds_dwordx4 v[144:145], off
	s_waitcnt vmcnt(8) lgkmcnt(0)
	s_barrier
	s_setprio 1
	v_mfma_f32_16x16x32_bf16 v[126:129], v[140:143], v[178:181], v[126:129]
	v_mfma_f32_16x16x32_bf16 v[122:125], v[154:157], v[178:181], v[122:125]
	v_mfma_f32_16x16x32_bf16 v[110:113], v[140:143], v[186:189], v[110:113]
	v_mfma_f32_16x16x32_bf16 v[106:109], v[154:157], v[186:189], v[106:109]
	v_mfma_f32_16x16x32_bf16 v[94:97], v[140:143], v[214:217], v[94:97]
	v_mfma_f32_16x16x32_bf16 v[90:93], v[154:157], v[214:217], v[90:93]
	v_mfma_f32_16x16x32_bf16 v[78:81], v[140:143], v[222:225], v[78:81]
	v_mfma_f32_16x16x32_bf16 v[74:77], v[154:157], v[222:225], v[74:77]
	v_mfma_f32_16x16x32_bf16 v[126:129], v[150:153], v[182:185], v[126:129]
	v_mfma_f32_16x16x32_bf16 v[122:125], v[158:161], v[182:185], v[122:125]
	v_mfma_f32_16x16x32_bf16 v[110:113], v[150:153], v[190:193], v[110:113]
	v_mfma_f32_16x16x32_bf16 v[106:109], v[158:161], v[190:193], v[106:109]
	v_mfma_f32_16x16x32_bf16 v[94:97], v[150:153], v[218:221], v[94:97]
	v_mfma_f32_16x16x32_bf16 v[90:93], v[158:161], v[218:221], v[90:93]
	v_mfma_f32_16x16x32_bf16 v[78:81], v[150:153], v[226:229], v[78:81]
	v_mfma_f32_16x16x32_bf16 v[74:77], v[158:161], v[226:229], v[74:77]
	s_setprio 0
	s_setprio 1
	v_mfma_f32_16x16x32_bf16 v[118:121], v[162:165], v[178:181], v[118:121]
	v_mfma_f32_16x16x32_bf16 v[114:117], v[170:173], v[178:181], v[114:117]
	v_mfma_f32_16x16x32_bf16 v[102:105], v[162:165], v[186:189], v[102:105]
	v_mfma_f32_16x16x32_bf16 v[98:101], v[170:173], v[186:189], v[98:101]
	v_mfma_f32_16x16x32_bf16 v[86:89], v[162:165], v[214:217], v[86:89]
	v_mfma_f32_16x16x32_bf16 v[82:85], v[170:173], v[214:217], v[82:85]
	v_mfma_f32_16x16x32_bf16 v[70:73], v[162:165], v[222:225], v[70:73]
	v_mfma_f32_16x16x32_bf16 v[66:69], v[170:173], v[222:225], v[66:69]
	v_mfma_f32_16x16x32_bf16 v[118:121], v[166:169], v[182:185], v[118:121]
	v_mfma_f32_16x16x32_bf16 v[114:117], v[174:177], v[182:185], v[114:117]
	v_mfma_f32_16x16x32_bf16 v[102:105], v[166:169], v[190:193], v[102:105]
	v_mfma_f32_16x16x32_bf16 v[98:101], v[174:177], v[190:193], v[98:101]
	v_mfma_f32_16x16x32_bf16 v[86:89], v[166:169], v[218:221], v[86:89]
	v_mfma_f32_16x16x32_bf16 v[82:85], v[174:177], v[218:221], v[82:85]
	v_mfma_f32_16x16x32_bf16 v[70:73], v[166:169], v[226:229], v[70:73]
	v_mfma_f32_16x16x32_bf16 v[66:69], v[174:177], v[226:229], v[66:69]
	s_setprio 0
	s_barrier
	s_add_i32 s22, s22, s12
	v_lshl_add_u64 v[144:145], s[6:7], 0, v[64:65]
	s_mov_b32 m0, s22
	ds_read_b128 v[178:181], v149 offset:16384
	ds_read_b128 v[182:185], v149 offset:17408
	ds_read_b128 v[186:189], v149 offset:18432
	ds_read_b128 v[190:193], v149 offset:19456
	ds_read_b128 v[214:217], v149 offset:20480
	ds_read_b128 v[218:221], v149 offset:21504
	ds_read_b128 v[222:225], v149 offset:22528
	ds_read_b128 v[226:229], v149 offset:23552
	global_load_lds_dwordx4 v[144:145], off
	s_add_i32 m0, s22, 0x2000
	s_add_u32 s22, s6, 0x40000
	v_lshl_add_u64 v[230:231], s[6:7], 0, v[134:135]
	s_addc_u32 s23, s7, 0
	s_add_i32 s24, s24, s12
	global_load_lds_dwordx4 v[230:231], off
	v_lshl_add_u64 v[232:233], s[22:23], 0, v[64:65]
	s_mov_b32 m0, s24
	v_lshl_add_u64 v[234:235], s[10:11], 0, v[132:133]
	global_load_lds_dwordx4 v[232:233], off
	v_lshl_add_u64 v[232:233], s[22:23], 0, v[134:135]
	s_add_i32 m0, s24, 0x2000
	s_nop 0
	global_load_lds_dwordx4 v[232:233], off
	v_lshl_add_u64 v[232:233], s[10:11], 0, v[130:131]
	s_mov_b32 m0, s13
	s_nop 0
	global_load_lds_dwordx4 v[232:233], off
	s_mov_b32 m0, s14
	s_nop 0
	global_load_lds_dwordx4 v[234:235], off
	s_waitcnt vmcnt(8) lgkmcnt(0)
	s_barrier
; #define PG8_STAGE(bufoff, gbase, voff) do { _Pragma("unroll") for (int _i = 0; _i < 2; ++_i) \
;         __builtin_amdgcn_global_load_lds((const unsigned*)((const char*)(gbase) + (voff)[_i]), (LAS unsigned*)(lds + (bufoff) + ldsw + _i * 8192), 16, 0, 0); } while (0)
; #define PG8_LDA(dst, b, h) do { _Pragma("unroll") for (int m = 0; m < 4; ++m) _Pragma("unroll") for (int k = 0; k < 2; ++k) dst[m][k] = *(const LAS bf16x8*)(lds + PG8_SA(b, h) + aoff + m * 2048 + k * 1024); } while (0)
; #define PG8_LDB(dst, b, h) do { _Pragma("unroll") for (int n = 0; n < 2; ++n) _Pragma("unroll") for (int k = 0; k < 2; ++k) dst[n][k] = *(const LAS bf16x8*)(lds + PG8_SB(b, h) + boff + n * 2048 + k * 1024); } while (0)
; #define PG8_MMA(ai, bj, At, Bt) do { __builtin_amdgcn_s_setprio(1); _Pragma("unroll") for (int m = 0; m < 4; ++m) _Pragma("unroll") for (int n = 0; n < 2; ++n) _Pragma("unroll") for (int k = 0; k < 2; ++k) \
;         acc[ai][bj][m][n] = __builtin_amdgcn_mfma_f32_16x16x32_bf16(Bt[n][k], At[m][k], acc[ai][bj][m][n], 0, 0, 0); __builtin_amdgcn_s_setprio(0); } while (0)
; #define PG8_WAIT_V(n) asm volatile("s_waitcnt vmcnt(" #n ")" ::: "memory")
; #define PG8_WAIT_L(n) asm volatile("s_waitcnt lgkmcnt(" #n ")" ::: "memory")
; #define PG8_BAR __builtin_amdgcn_s_barrier()
; #define PG8_SCHED __builtin_amdgcn_sched_barrier(0)
; template <class Epi, bool SP2, class Sched>
; __device__ __forceinline__ void gemm_phase(LAS unsigned char* lds, const Gemm g, const Sched& S, const Epi& E) {
;     ...
;             PG8_WAIT_V(8); PG8_WAIT_L(0); PG8_BAR; PG8_MMA(1, 0, At, B0); PG8_MMA(1, 1, At, B1); PG8_BAR; PG8_SCHED;
;             PG8_LDB(B0, 1, 0); PG8_LDB(B1, 1, 1); PG8_SCHED; PG8_LDA(At, 1, 0); PG8_STAGE(PG8_SA(0, 1), a2 + hstep, voffA);
;             PG8_WAIT_V(8); PG8_WAIT_L(0); PG8_BAR; PG8_MMA(0, 0, At, B0); PG8_MMA(0, 1, At, B1); PG8_BAR; PG8_SCHED;
	s_setprio 1
	v_mfma_f32_16x16x32_bf16 v[60:63], v[140:143], v[178:181], v[60:63]
	v_mfma_f32_16x16x32_bf16 v[56:59], v[154:157], v[178:181], v[56:59]
	v_mfma_f32_16x16x32_bf16 v[44:47], v[140:143], v[186:189], v[44:47]
	v_mfma_f32_16x16x32_bf16 v[40:43], v[154:157], v[186:189], v[40:43]
	v_mfma_f32_16x16x32_bf16 v[28:31], v[140:143], v[214:217], v[28:31]
	v_mfma_f32_16x16x32_bf16 v[24:27], v[154:157], v[214:217], v[24:27]
	v_mfma_f32_16x16x32_bf16 v[12:15], v[140:143], v[222:225], v[12:15]
	v_mfma_f32_16x16x32_bf16 v[8:11], v[154:157], v[222:225], v[8:11]
	v_mfma_f32_16x16x32_bf16 v[60:63], v[150:153], v[182:185], v[60:63]
	v_mfma_f32_16x16x32_bf16 v[56:59], v[158:161], v[182:185], v[56:59]
	v_mfma_f32_16x16x32_bf16 v[44:47], v[150:153], v[190:193], v[44:47]
	v_mfma_f32_16x16x32_bf16 v[40:43], v[158:161], v[190:193], v[40:43]
	v_mfma_f32_16x16x32_bf16 v[28:31], v[150:153], v[218:221], v[28:31]
	v_mfma_f32_16x16x32_bf16 v[24:27], v[158:161], v[218:221], v[24:27]
	v_mfma_f32_16x16x32_bf16 v[12:15], v[150:153], v[226:229], v[12:15]
	v_mfma_f32_16x16x32_bf16 v[8:11], v[158:161], v[226:229], v[8:11]
	s_setprio 0
	s_setprio 1
	v_mfma_f32_16x16x32_bf16 v[52:55], v[162:165], v[178:181], v[52:55]
	v_mfma_f32_16x16x32_bf16 v[48:51], v[170:173], v[178:181], v[48:51]
	v_mfma_f32_16x16x32_bf16 v[36:39], v[162:165], v[186:189], v[36:39]
	v_mfma_f32_16x16x32_bf16 v[32:35], v[170:173], v[186:189], v[32:35]
	v_mfma_f32_16x16x32_bf16 v[20:23], v[162:165], v[214:217], v[20:23]
	v_mfma_f32_16x16x32_bf16 v[16:19], v[170:173], v[214:217], v[16:19]
	v_mfma_f32_16x16x32_bf16 v[4:7], v[162:165], v[222:225], v[4:7]
	v_mfma_f32_16x16x32_bf16 v[0:3], v[170:173], v[222:225], v[0:3]
	v_mfma_f32_16x16x32_bf16 v[52:55], v[166:169], v[182:185], v[52:55]
	v_mfma_f32_16x16x32_bf16 v[48:51], v[174:177], v[182:185], v[48:51]
	v_mfma_f32_16x16x32_bf16 v[36:39], v[166:169], v[190:193], v[36:39]
	v_mfma_f32_16x16x32_bf16 v[32:35], v[174:177], v[190:193], v[32:35]
	v_mfma_f32_16x16x32_bf16 v[20:23], v[166:169], v[218:221], v[20:23]
	v_mfma_f32_16x16x32_bf16 v[16:19], v[174:177], v[218:221], v[16:19]
	v_mfma_f32_16x16x32_bf16 v[4:7], v[166:169], v[226:229], v[4:7]
	v_mfma_f32_16x16x32_bf16 v[0:3], v[174:177], v[226:229], v[0:3]
	s_setprio 0
	s_barrier
	s_add_i32 s22, 0, 0x18000
	s_add_i32 s23, 0, 0x1c000
	v_add_u32_e32 v158, s22, v147
	v_add_u32_e32 v174, s23, v147
	ds_read_b128 v[140:143], v158
	ds_read_b128 v[150:153], v158 offset:1024
	ds_read_b128 v[154:157], v158 offset:2048
	ds_read_b128 v[158:161], v158 offset:3072
	ds_read_b128 v[162:165], v174
	ds_read_b128 v[166:169], v174 offset:1024
	ds_read_b128 v[170:173], v174 offset:2048
	ds_read_b128 v[174:177], v174 offset:3072
	s_add_u32 s10, s10, 0x40000
	s_addc_u32 s11, s11, 0
	s_mov_b32 m0, s15
	v_lshl_add_u64 v[236:237], s[10:11], 0, v[130:131]
	ds_read_b128 v[178:181], v149 offset:32768
	ds_read_b128 v[182:185], v149 offset:33792
	ds_read_b128 v[186:189], v149 offset:34816
	ds_read_b128 v[190:193], v149 offset:35840
	ds_read_b128 v[214:217], v149 offset:36864
	ds_read_b128 v[218:221], v149 offset:37888
	ds_read_b128 v[222:225], v149 offset:38912
	ds_read_b128 v[226:229], v149 offset:39936
	global_load_lds_dwordx4 v[236:237], off
	v_lshl_add_u64 v[236:237], s[10:11], 0, v[132:133]
	s_mov_b32 m0, s17
	s_nop 0
	global_load_lds_dwordx4 v[236:237], off
	s_waitcnt vmcnt(8) lgkmcnt(0)
	s_barrier
	s_setprio 1
	v_mfma_f32_16x16x32_bf16 v[126:129], v[140:143], v[178:181], v[126:129]
	v_mfma_f32_16x16x32_bf16 v[122:125], v[154:157], v[178:181], v[122:125]
	v_mfma_f32_16x16x32_bf16 v[110:113], v[140:143], v[186:189], v[110:113]
	v_mfma_f32_16x16x32_bf16 v[106:109], v[154:157], v[186:189], v[106:109]
	v_mfma_f32_16x16x32_bf16 v[94:97], v[140:143], v[214:217], v[94:97]
	v_mfma_f32_16x16x32_bf16 v[90:93], v[154:157], v[214:217], v[90:93]
	v_mfma_f32_16x16x32_bf16 v[78:81], v[140:143], v[222:225], v[78:81]
	v_mfma_f32_16x16x32_bf16 v[74:77], v[154:157], v[222:225], v[74:77]
	v_mfma_f32_16x16x32_bf16 v[126:129], v[150:153], v[182:185], v[126:129]
	v_mfma_f32_16x16x32_bf16 v[122:125], v[158:161], v[182:185], v[122:125]
	v_mfma_f32_16x16x32_bf16 v[110:113], v[150:153], v[190:193], v[110:113]
	v_mfma_f32_16x16x32_bf16 v[106:109], v[158:161], v[190:193], v[106:109]
	v_mfma_f32_16x16x32_bf16 v[94:97], v[150:153], v[218:221], v[94:97]
	v_mfma_f32_16x16x32_bf16 v[90:93], v[158:161], v[218:221], v[90:93]
	v_mfma_f32_16x16x32_bf16 v[78:81], v[150:153], v[226:229], v[78:81]
	v_mfma_f32_16x16x32_bf16 v[74:77], v[158:161], v[226:229], v[74:77]
	s_setprio 0
	s_setprio 1
	v_mfma_f32_16x16x32_bf16 v[118:121], v[162:165], v[178:181], v[118:121]
	v_mfma_f32_16x16x32_bf16 v[114:117], v[170:173], v[178:181], v[114:117]
	v_mfma_f32_16x16x32_bf16 v[102:105], v[162:165], v[186:189], v[102:105]
	v_mfma_f32_16x16x32_bf16 v[98:101], v[170:173], v[186:189], v[98:101]
	v_mfma_f32_16x16x32_bf16 v[86:89], v[162:165], v[214:217], v[86:89]
	v_mfma_f32_16x16x32_bf16 v[82:85], v[170:173], v[214:217], v[82:85]
	v_mfma_f32_16x16x32_bf16 v[70:73], v[162:165], v[222:225], v[70:73]
	v_mfma_f32_16x16x32_bf16 v[66:69], v[170:173], v[222:225], v[66:69]
	v_mfma_f32_16x16x32_bf16 v[118:121], v[166:169], v[182:185], v[118:121]
	v_mfma_f32_16x16x32_bf16 v[114:117], v[174:177], v[182:185], v[114:117]
	v_mfma_f32_16x16x32_bf16 v[102:105], v[166:169], v[190:193], v[102:105]
	v_mfma_f32_16x16x32_bf16 v[98:101], v[174:177], v[190:193], v[98:101]
	v_mfma_f32_16x16x32_bf16 v[86:89], v[166:169], v[218:221], v[86:89]
	v_mfma_f32_16x16x32_bf16 v[82:85], v[174:177], v[218:221], v[82:85]
	v_mfma_f32_16x16x32_bf16 v[70:73], v[166:169], v[226:229], v[70:73]
	v_mfma_f32_16x16x32_bf16 v[66:69], v[174:177], v[226:229], v[66:69]
	s_setprio 0
	s_barrier
; #define PG8_STAGE(bufoff, gbase, voff) do { _Pragma("unroll") for (int _i = 0; _i < 2; ++_i) \
;         __builtin_amdgcn_global_load_lds((const unsigned*)((const char*)(gbase) + (voff)[_i]), (LAS unsigned*)(lds + (bufoff) + ldsw + _i * 8192), 16, 0, 0); } while (0)
; #define PG8_LDA(dst, b, h) do { _Pragma("unroll") for (int m = 0; m < 4; ++m) _Pragma("unroll") for (int k = 0; k < 2; ++k) dst[m][k] = *(const LAS bf16x8*)(lds + PG8_SA(b, h) + aoff + m * 2048 + k * 1024); } while (0)
; #define PG8_MMA(ai, bj, At, Bt) do { __builtin_amdgcn_s_setprio(1); _Pragma("unroll") for (int m = 0; m < 4; ++m) _Pragma("unroll") for (int n = 0; n < 2; ++n) _Pragma("unroll") for (int k = 0; k < 2; ++k) \
;         acc[ai][bj][m][n] = __builtin_amdgcn_mfma_f32_16x16x32_bf16(Bt[n][k], At[m][k], acc[ai][bj][m][n], 0, 0, 0); __builtin_amdgcn_s_setprio(0); } while (0)
; #define PG8_WAIT_V(n) asm volatile("s_waitcnt vmcnt(" #n ")" ::: "memory")
; #define PG8_WAIT_L(n) asm volatile("s_waitcnt lgkmcnt(" #n ")" ::: "memory")
; #define PG8_BAR __builtin_amdgcn_s_barrier()
; #define PG8_SCHED __builtin_amdgcn_sched_barrier(0)
; template <class Epi, bool SP2, class Sched>
; __device__ __forceinline__ void gemm_phase(LAS unsigned char* lds, const Gemm g, const Sched& S, const Epi& E) {
;     ...
;         for (int t = 0; t < nt; t += 2) {
;     ...
;             PG8_LDA(At, 1, 1); PG8_STAGE(PG8_SB(1, 0), b3, voffB); PG8_STAGE(PG8_SB(1, 1), b3 + hstepB, voffB); PG8_STAGE(PG8_SA(1, 0), a3, voffA);
;             PG8_WAIT_V(8); PG8_WAIT_L(0); PG8_BAR; PG8_MMA(1, 0, At, B0); PG8_MMA(1, 1, At, B1); PG8_BAR; PG8_SCHED;
;     ...
;         if (wr == 0) PG8_BAR;
	s_add_i32 s10, s22, s12
	v_lshl_add_u64 v[144:145], v[144:145], 0, s[66:67]
	s_mov_b32 m0, s10
	ds_read_b128 v[178:181], v149 offset:49152
	ds_read_b128 v[182:185], v149 offset:50176
	ds_read_b128 v[186:189], v149 offset:51200
	ds_read_b128 v[190:193], v149 offset:52224
	ds_read_b128 v[214:217], v149 offset:53248
	ds_read_b128 v[218:221], v149 offset:54272
	ds_read_b128 v[222:225], v149 offset:55296
	ds_read_b128 v[226:229], v149 offset:56320
	global_load_lds_dwordx4 v[144:145], off
	s_add_i32 m0, s10, 0x2000
	s_add_u32 s6, s6, 0x40080
	v_lshl_add_u64 v[144:145], v[230:231], 0, s[66:67]
	s_addc_u32 s7, s7, 0
	s_add_i32 s10, s23, s12
	global_load_lds_dwordx4 v[144:145], off
	v_lshl_add_u64 v[144:145], s[6:7], 0, v[64:65]
	s_mov_b32 m0, s10
	s_nop 0
	global_load_lds_dwordx4 v[144:145], off
	v_lshl_add_u64 v[144:145], s[6:7], 0, v[134:135]
	s_add_i32 m0, s10, 0x2000
	s_nop 0
	global_load_lds_dwordx4 v[144:145], off
	v_lshl_add_u64 v[144:145], v[232:233], 0, s[66:67]
	s_mov_b32 m0, s18
	s_nop 0
	global_load_lds_dwordx4 v[144:145], off
	v_lshl_add_u64 v[144:145], v[234:235], 0, s[66:67]
	s_mov_b32 m0, s19
	s_nop 0
	global_load_lds_dwordx4 v[144:145], off
	s_waitcnt vmcnt(8) lgkmcnt(0)
	s_barrier
	s_setprio 1
	v_mfma_f32_16x16x32_bf16 v[60:63], v[140:143], v[178:181], v[60:63]
	v_mfma_f32_16x16x32_bf16 v[56:59], v[154:157], v[178:181], v[56:59]
	v_mfma_f32_16x16x32_bf16 v[44:47], v[140:143], v[186:189], v[44:47]
	v_mfma_f32_16x16x32_bf16 v[40:43], v[154:157], v[186:189], v[40:43]
	v_mfma_f32_16x16x32_bf16 v[28:31], v[140:143], v[214:217], v[28:31]
	v_mfma_f32_16x16x32_bf16 v[24:27], v[154:157], v[214:217], v[24:27]
	v_mfma_f32_16x16x32_bf16 v[12:15], v[140:143], v[222:225], v[12:15]
	v_mfma_f32_16x16x32_bf16 v[8:11], v[154:157], v[222:225], v[8:11]
	v_mfma_f32_16x16x32_bf16 v[60:63], v[150:153], v[182:185], v[60:63]
	v_mfma_f32_16x16x32_bf16 v[56:59], v[158:161], v[182:185], v[56:59]
	v_mfma_f32_16x16x32_bf16 v[44:47], v[150:153], v[190:193], v[44:47]
	v_mfma_f32_16x16x32_bf16 v[40:43], v[158:161], v[190:193], v[40:43]
	v_mfma_f32_16x16x32_bf16 v[28:31], v[150:153], v[218:221], v[28:31]
	v_mfma_f32_16x16x32_bf16 v[24:27], v[158:161], v[218:221], v[24:27]
	v_mfma_f32_16x16x32_bf16 v[12:15], v[150:153], v[226:229], v[12:15]
	v_mfma_f32_16x16x32_bf16 v[8:11], v[158:161], v[226:229], v[8:11]
	s_setprio 0
	s_setprio 1
	v_mfma_f32_16x16x32_bf16 v[52:55], v[162:165], v[178:181], v[52:55]
	v_mfma_f32_16x16x32_bf16 v[48:51], v[170:173], v[178:181], v[48:51]
	v_mfma_f32_16x16x32_bf16 v[36:39], v[162:165], v[186:189], v[36:39]
	v_mfma_f32_16x16x32_bf16 v[32:35], v[170:173], v[186:189], v[32:35]
	v_mfma_f32_16x16x32_bf16 v[20:23], v[162:165], v[214:217], v[20:23]
	v_mfma_f32_16x16x32_bf16 v[16:19], v[170:173], v[214:217], v[16:19]
	v_mfma_f32_16x16x32_bf16 v[4:7], v[162:165], v[222:225], v[4:7]
	v_mfma_f32_16x16x32_bf16 v[0:3], v[170:173], v[222:225], v[0:3]
	v_mfma_f32_16x16x32_bf16 v[52:55], v[166:169], v[182:185], v[52:55]
	v_mfma_f32_16x16x32_bf16 v[48:51], v[174:177], v[182:185], v[48:51]
	v_mfma_f32_16x16x32_bf16 v[36:39], v[166:169], v[190:193], v[36:39]
	v_mfma_f32_16x16x32_bf16 v[32:35], v[174:177], v[190:193], v[32:35]
	v_mfma_f32_16x16x32_bf16 v[20:23], v[166:169], v[218:221], v[20:23]
	v_mfma_f32_16x16x32_bf16 v[16:19], v[174:177], v[218:221], v[16:19]
	v_mfma_f32_16x16x32_bf16 v[4:7], v[166:169], v[226:229], v[4:7]
	v_mfma_f32_16x16x32_bf16 v[0:3], v[174:177], v[226:229], v[0:3]
	s_setprio 0
	s_barrier
	s_add_i32 s21, s21, 2
	s_add_u32 s76, s76, 0x100
	s_addc_u32 s20, s20, 0
	s_add_u32 s92, s92, 0x100
	s_addc_u32 s93, s93, 0
	s_cmp_gt_u32 s21, 13
	s_cbranch_scc0 .LBB0_955
	s_and_b64 vcc, exec, s[60:61]
	s_cbranch_vccz .LBB0_958
	s_barrier

; #define PG8_STAGE(bufoff, gbase, voff) do { _Pragma("unroll") for (int _i = 0; _i < 2; ++_i) \
;         __builtin_amdgcn_global_load_lds((const unsigned*)((const char*)(gbase) + (voff)[_i]), (LAS unsigned*)(lds + (bufoff) + ldsw + _i * 8192), 16, 0, 0); } while (0)
; #define PG8_LDA(dst, b, h) do { _Pragma("unroll") for (int m = 0; m < 4; ++m) _Pragma("unroll") for (int k = 0; k < 2; ++k) dst[m][k] = *(const LAS bf16x8*)(lds + PG8_SA(b, h) + aoff + m * 2048 + k * 1024); } while (0)
; #define PG8_LDB(dst, b, h) do { _Pragma("unroll") for (int n = 0; n < 2; ++n) _Pragma("unroll") for (int k = 0; k < 2; ++k) dst[n][k] = *(const LAS bf16x8*)(lds + PG8_SB(b, h) + boff + n * 2048 + k * 1024); } while (0)
; #define PG8_MMA(ai, bj, At, Bt) do { __builtin_amdgcn_s_setprio(1); _Pragma("unroll") for (int m = 0; m < 4; ++m) _Pragma("unroll") for (int n = 0; n < 2; ++n) _Pragma("unroll") for (int k = 0; k < 2; ++k) \
;         acc[ai][bj][m][n] = __builtin_amdgcn_mfma_f32_16x16x32_bf16(Bt[n][k], At[m][k], acc[ai][bj][m][n], 0, 0, 0); __builtin_amdgcn_s_setprio(0); } while (0)
; #define PG8_BAR __builtin_amdgcn_s_barrier()
; template <class Epi, bool SP2, class Sched>
; __device__ __forceinline__ void gemm_phase(LAS unsigned char* lds, const Gemm g, const Sched& S, const Epi& E) {
;     ...
;         const bool has_next = S.next(ui + 1, nxt);
;         const char* nA = has_next ? (const char*)g.A + (size_t)nxt.pm * tstep + nxt.ko : cA; const char* nB = has_next ? (const char*)g.Bt + (size_t)nxt.pn * tstepB + nxt.ko : cB;
;         for (int t = 0; t < nt; t += 2) {
;             const bool last = (t == nt - 2);
;             const char* a1 = cA + (size_t)(t + 1) * kstep;
;             const char* a2 = last ? nA : cA + (size_t)(t + 2) * kstep; const char* b2 = last ? nB : cB + (size_t)(t + 2) * kstep;
;             const char* a3 = a2 + kstep; const char* b3 = b2 + kstep;
;             if constexpr (Epi::MID) { if (t == (nt >> 1)) E.mid(acc, cur, wr, fr); }
;             if constexpr (SP2) {
;             PG8_LDB(B0, 0, 0); PG8_LDB(B1, 0, 1); PG8_SCHED; PG8_LDA(At, 0, 0); PG8_STAGE(PG8_SA(1, 1), a1 + hstep, voffA);
;             PG8_WAIT_V(8); PG8_WAIT_L(0); PG8_BAR; PG8_MMA(0, 0, At, B0); PG8_MMA(0, 1, At, B1); PG8_BAR; PG8_SCHED;
;             PG8_LDA(At, 0, 1); PG8_STAGE(PG8_SB(0, 0), b2, voffB); PG8_STAGE(PG8_SB(0, 1), b2 + hstepB, voffB); PG8_STAGE(PG8_SA(0, 0), a2, voffA);
.LBB0_1039:
	s_add_u32 s6, s16, 0xfffc0080
	s_addc_u32 s7, s17, -1
	s_add_i32 s19, 0, 0x10000
	s_cmp_eq_u32 s18, 12
	s_cselect_b32 s11, s8, s7
	s_cselect_b32 s10, s9, s6
	s_cselect_b32 s7, s12, s15
	s_cselect_b32 s6, s13, s14
	s_add_i32 s22, 0, 0x14000
	v_add_u32_e32 v156, s19, v145
	v_add_u32_e32 v172, s22, v145
	ds_read_b128 v[140:143], v156
	ds_read_b128 v[148:151], v156 offset:1024
	ds_read_b128 v[152:155], v156 offset:2048
	ds_read_b128 v[156:159], v156 offset:3072
	ds_read_b128 v[160:163], v172
	ds_read_b128 v[164:167], v172 offset:1024
	ds_read_b128 v[168:171], v172 offset:2048
	ds_read_b128 v[172:175], v172 offset:3072
	v_lshl_add_u64 v[192:193], s[16:17], 0, v[138:139]
	s_add_i32 m0, s83, 0xc000
	ds_read_b128 v[176:179], v147
	ds_read_b128 v[180:183], v147 offset:1024
	ds_read_b128 v[184:187], v147 offset:2048
	ds_read_b128 v[188:191], v147 offset:3072
	ds_read_b128 v[214:217], v147 offset:4096
	ds_read_b128 v[218:221], v147 offset:5120
	ds_read_b128 v[222:225], v147 offset:6144
	ds_read_b128 v[226:229], v147 offset:7168
	global_load_lds_dwordx4 v[192:193], off
	v_lshl_add_u64 v[192:193], s[16:17], 0, v[136:137]
	s_add_i32 m0, s83, 0xe000
	s_nop 0
	global_load_lds_dwordx4 v[192:193], off
	s_waitcnt vmcnt(8) lgkmcnt(0)
	s_barrier
	s_setprio 1
	v_mfma_f32_16x16x32_bf16 v[126:129], v[140:143], v[176:179], v[126:129]
	v_mfma_f32_16x16x32_bf16 v[122:125], v[152:155], v[176:179], v[122:125]
	v_mfma_f32_16x16x32_bf16 v[110:113], v[140:143], v[184:187], v[110:113]
	v_mfma_f32_16x16x32_bf16 v[106:109], v[152:155], v[184:187], v[106:109]
	v_mfma_f32_16x16x32_bf16 v[94:97], v[140:143], v[214:217], v[94:97]
	v_mfma_f32_16x16x32_bf16 v[90:93], v[152:155], v[214:217], v[90:93]
	v_mfma_f32_16x16x32_bf16 v[78:81], v[140:143], v[222:225], v[78:81]
	v_mfma_f32_16x16x32_bf16 v[74:77], v[152:155], v[222:225], v[74:77]
	v_mfma_f32_16x16x32_bf16 v[126:129], v[148:151], v[180:183], v[126:129]
	v_mfma_f32_16x16x32_bf16 v[122:125], v[156:159], v[180:183], v[122:125]
	v_mfma_f32_16x16x32_bf16 v[110:113], v[148:151], v[188:191], v[110:113]
	v_mfma_f32_16x16x32_bf16 v[106:109], v[156:159], v[188:191], v[106:109]
	v_mfma_f32_16x16x32_bf16 v[94:97], v[148:151], v[218:221], v[94:97]
	v_mfma_f32_16x16x32_bf16 v[90:93], v[156:159], v[218:221], v[90:93]
	v_mfma_f32_16x16x32_bf16 v[78:81], v[148:151], v[226:229], v[78:81]
	v_mfma_f32_16x16x32_bf16 v[74:77], v[156:159], v[226:229], v[74:77]
	s_setprio 0
	s_setprio 1
	v_mfma_f32_16x16x32_bf16 v[118:121], v[160:163], v[176:179], v[118:121]
	v_mfma_f32_16x16x32_bf16 v[114:117], v[168:171], v[176:179], v[114:117]
	v_mfma_f32_16x16x32_bf16 v[102:105], v[160:163], v[184:187], v[102:105]
	v_mfma_f32_16x16x32_bf16 v[98:101], v[168:171], v[184:187], v[98:101]
	v_mfma_f32_16x16x32_bf16 v[86:89], v[160:163], v[214:217], v[86:89]
	v_mfma_f32_16x16x32_bf16 v[82:85], v[168:171], v[214:217], v[82:85]
	v_mfma_f32_16x16x32_bf16 v[70:73], v[160:163], v[222:225], v[70:73]
	v_mfma_f32_16x16x32_bf16 v[66:69], v[168:171], v[222:225], v[66:69]
	v_mfma_f32_16x16x32_bf16 v[118:121], v[164:167], v[180:183], v[118:121]
	v_mfma_f32_16x16x32_bf16 v[114:117], v[172:175], v[180:183], v[114:117]
	v_mfma_f32_16x16x32_bf16 v[102:105], v[164:167], v[188:191], v[102:105]
	v_mfma_f32_16x16x32_bf16 v[98:101], v[172:175], v[188:191], v[98:101]
	v_mfma_f32_16x16x32_bf16 v[86:89], v[164:167], v[218:221], v[86:89]
	v_mfma_f32_16x16x32_bf16 v[82:85], v[172:175], v[218:221], v[82:85]
	v_mfma_f32_16x16x32_bf16 v[70:73], v[164:167], v[226:229], v[70:73]
	v_mfma_f32_16x16x32_bf16 v[66:69], v[172:175], v[226:229], v[66:69]
	s_setprio 0
	s_barrier
	s_add_i32 s19, s19, s79
	v_lshl_add_u64 v[192:193], s[6:7], 0, v[64:65]
	s_mov_b32 m0, s19
	ds_read_b128 v[176:179], v147 offset:16384
	ds_read_b128 v[180:183], v147 offset:17408
	ds_read_b128 v[184:187], v147 offset:18432
	ds_read_b128 v[188:191], v147 offset:19456
	ds_read_b128 v[214:217], v147 offset:20480
	ds_read_b128 v[218:221], v147 offset:21504
	ds_read_b128 v[222:225], v147 offset:22528
	ds_read_b128 v[226:229], v147 offset:23552
	global_load_lds_dwordx4 v[192:193], off
	s_add_i32 m0, s19, 0x2000
	s_add_u32 s20, s6, 0x40000
	v_lshl_add_u64 v[230:231], s[6:7], 0, v[130:131]
	s_addc_u32 s21, s7, 0
	s_add_i32 s19, s22, s79
	global_load_lds_dwordx4 v[230:231], off
	v_lshl_add_u64 v[232:233], s[20:21], 0, v[64:65]
	s_mov_b32 m0, s19
	v_lshl_add_u64 v[234:235], s[10:11], 0, v[132:133]
	global_load_lds_dwordx4 v[232:233], off
	v_lshl_add_u64 v[232:233], s[20:21], 0, v[130:131]
	s_add_i32 m0, s19, 0x2000
	s_nop 0
	global_load_lds_dwordx4 v[232:233], off
	v_lshl_add_u64 v[232:233], s[10:11], 0, v[134:135]
	s_mov_b32 m0, s83
	s_nop 0
	global_load_lds_dwordx4 v[232:233], off
	s_mov_b32 m0, s90
	s_nop 0
	global_load_lds_dwordx4 v[234:235], off
	s_waitcnt vmcnt(8) lgkmcnt(0)
	s_barrier
; #define PG8_STAGE(bufoff, gbase, voff) do { _Pragma("unroll") for (int _i = 0; _i < 2; ++_i) \
;         __builtin_amdgcn_global_load_lds((const unsigned*)((const char*)(gbase) + (voff)[_i]), (LAS unsigned*)(lds + (bufoff) + ldsw + _i * 8192), 16, 0, 0); } while (0)
; #define PG8_LDA(dst, b, h) do { _Pragma("unroll") for (int m = 0; m < 4; ++m) _Pragma("unroll") for (int k = 0; k < 2; ++k) dst[m][k] = *(const LAS bf16x8*)(lds + PG8_SA(b, h) + aoff + m * 2048 + k * 1024); } while (0)
; #define PG8_LDB(dst, b, h) do { _Pragma("unroll") for (int n = 0; n < 2; ++n) _Pragma("unroll") for (int k = 0; k < 2; ++k) dst[n][k] = *(const LAS bf16x8*)(lds + PG8_SB(b, h) + boff + n * 2048 + k * 1024); } while (0)
; #define PG8_MMA(ai, bj, At, Bt) do { __builtin_amdgcn_s_setprio(1); _Pragma("unroll") for (int m = 0; m < 4; ++m) _Pragma("unroll") for (int n = 0; n < 2; ++n) _Pragma("unroll") for (int k = 0; k < 2; ++k) \
;         acc[ai][bj][m][n] = __builtin_amdgcn_mfma_f32_16x16x32_bf16(Bt[n][k], At[m][k], acc[ai][bj][m][n], 0, 0, 0); __builtin_amdgcn_s_setprio(0); } while (0)
; #define PG8_WAIT_V(n) asm volatile("s_waitcnt vmcnt(" #n ")" ::: "memory")
; #define PG8_WAIT_L(n) asm volatile("s_waitcnt lgkmcnt(" #n ")" ::: "memory")
; #define PG8_BAR __builtin_amdgcn_s_barrier()
; #define PG8_SCHED __builtin_amdgcn_sched_barrier(0)
; template <class Epi, bool SP2, class Sched>
; __device__ __forceinline__ void gemm_phase(LAS unsigned char* lds, const Gemm g, const Sched& S, const Epi& E) {
;     ...
;             PG8_WAIT_V(8); PG8_WAIT_L(0); PG8_BAR; PG8_MMA(1, 0, At, B0); PG8_MMA(1, 1, At, B1); PG8_BAR; PG8_SCHED;
;             PG8_LDB(B0, 1, 0); PG8_LDB(B1, 1, 1); PG8_SCHED; PG8_LDA(At, 1, 0); PG8_STAGE(PG8_SA(0, 1), a2 + hstep, voffA);
;             PG8_WAIT_V(8); PG8_WAIT_L(0); PG8_BAR; PG8_MMA(0, 0, At, B0); PG8_MMA(0, 1, At, B1); PG8_BAR; PG8_SCHED;
	s_setprio 1
	v_mfma_f32_16x16x32_bf16 v[60:63], v[140:143], v[176:179], v[60:63]
	v_mfma_f32_16x16x32_bf16 v[56:59], v[152:155], v[176:179], v[56:59]
	v_mfma_f32_16x16x32_bf16 v[44:47], v[140:143], v[184:187], v[44:47]
	v_mfma_f32_16x16x32_bf16 v[40:43], v[152:155], v[184:187], v[40:43]
	v_mfma_f32_16x16x32_bf16 v[28:31], v[140:143], v[214:217], v[28:31]
	v_mfma_f32_16x16x32_bf16 v[24:27], v[152:155], v[214:217], v[24:27]
	v_mfma_f32_16x16x32_bf16 v[12:15], v[140:143], v[222:225], v[12:15]
	v_mfma_f32_16x16x32_bf16 v[8:11], v[152:155], v[222:225], v[8:11]
	v_mfma_f32_16x16x32_bf16 v[60:63], v[148:151], v[180:183], v[60:63]
	v_mfma_f32_16x16x32_bf16 v[56:59], v[156:159], v[180:183], v[56:59]
	v_mfma_f32_16x16x32_bf16 v[44:47], v[148:151], v[188:191], v[44:47]
	v_mfma_f32_16x16x32_bf16 v[40:43], v[156:159], v[188:191], v[40:43]
	v_mfma_f32_16x16x32_bf16 v[28:31], v[148:151], v[218:221], v[28:31]
	v_mfma_f32_16x16x32_bf16 v[24:27], v[156:159], v[218:221], v[24:27]
	v_mfma_f32_16x16x32_bf16 v[12:15], v[148:151], v[226:229], v[12:15]
	v_mfma_f32_16x16x32_bf16 v[8:11], v[156:159], v[226:229], v[8:11]
	s_setprio 0
	s_setprio 1
	v_mfma_f32_16x16x32_bf16 v[52:55], v[160:163], v[176:179], v[52:55]
	v_mfma_f32_16x16x32_bf16 v[48:51], v[168:171], v[176:179], v[48:51]
	v_mfma_f32_16x16x32_bf16 v[36:39], v[160:163], v[184:187], v[36:39]
	v_mfma_f32_16x16x32_bf16 v[32:35], v[168:171], v[184:187], v[32:35]
	v_mfma_f32_16x16x32_bf16 v[20:23], v[160:163], v[214:217], v[20:23]
	v_mfma_f32_16x16x32_bf16 v[16:19], v[168:171], v[214:217], v[16:19]
	v_mfma_f32_16x16x32_bf16 v[4:7], v[160:163], v[222:225], v[4:7]
	v_mfma_f32_16x16x32_bf16 v[0:3], v[168:171], v[222:225], v[0:3]
	v_mfma_f32_16x16x32_bf16 v[52:55], v[164:167], v[180:183], v[52:55]
	v_mfma_f32_16x16x32_bf16 v[48:51], v[172:175], v[180:183], v[48:51]
	v_mfma_f32_16x16x32_bf16 v[36:39], v[164:167], v[188:191], v[36:39]
	v_mfma_f32_16x16x32_bf16 v[32:35], v[172:175], v[188:191], v[32:35]
	v_mfma_f32_16x16x32_bf16 v[20:23], v[164:167], v[218:221], v[20:23]
	v_mfma_f32_16x16x32_bf16 v[16:19], v[172:175], v[218:221], v[16:19]
	v_mfma_f32_16x16x32_bf16 v[4:7], v[164:167], v[226:229], v[4:7]
	v_mfma_f32_16x16x32_bf16 v[0:3], v[172:175], v[226:229], v[0:3]
	s_setprio 0
	s_barrier
	s_add_i32 s19, 0, 0x18000
	s_add_i32 s20, 0, 0x1c000
	v_add_u32_e32 v156, s19, v145
	v_add_u32_e32 v172, s20, v145
	ds_read_b128 v[140:143], v156
	ds_read_b128 v[148:151], v156 offset:1024
	ds_read_b128 v[152:155], v156 offset:2048
	ds_read_b128 v[156:159], v156 offset:3072
	ds_read_b128 v[160:163], v172
	ds_read_b128 v[164:167], v172 offset:1024
	ds_read_b128 v[168:171], v172 offset:2048
	ds_read_b128 v[172:175], v172 offset:3072
	s_add_u32 s10, s10, 0x40000
	s_addc_u32 s11, s11, 0
	s_mov_b32 m0, s91
	v_lshl_add_u64 v[236:237], s[10:11], 0, v[134:135]
	ds_read_b128 v[176:179], v147 offset:32768
	ds_read_b128 v[180:183], v147 offset:33792
	ds_read_b128 v[184:187], v147 offset:34816
	ds_read_b128 v[188:191], v147 offset:35840
	ds_read_b128 v[214:217], v147 offset:36864
	ds_read_b128 v[218:221], v147 offset:37888
	ds_read_b128 v[222:225], v147 offset:38912
	ds_read_b128 v[226:229], v147 offset:39936
	global_load_lds_dwordx4 v[236:237], off
	v_lshl_add_u64 v[236:237], s[10:11], 0, v[132:133]
	s_mov_b32 m0, s92
	s_nop 0
	global_load_lds_dwordx4 v[236:237], off
	s_waitcnt vmcnt(8) lgkmcnt(0)
	s_barrier
	s_setprio 1
	v_mfma_f32_16x16x32_bf16 v[126:129], v[140:143], v[176:179], v[126:129]
	v_mfma_f32_16x16x32_bf16 v[122:125], v[152:155], v[176:179], v[122:125]
	v_mfma_f32_16x16x32_bf16 v[110:113], v[140:143], v[184:187], v[110:113]
	v_mfma_f32_16x16x32_bf16 v[106:109], v[152:155], v[184:187], v[106:109]
	v_mfma_f32_16x16x32_bf16 v[94:97], v[140:143], v[214:217], v[94:97]
	v_mfma_f32_16x16x32_bf16 v[90:93], v[152:155], v[214:217], v[90:93]
	v_mfma_f32_16x16x32_bf16 v[78:81], v[140:143], v[222:225], v[78:81]
	v_mfma_f32_16x16x32_bf16 v[74:77], v[152:155], v[222:225], v[74:77]
	v_mfma_f32_16x16x32_bf16 v[126:129], v[148:151], v[180:183], v[126:129]
	v_mfma_f32_16x16x32_bf16 v[122:125], v[156:159], v[180:183], v[122:125]
	v_mfma_f32_16x16x32_bf16 v[110:113], v[148:151], v[188:191], v[110:113]
	v_mfma_f32_16x16x32_bf16 v[106:109], v[156:159], v[188:191], v[106:109]
	v_mfma_f32_16x16x32_bf16 v[94:97], v[148:151], v[218:221], v[94:97]
	v_mfma_f32_16x16x32_bf16 v[90:93], v[156:159], v[218:221], v[90:93]
	v_mfma_f32_16x16x32_bf16 v[78:81], v[148:151], v[226:229], v[78:81]
	v_mfma_f32_16x16x32_bf16 v[74:77], v[156:159], v[226:229], v[74:77]
	s_setprio 0
	s_setprio 1
	v_mfma_f32_16x16x32_bf16 v[118:121], v[160:163], v[176:179], v[118:121]
	v_mfma_f32_16x16x32_bf16 v[114:117], v[168:171], v[176:179], v[114:117]
	v_mfma_f32_16x16x32_bf16 v[102:105], v[160:163], v[184:187], v[102:105]
	v_mfma_f32_16x16x32_bf16 v[98:101], v[168:171], v[184:187], v[98:101]
	v_mfma_f32_16x16x32_bf16 v[86:89], v[160:163], v[214:217], v[86:89]
	v_mfma_f32_16x16x32_bf16 v[82:85], v[168:171], v[214:217], v[82:85]
	v_mfma_f32_16x16x32_bf16 v[70:73], v[160:163], v[222:225], v[70:73]
	v_mfma_f32_16x16x32_bf16 v[66:69], v[168:171], v[222:225], v[66:69]
	v_mfma_f32_16x16x32_bf16 v[118:121], v[164:167], v[180:183], v[118:121]
	v_mfma_f32_16x16x32_bf16 v[114:117], v[172:175], v[180:183], v[114:117]
	v_mfma_f32_16x16x32_bf16 v[102:105], v[164:167], v[188:191], v[102:105]
	v_mfma_f32_16x16x32_bf16 v[98:101], v[172:175], v[188:191], v[98:101]
	v_mfma_f32_16x16x32_bf16 v[86:89], v[164:167], v[218:221], v[86:89]
	v_mfma_f32_16x16x32_bf16 v[82:85], v[172:175], v[218:221], v[82:85]
	v_mfma_f32_16x16x32_bf16 v[70:73], v[164:167], v[226:229], v[70:73]
	v_mfma_f32_16x16x32_bf16 v[66:69], v[172:175], v[226:229], v[66:69]
	s_setprio 0
	s_barrier
; #define PG8_STAGE(bufoff, gbase, voff) do { _Pragma("unroll") for (int _i = 0; _i < 2; ++_i) \
;         __builtin_amdgcn_global_load_lds((const unsigned*)((const char*)(gbase) + (voff)[_i]), (LAS unsigned*)(lds + (bufoff) + ldsw + _i * 8192), 16, 0, 0); } while (0)
; #define PG8_LDA(dst, b, h) do { _Pragma("unroll") for (int m = 0; m < 4; ++m) _Pragma("unroll") for (int k = 0; k < 2; ++k) dst[m][k] = *(const LAS bf16x8*)(lds + PG8_SA(b, h) + aoff + m * 2048 + k * 1024); } while (0)
; #define PG8_MMA(ai, bj, At, Bt) do { __builtin_amdgcn_s_setprio(1); _Pragma("unroll") for (int m = 0; m < 4; ++m) _Pragma("unroll") for (int n = 0; n < 2; ++n) _Pragma("unroll") for (int k = 0; k < 2; ++k) \
;         acc[ai][bj][m][n] = __builtin_amdgcn_mfma_f32_16x16x32_bf16(Bt[n][k], At[m][k], acc[ai][bj][m][n], 0, 0, 0); __builtin_amdgcn_s_setprio(0); } while (0)
; #define PG8_WAIT_V(n) asm volatile("s_waitcnt vmcnt(" #n ")" ::: "memory")
; #define PG8_WAIT_L(n) asm volatile("s_waitcnt lgkmcnt(" #n ")" ::: "memory")
; #define PG8_BAR __builtin_amdgcn_s_barrier()
; #define PG8_SCHED __builtin_amdgcn_sched_barrier(0)
; template <class Epi, bool SP2, class Sched>
; __device__ __forceinline__ void gemm_phase(LAS unsigned char* lds, const Gemm g, const Sched& S, const Epi& E) {
;     ...
;         for (int t = 0; t < nt; t += 2) {
;     ...
;             PG8_LDA(At, 1, 1); PG8_STAGE(PG8_SB(1, 0), b3, voffB); PG8_STAGE(PG8_SB(1, 1), b3 + hstepB, voffB); PG8_STAGE(PG8_SA(1, 0), a3, voffA);
;             PG8_WAIT_V(8); PG8_WAIT_L(0); PG8_BAR; PG8_MMA(1, 0, At, B0); PG8_MMA(1, 1, At, B1); PG8_BAR; PG8_SCHED;
;     ...
;         if (wr == 0) PG8_BAR;
	s_add_i32 s10, s19, s79
	v_lshl_add_u64 v[192:193], v[192:193], 0, s[66:67]
	s_mov_b32 m0, s10
	ds_read_b128 v[176:179], v147 offset:49152
	ds_read_b128 v[180:183], v147 offset:50176
	ds_read_b128 v[184:187], v147 offset:51200
	ds_read_b128 v[188:191], v147 offset:52224
	ds_read_b128 v[214:217], v147 offset:53248
	ds_read_b128 v[218:221], v147 offset:54272
	ds_read_b128 v[222:225], v147 offset:55296
	ds_read_b128 v[226:229], v147 offset:56320
	global_load_lds_dwordx4 v[192:193], off
	s_add_i32 m0, s10, 0x2000
	s_add_u32 s6, s6, 0x40080
	v_lshl_add_u64 v[192:193], v[230:231], 0, s[66:67]
	s_addc_u32 s7, s7, 0
	s_add_i32 s10, s20, s79
	global_load_lds_dwordx4 v[192:193], off
	v_lshl_add_u64 v[192:193], s[6:7], 0, v[64:65]
	s_mov_b32 m0, s10
	s_nop 0
	global_load_lds_dwordx4 v[192:193], off
	v_lshl_add_u64 v[192:193], s[6:7], 0, v[130:131]
	s_add_i32 m0, s10, 0x2000
	s_nop 0
	global_load_lds_dwordx4 v[192:193], off
	v_lshl_add_u64 v[192:193], v[232:233], 0, s[66:67]
	s_mov_b32 m0, s94
	s_nop 0
	global_load_lds_dwordx4 v[192:193], off
	v_lshl_add_u64 v[192:193], v[234:235], 0, s[66:67]
	s_mov_b32 m0, s95
	s_nop 0
	global_load_lds_dwordx4 v[192:193], off
	s_waitcnt vmcnt(8) lgkmcnt(0)
	s_barrier
	s_setprio 1
	v_mfma_f32_16x16x32_bf16 v[60:63], v[140:143], v[176:179], v[60:63]
	v_mfma_f32_16x16x32_bf16 v[56:59], v[152:155], v[176:179], v[56:59]
	v_mfma_f32_16x16x32_bf16 v[44:47], v[140:143], v[184:187], v[44:47]
	v_mfma_f32_16x16x32_bf16 v[40:43], v[152:155], v[184:187], v[40:43]
	v_mfma_f32_16x16x32_bf16 v[28:31], v[140:143], v[214:217], v[28:31]
	v_mfma_f32_16x16x32_bf16 v[24:27], v[152:155], v[214:217], v[24:27]
	v_mfma_f32_16x16x32_bf16 v[12:15], v[140:143], v[222:225], v[12:15]
	v_mfma_f32_16x16x32_bf16 v[8:11], v[152:155], v[222:225], v[8:11]
	v_mfma_f32_16x16x32_bf16 v[60:63], v[148:151], v[180:183], v[60:63]
	v_mfma_f32_16x16x32_bf16 v[56:59], v[156:159], v[180:183], v[56:59]
	v_mfma_f32_16x16x32_bf16 v[44:47], v[148:151], v[188:191], v[44:47]
	v_mfma_f32_16x16x32_bf16 v[40:43], v[156:159], v[188:191], v[40:43]
	v_mfma_f32_16x16x32_bf16 v[28:31], v[148:151], v[218:221], v[28:31]
	v_mfma_f32_16x16x32_bf16 v[24:27], v[156:159], v[218:221], v[24:27]
	v_mfma_f32_16x16x32_bf16 v[12:15], v[148:151], v[226:229], v[12:15]
	v_mfma_f32_16x16x32_bf16 v[8:11], v[156:159], v[226:229], v[8:11]
	s_setprio 0
	s_setprio 1
	v_mfma_f32_16x16x32_bf16 v[52:55], v[160:163], v[176:179], v[52:55]
	v_mfma_f32_16x16x32_bf16 v[48:51], v[168:171], v[176:179], v[48:51]
	v_mfma_f32_16x16x32_bf16 v[36:39], v[160:163], v[184:187], v[36:39]
	v_mfma_f32_16x16x32_bf16 v[32:35], v[168:171], v[184:187], v[32:35]
	v_mfma_f32_16x16x32_bf16 v[20:23], v[160:163], v[214:217], v[20:23]
	v_mfma_f32_16x16x32_bf16 v[16:19], v[168:171], v[214:217], v[16:19]
	v_mfma_f32_16x16x32_bf16 v[4:7], v[160:163], v[222:225], v[4:7]
	v_mfma_f32_16x16x32_bf16 v[0:3], v[168:171], v[222:225], v[0:3]
	v_mfma_f32_16x16x32_bf16 v[52:55], v[164:167], v[180:183], v[52:55]
	v_mfma_f32_16x16x32_bf16 v[48:51], v[172:175], v[180:183], v[48:51]
	v_mfma_f32_16x16x32_bf16 v[36:39], v[164:167], v[188:191], v[36:39]
	v_mfma_f32_16x16x32_bf16 v[32:35], v[172:175], v[188:191], v[32:35]
	v_mfma_f32_16x16x32_bf16 v[20:23], v[164:167], v[218:221], v[20:23]
	v_mfma_f32_16x16x32_bf16 v[16:19], v[172:175], v[218:221], v[16:19]
	v_mfma_f32_16x16x32_bf16 v[4:7], v[164:167], v[226:229], v[4:7]
	v_mfma_f32_16x16x32_bf16 v[0:3], v[172:175], v[226:229], v[0:3]
	s_setprio 0
	s_barrier
	s_add_i32 s18, s18, 2
	s_add_u32 s14, s14, 0x100
	s_addc_u32 s15, s15, 0
	s_add_u32 s16, s16, 0x100
	s_addc_u32 s17, s17, 0
	s_cmp_gt_u32 s18, 13
	s_cbranch_scc0 .LBB0_1039
	s_and_b64 vcc, exec, s[58:59]
	s_cbranch_vccz .LBB0_1042
	s_barrier

; #define PG8_STAGE(bufoff, gbase, voff) do { _Pragma("unroll") for (int _i = 0; _i < 2; ++_i) \
;         __builtin_amdgcn_global_load_lds((const unsigned*)((const char*)(gbase) + (voff)[_i]), (LAS unsigned*)(lds + (bufoff) + ldsw + _i * 8192), 16, 0, 0); } while (0)
; #define PG8_LDA(dst, b, h) do { _Pragma("unroll") for (int m = 0; m < 4; ++m) _Pragma("unroll") for (int k = 0; k < 2; ++k) dst[m][k] = *(const LAS bf16x8*)(lds + PG8_SA(b, h) + aoff + m * 2048 + k * 1024); } while (0)
; #define PG8_LDB(dst, b, h) do { _Pragma("unroll") for (int n = 0; n < 2; ++n) _Pragma("unroll") for (int k = 0; k < 2; ++k) dst[n][k] = *(const LAS bf16x8*)(lds + PG8_SB(b, h) + boff + n * 2048 + k * 1024); } while (0)
; #define PG8_MMA(ai, bj, At, Bt) do { __builtin_amdgcn_s_setprio(1); _Pragma("unroll") for (int m = 0; m < 4; ++m) _Pragma("unroll") for (int n = 0; n < 2; ++n) _Pragma("unroll") for (int k = 0; k < 2; ++k) \
;         acc[ai][bj][m][n] = __builtin_amdgcn_mfma_f32_16x16x32_bf16(Bt[n][k], At[m][k], acc[ai][bj][m][n], 0, 0, 0); __builtin_amdgcn_s_setprio(0); } while (0)
; #define PG8_BAR __builtin_amdgcn_s_barrier()
; template <class Epi, bool SP2, class Sched>
; __device__ __forceinline__ void gemm_phase(LAS unsigned char* lds, const Gemm g, const Sched& S, const Epi& E) {
;     ...
;         const bool has_next = S.next(ui + 1, nxt);
;         const char* nA = has_next ? (const char*)g.A + (size_t)nxt.pm * tstep + nxt.ko : cA; const char* nB = has_next ? (const char*)g.Bt + (size_t)nxt.pn * tstepB + nxt.ko : cB;
;         for (int t = 0; t < nt; t += 2) {
;             const bool last = (t == nt - 2);
;             const char* a1 = cA + (size_t)(t + 1) * kstep;
;             const char* a2 = last ? nA : cA + (size_t)(t + 2) * kstep; const char* b2 = last ? nB : cB + (size_t)(t + 2) * kstep;
;             const char* a3 = a2 + kstep; const char* b3 = b2 + kstep;
;             if constexpr (Epi::MID) { if (t == (nt >> 1)) E.mid(acc, cur, wr, fr); }
;             if constexpr (SP2) {
;             PG8_LDB(B0, 0, 0); PG8_LDB(B1, 0, 1); PG8_SCHED; PG8_LDA(At, 0, 0); PG8_STAGE(PG8_SA(1, 1), a1 + hstep, voffA);
;             PG8_WAIT_V(8); PG8_WAIT_L(0); PG8_BAR; PG8_MMA(0, 0, At, B0); PG8_MMA(0, 1, At, B1); PG8_BAR; PG8_SCHED;
;             PG8_LDA(At, 0, 1); PG8_STAGE(PG8_SB(0, 0), b2, voffB); PG8_STAGE(PG8_SB(0, 1), b2 + hstepB, voffB); PG8_STAGE(PG8_SA(0, 0), a2, voffA);
.LBB0_1118:
	s_add_u32 s6, s92, 0xfff00080
	s_addc_u32 s7, s93, -1
	s_add_i32 s22, 0, 0x10000
	s_cmp_eq_u32 s21, 60
	s_cselect_b32 s11, s73, s7
	s_cselect_b32 s10, s74, s6
	v_add_u32_e32 v144, s22, v147
	s_cselect_b32 s7, s5, s20
	s_cselect_b32 s6, s75, s76
	s_add_i32 s24, 0, 0x14000
	ds_read_b128 v[140:143], v144
	ds_read_b128 v[150:153], v144 offset:1024
	ds_read_b128 v[154:157], v144 offset:2048
	ds_read_b128 v[158:161], v144 offset:3072
	v_add_u32_e32 v144, s24, v147
	ds_read_b128 v[162:165], v144
	ds_read_b128 v[166:169], v144 offset:1024
	ds_read_b128 v[170:173], v144 offset:2048
	ds_read_b128 v[174:177], v144 offset:3072
	v_lshl_add_u64 v[144:145], s[92:93], 0, v[138:139]
	s_add_i32 m0, s13, 0xc000
	ds_read_b128 v[178:181], v149
	ds_read_b128 v[182:185], v149 offset:1024
	ds_read_b128 v[186:189], v149 offset:2048
	ds_read_b128 v[190:193], v149 offset:3072
	ds_read_b128 v[214:217], v149 offset:4096
	ds_read_b128 v[218:221], v149 offset:5120
	ds_read_b128 v[222:225], v149 offset:6144
	ds_read_b128 v[226:229], v149 offset:7168
	global_load_lds_dwordx4 v[144:145], off
	v_lshl_add_u64 v[144:145], s[92:93], 0, v[136:137]
	s_add_i32 m0, s13, 0xe000
	s_nop 0
	global_load_lds_dwordx4 v[144:145], off
	s_waitcnt vmcnt(8) lgkmcnt(0)
	s_barrier
	s_setprio 1
	v_mfma_f32_16x16x32_bf16 v[126:129], v[140:143], v[178:181], v[126:129]
	v_mfma_f32_16x16x32_bf16 v[122:125], v[154:157], v[178:181], v[122:125]
	v_mfma_f32_16x16x32_bf16 v[110:113], v[140:143], v[186:189], v[110:113]
	v_mfma_f32_16x16x32_bf16 v[106:109], v[154:157], v[186:189], v[106:109]
	v_mfma_f32_16x16x32_bf16 v[94:97], v[140:143], v[214:217], v[94:97]
	v_mfma_f32_16x16x32_bf16 v[90:93], v[154:157], v[214:217], v[90:93]
	v_mfma_f32_16x16x32_bf16 v[78:81], v[140:143], v[222:225], v[78:81]
	v_mfma_f32_16x16x32_bf16 v[74:77], v[154:157], v[222:225], v[74:77]
	v_mfma_f32_16x16x32_bf16 v[126:129], v[150:153], v[182:185], v[126:129]
	v_mfma_f32_16x16x32_bf16 v[122:125], v[158:161], v[182:185], v[122:125]
	v_mfma_f32_16x16x32_bf16 v[110:113], v[150:153], v[190:193], v[110:113]
	v_mfma_f32_16x16x32_bf16 v[106:109], v[158:161], v[190:193], v[106:109]
	v_mfma_f32_16x16x32_bf16 v[94:97], v[150:153], v[218:221], v[94:97]
	v_mfma_f32_16x16x32_bf16 v[90:93], v[158:161], v[218:221], v[90:93]
	v_mfma_f32_16x16x32_bf16 v[78:81], v[150:153], v[226:229], v[78:81]
	v_mfma_f32_16x16x32_bf16 v[74:77], v[158:161], v[226:229], v[74:77]
	s_setprio 0
	s_setprio 1
	v_mfma_f32_16x16x32_bf16 v[118:121], v[162:165], v[178:181], v[118:121]
	v_mfma_f32_16x16x32_bf16 v[114:117], v[170:173], v[178:181], v[114:117]
	v_mfma_f32_16x16x32_bf16 v[102:105], v[162:165], v[186:189], v[102:105]
	v_mfma_f32_16x16x32_bf16 v[98:101], v[170:173], v[186:189], v[98:101]
	v_mfma_f32_16x16x32_bf16 v[86:89], v[162:165], v[214:217], v[86:89]
	v_mfma_f32_16x16x32_bf16 v[82:85], v[170:173], v[214:217], v[82:85]
	v_mfma_f32_16x16x32_bf16 v[70:73], v[162:165], v[222:225], v[70:73]
	v_mfma_f32_16x16x32_bf16 v[66:69], v[170:173], v[222:225], v[66:69]
	v_mfma_f32_16x16x32_bf16 v[118:121], v[166:169], v[182:185], v[118:121]
	v_mfma_f32_16x16x32_bf16 v[114:117], v[174:177], v[182:185], v[114:117]
	v_mfma_f32_16x16x32_bf16 v[102:105], v[166:169], v[190:193], v[102:105]
	v_mfma_f32_16x16x32_bf16 v[98:101], v[174:177], v[190:193], v[98:101]
	v_mfma_f32_16x16x32_bf16 v[86:89], v[166:169], v[218:221], v[86:89]
	v_mfma_f32_16x16x32_bf16 v[82:85], v[174:177], v[218:221], v[82:85]
	v_mfma_f32_16x16x32_bf16 v[70:73], v[166:169], v[226:229], v[70:73]
	v_mfma_f32_16x16x32_bf16 v[66:69], v[174:177], v[226:229], v[66:69]
	s_setprio 0
	s_barrier
	s_add_i32 s22, s22, s12
	v_lshl_add_u64 v[144:145], s[6:7], 0, v[64:65]
	s_mov_b32 m0, s22
	ds_read_b128 v[178:181], v149 offset:16384
	ds_read_b128 v[182:185], v149 offset:17408
	ds_read_b128 v[186:189], v149 offset:18432
	ds_read_b128 v[190:193], v149 offset:19456
	ds_read_b128 v[214:217], v149 offset:20480
	ds_read_b128 v[218:221], v149 offset:21504
	ds_read_b128 v[222:225], v149 offset:22528
	ds_read_b128 v[226:229], v149 offset:23552
	global_load_lds_dwordx4 v[144:145], off
	s_add_i32 m0, s22, 0x2000
	s_add_u32 s22, s6, 0x100000
	v_lshl_add_u64 v[230:231], s[6:7], 0, v[134:135]
	s_addc_u32 s23, s7, 0
	s_add_i32 s24, s24, s12
	global_load_lds_dwordx4 v[230:231], off
	v_lshl_add_u64 v[232:233], s[22:23], 0, v[64:65]
	s_mov_b32 m0, s24
	v_lshl_add_u64 v[234:235], s[10:11], 0, v[132:133]
	global_load_lds_dwordx4 v[232:233], off
	v_lshl_add_u64 v[232:233], s[22:23], 0, v[134:135]
	s_add_i32 m0, s24, 0x2000
	s_nop 0
	global_load_lds_dwordx4 v[232:233], off
	v_lshl_add_u64 v[232:233], s[10:11], 0, v[130:131]
	s_mov_b32 m0, s13
	s_nop 0
	global_load_lds_dwordx4 v[232:233], off
	s_mov_b32 m0, s14
	s_nop 0
	global_load_lds_dwordx4 v[234:235], off
	s_waitcnt vmcnt(8) lgkmcnt(0)
	s_barrier
; #define PG8_STAGE(bufoff, gbase, voff) do { _Pragma("unroll") for (int _i = 0; _i < 2; ++_i) \
;         __builtin_amdgcn_global_load_lds((const unsigned*)((const char*)(gbase) + (voff)[_i]), (LAS unsigned*)(lds + (bufoff) + ldsw + _i * 8192), 16, 0, 0); } while (0)
; #define PG8_LDA(dst, b, h) do { _Pragma("unroll") for (int m = 0; m < 4; ++m) _Pragma("unroll") for (int k = 0; k < 2; ++k) dst[m][k] = *(const LAS bf16x8*)(lds + PG8_SA(b, h) + aoff + m * 2048 + k * 1024); } while (0)
; #define PG8_LDB(dst, b, h) do { _Pragma("unroll") for (int n = 0; n < 2; ++n) _Pragma("unroll") for (int k = 0; k < 2; ++k) dst[n][k] = *(const LAS bf16x8*)(lds + PG8_SB(b, h) + boff + n * 2048 + k * 1024); } while (0)
; #define PG8_MMA(ai, bj, At, Bt) do { __builtin_amdgcn_s_setprio(1); _Pragma("unroll") for (int m = 0; m < 4; ++m) _Pragma("unroll") for (int n = 0; n < 2; ++n) _Pragma("unroll") for (int k = 0; k < 2; ++k) \
;         acc[ai][bj][m][n] = __builtin_amdgcn_mfma_f32_16x16x32_bf16(Bt[n][k], At[m][k], acc[ai][bj][m][n], 0, 0, 0); __builtin_amdgcn_s_setprio(0); } while (0)
; #define PG8_WAIT_V(n) asm volatile("s_waitcnt vmcnt(" #n ")" ::: "memory")
; #define PG8_WAIT_L(n) asm volatile("s_waitcnt lgkmcnt(" #n ")" ::: "memory")
; #define PG8_BAR __builtin_amdgcn_s_barrier()
; #define PG8_SCHED __builtin_amdgcn_sched_barrier(0)
; template <class Epi, bool SP2, class Sched>
; __device__ __forceinline__ void gemm_phase(LAS unsigned char* lds, const Gemm g, const Sched& S, const Epi& E) {
;     ...
;             PG8_WAIT_V(8); PG8_WAIT_L(0); PG8_BAR; PG8_MMA(1, 0, At, B0); PG8_MMA(1, 1, At, B1); PG8_BAR; PG8_SCHED;
;             PG8_LDB(B0, 1, 0); PG8_LDB(B1, 1, 1); PG8_SCHED; PG8_LDA(At, 1, 0); PG8_STAGE(PG8_SA(0, 1), a2 + hstep, voffA);
;             PG8_WAIT_V(8); PG8_WAIT_L(0); PG8_BAR; PG8_MMA(0, 0, At, B0); PG8_MMA(0, 1, At, B1); PG8_BAR; PG8_SCHED;
	s_setprio 1
	v_mfma_f32_16x16x32_bf16 v[60:63], v[140:143], v[178:181], v[60:63]
	v_mfma_f32_16x16x32_bf16 v[56:59], v[154:157], v[178:181], v[56:59]
	v_mfma_f32_16x16x32_bf16 v[44:47], v[140:143], v[186:189], v[44:47]
	v_mfma_f32_16x16x32_bf16 v[40:43], v[154:157], v[186:189], v[40:43]
	v_mfma_f32_16x16x32_bf16 v[28:31], v[140:143], v[214:217], v[28:31]
	v_mfma_f32_16x16x32_bf16 v[24:27], v[154:157], v[214:217], v[24:27]
	v_mfma_f32_16x16x32_bf16 v[12:15], v[140:143], v[222:225], v[12:15]
	v_mfma_f32_16x16x32_bf16 v[8:11], v[154:157], v[222:225], v[8:11]
	v_mfma_f32_16x16x32_bf16 v[60:63], v[150:153], v[182:185], v[60:63]
	v_mfma_f32_16x16x32_bf16 v[56:59], v[158:161], v[182:185], v[56:59]
	v_mfma_f32_16x16x32_bf16 v[44:47], v[150:153], v[190:193], v[44:47]
	v_mfma_f32_16x16x32_bf16 v[40:43], v[158:161], v[190:193], v[40:43]
	v_mfma_f32_16x16x32_bf16 v[28:31], v[150:153], v[218:221], v[28:31]
	v_mfma_f32_16x16x32_bf16 v[24:27], v[158:161], v[218:221], v[24:27]
	v_mfma_f32_16x16x32_bf16 v[12:15], v[150:153], v[226:229], v[12:15]
	v_mfma_f32_16x16x32_bf16 v[8:11], v[158:161], v[226:229], v[8:11]
	s_setprio 0
	s_setprio 1
	v_mfma_f32_16x16x32_bf16 v[52:55], v[162:165], v[178:181], v[52:55]
	v_mfma_f32_16x16x32_bf16 v[48:51], v[170:173], v[178:181], v[48:51]
	v_mfma_f32_16x16x32_bf16 v[36:39], v[162:165], v[186:189], v[36:39]
	v_mfma_f32_16x16x32_bf16 v[32:35], v[170:173], v[186:189], v[32:35]
	v_mfma_f32_16x16x32_bf16 v[20:23], v[162:165], v[214:217], v[20:23]
	v_mfma_f32_16x16x32_bf16 v[16:19], v[170:173], v[214:217], v[16:19]
	v_mfma_f32_16x16x32_bf16 v[4:7], v[162:165], v[222:225], v[4:7]
	v_mfma_f32_16x16x32_bf16 v[0:3], v[170:173], v[222:225], v[0:3]
	v_mfma_f32_16x16x32_bf16 v[52:55], v[166:169], v[182:185], v[52:55]
	v_mfma_f32_16x16x32_bf16 v[48:51], v[174:177], v[182:185], v[48:51]
	v_mfma_f32_16x16x32_bf16 v[36:39], v[166:169], v[190:193], v[36:39]
	v_mfma_f32_16x16x32_bf16 v[32:35], v[174:177], v[190:193], v[32:35]
	v_mfma_f32_16x16x32_bf16 v[20:23], v[166:169], v[218:221], v[20:23]
	v_mfma_f32_16x16x32_bf16 v[16:19], v[174:177], v[218:221], v[16:19]
	v_mfma_f32_16x16x32_bf16 v[4:7], v[166:169], v[226:229], v[4:7]
	v_mfma_f32_16x16x32_bf16 v[0:3], v[174:177], v[226:229], v[0:3]
	s_setprio 0
	s_barrier
	s_add_i32 s22, 0, 0x18000
	s_add_i32 s23, 0, 0x1c000
	v_add_u32_e32 v158, s22, v147
	v_add_u32_e32 v174, s23, v147
	ds_read_b128 v[140:143], v158
	ds_read_b128 v[150:153], v158 offset:1024
	ds_read_b128 v[154:157], v158 offset:2048
	ds_read_b128 v[158:161], v158 offset:3072
	ds_read_b128 v[162:165], v174
	ds_read_b128 v[166:169], v174 offset:1024
	ds_read_b128 v[170:173], v174 offset:2048
	ds_read_b128 v[174:177], v174 offset:3072
	s_add_u32 s10, s10, 0x100000
	s_addc_u32 s11, s11, 0
	s_mov_b32 m0, s15
	v_lshl_add_u64 v[236:237], s[10:11], 0, v[130:131]
	ds_read_b128 v[178:181], v149 offset:32768
	ds_read_b128 v[182:185], v149 offset:33792
	ds_read_b128 v[186:189], v149 offset:34816
	ds_read_b128 v[190:193], v149 offset:35840
	ds_read_b128 v[214:217], v149 offset:36864
	ds_read_b128 v[218:221], v149 offset:37888
	ds_read_b128 v[222:225], v149 offset:38912
	ds_read_b128 v[226:229], v149 offset:39936
	global_load_lds_dwordx4 v[236:237], off
	v_lshl_add_u64 v[236:237], s[10:11], 0, v[132:133]
	s_mov_b32 m0, s17
	s_nop 0
	global_load_lds_dwordx4 v[236:237], off
	s_waitcnt vmcnt(8) lgkmcnt(0)
	s_barrier
	s_setprio 1
	v_mfma_f32_16x16x32_bf16 v[126:129], v[140:143], v[178:181], v[126:129]
	v_mfma_f32_16x16x32_bf16 v[122:125], v[154:157], v[178:181], v[122:125]
	v_mfma_f32_16x16x32_bf16 v[110:113], v[140:143], v[186:189], v[110:113]
	v_mfma_f32_16x16x32_bf16 v[106:109], v[154:157], v[186:189], v[106:109]
	v_mfma_f32_16x16x32_bf16 v[94:97], v[140:143], v[214:217], v[94:97]
	v_mfma_f32_16x16x32_bf16 v[90:93], v[154:157], v[214:217], v[90:93]
	v_mfma_f32_16x16x32_bf16 v[78:81], v[140:143], v[222:225], v[78:81]
	v_mfma_f32_16x16x32_bf16 v[74:77], v[154:157], v[222:225], v[74:77]
	v_mfma_f32_16x16x32_bf16 v[126:129], v[150:153], v[182:185], v[126:129]
	v_mfma_f32_16x16x32_bf16 v[122:125], v[158:161], v[182:185], v[122:125]
	v_mfma_f32_16x16x32_bf16 v[110:113], v[150:153], v[190:193], v[110:113]
	v_mfma_f32_16x16x32_bf16 v[106:109], v[158:161], v[190:193], v[106:109]
	v_mfma_f32_16x16x32_bf16 v[94:97], v[150:153], v[218:221], v[94:97]
	v_mfma_f32_16x16x32_bf16 v[90:93], v[158:161], v[218:221], v[90:93]
	v_mfma_f32_16x16x32_bf16 v[78:81], v[150:153], v[226:229], v[78:81]
	v_mfma_f32_16x16x32_bf16 v[74:77], v[158:161], v[226:229], v[74:77]
	s_setprio 0
	s_setprio 1
	v_mfma_f32_16x16x32_bf16 v[118:121], v[162:165], v[178:181], v[118:121]
	v_mfma_f32_16x16x32_bf16 v[114:117], v[170:173], v[178:181], v[114:117]
	v_mfma_f32_16x16x32_bf16 v[102:105], v[162:165], v[186:189], v[102:105]
	v_mfma_f32_16x16x32_bf16 v[98:101], v[170:173], v[186:189], v[98:101]
	v_mfma_f32_16x16x32_bf16 v[86:89], v[162:165], v[214:217], v[86:89]
	v_mfma_f32_16x16x32_bf16 v[82:85], v[170:173], v[214:217], v[82:85]
	v_mfma_f32_16x16x32_bf16 v[70:73], v[162:165], v[222:225], v[70:73]
	v_mfma_f32_16x16x32_bf16 v[66:69], v[170:173], v[222:225], v[66:69]
	v_mfma_f32_16x16x32_bf16 v[118:121], v[166:169], v[182:185], v[118:121]
	v_mfma_f32_16x16x32_bf16 v[114:117], v[174:177], v[182:185], v[114:117]
	v_mfma_f32_16x16x32_bf16 v[102:105], v[166:169], v[190:193], v[102:105]
	v_mfma_f32_16x16x32_bf16 v[98:101], v[174:177], v[190:193], v[98:101]
	v_mfma_f32_16x16x32_bf16 v[86:89], v[166:169], v[218:221], v[86:89]
	v_mfma_f32_16x16x32_bf16 v[82:85], v[174:177], v[218:221], v[82:85]
	v_mfma_f32_16x16x32_bf16 v[70:73], v[166:169], v[226:229], v[70:73]
	v_mfma_f32_16x16x32_bf16 v[66:69], v[174:177], v[226:229], v[66:69]
	s_setprio 0
	s_barrier
; #define PG8_STAGE(bufoff, gbase, voff) do { _Pragma("unroll") for (int _i = 0; _i < 2; ++_i) \
;         __builtin_amdgcn_global_load_lds((const unsigned*)((const char*)(gbase) + (voff)[_i]), (LAS unsigned*)(lds + (bufoff) + ldsw + _i * 8192), 16, 0, 0); } while (0)
; #define PG8_LDA(dst, b, h) do { _Pragma("unroll") for (int m = 0; m < 4; ++m) _Pragma("unroll") for (int k = 0; k < 2; ++k) dst[m][k] = *(const LAS bf16x8*)(lds + PG8_SA(b, h) + aoff + m * 2048 + k * 1024); } while (0)
; #define PG8_MMA(ai, bj, At, Bt) do { __builtin_amdgcn_s_setprio(1); _Pragma("unroll") for (int m = 0; m < 4; ++m) _Pragma("unroll") for (int n = 0; n < 2; ++n) _Pragma("unroll") for (int k = 0; k < 2; ++k) \
;         acc[ai][bj][m][n] = __builtin_amdgcn_mfma_f32_16x16x32_bf16(Bt[n][k], At[m][k], acc[ai][bj][m][n], 0, 0, 0); __builtin_amdgcn_s_setprio(0); } while (0)
; #define PG8_WAIT_V(n) asm volatile("s_waitcnt vmcnt(" #n ")" ::: "memory")
; #define PG8_WAIT_L(n) asm volatile("s_waitcnt lgkmcnt(" #n ")" ::: "memory")
; #define PG8_BAR __builtin_amdgcn_s_barrier()
; #define PG8_SCHED __builtin_amdgcn_sched_barrier(0)
; template <class Epi, bool SP2, class Sched>
; __device__ __forceinline__ void gemm_phase(LAS unsigned char* lds, const Gemm g, const Sched& S, const Epi& E) {
;     ...
;             PG8_LDA(At, 1, 1); PG8_STAGE(PG8_SB(1, 0), b3, voffB); PG8_STAGE(PG8_SB(1, 1), b3 + hstepB, voffB); PG8_STAGE(PG8_SA(1, 0), a3, voffA);
;             PG8_WAIT_V(8); PG8_WAIT_L(0); PG8_BAR; PG8_MMA(1, 0, At, B0); PG8_MMA(1, 1, At, B1); PG8_BAR; PG8_SCHED;
;     ...
;         if (wr == 0) PG8_BAR;
	s_add_i32 s10, s22, s12
	v_lshl_add_u64 v[144:145], v[144:145], 0, s[66:67]
	s_mov_b32 m0, s10
	ds_read_b128 v[178:181], v149 offset:49152
	ds_read_b128 v[182:185], v149 offset:50176
	ds_read_b128 v[186:189], v149 offset:51200
	ds_read_b128 v[190:193], v149 offset:52224
	ds_read_b128 v[214:217], v149 offset:53248
	ds_read_b128 v[218:221], v149 offset:54272
	ds_read_b128 v[222:225], v149 offset:55296
	ds_read_b128 v[226:229], v149 offset:56320
	global_load_lds_dwordx4 v[144:145], off
	s_add_i32 m0, s10, 0x2000
	s_add_u32 s6, s6, 0x100080
	v_lshl_add_u64 v[144:145], v[230:231], 0, s[66:67]
	s_addc_u32 s7, s7, 0
	s_add_i32 s10, s23, s12
	global_load_lds_dwordx4 v[144:145], off
	v_lshl_add_u64 v[144:145], s[6:7], 0, v[64:65]
	s_mov_b32 m0, s10
	s_nop 0
	global_load_lds_dwordx4 v[144:145], off
	v_lshl_add_u64 v[144:145], s[6:7], 0, v[134:135]
	s_add_i32 m0, s10, 0x2000
	s_nop 0
	global_load_lds_dwordx4 v[144:145], off
	v_lshl_add_u64 v[144:145], v[232:233], 0, s[66:67]
	s_mov_b32 m0, s18
	s_nop 0
	global_load_lds_dwordx4 v[144:145], off
	v_lshl_add_u64 v[144:145], v[234:235], 0, s[66:67]
	s_mov_b32 m0, s19
	s_nop 0
	global_load_lds_dwordx4 v[144:145], off
	s_waitcnt vmcnt(8) lgkmcnt(0)
	s_barrier
	s_setprio 1
	v_mfma_f32_16x16x32_bf16 v[60:63], v[140:143], v[178:181], v[60:63]
	v_mfma_f32_16x16x32_bf16 v[56:59], v[154:157], v[178:181], v[56:59]
	v_mfma_f32_16x16x32_bf16 v[44:47], v[140:143], v[186:189], v[44:47]
	v_mfma_f32_16x16x32_bf16 v[40:43], v[154:157], v[186:189], v[40:43]
	v_mfma_f32_16x16x32_bf16 v[28:31], v[140:143], v[214:217], v[28:31]
	v_mfma_f32_16x16x32_bf16 v[24:27], v[154:157], v[214:217], v[24:27]
	v_mfma_f32_16x16x32_bf16 v[12:15], v[140:143], v[222:225], v[12:15]
	v_mfma_f32_16x16x32_bf16 v[8:11], v[154:157], v[222:225], v[8:11]
	v_mfma_f32_16x16x32_bf16 v[60:63], v[150:153], v[182:185], v[60:63]
	v_mfma_f32_16x16x32_bf16 v[56:59], v[158:161], v[182:185], v[56:59]
	v_mfma_f32_16x16x32_bf16 v[44:47], v[150:153], v[190:193], v[44:47]
	v_mfma_f32_16x16x32_bf16 v[40:43], v[158:161], v[190:193], v[40:43]
	v_mfma_f32_16x16x32_bf16 v[28:31], v[150:153], v[218:221], v[28:31]
	v_mfma_f32_16x16x32_bf16 v[24:27], v[158:161], v[218:221], v[24:27]
	v_mfma_f32_16x16x32_bf16 v[12:15], v[150:153], v[226:229], v[12:15]
	v_mfma_f32_16x16x32_bf16 v[8:11], v[158:161], v[226:229], v[8:11]
	s_setprio 0
	s_setprio 1
	v_mfma_f32_16x16x32_bf16 v[52:55], v[162:165], v[178:181], v[52:55]
	v_mfma_f32_16x16x32_bf16 v[48:51], v[170:173], v[178:181], v[48:51]
	v_mfma_f32_16x16x32_bf16 v[36:39], v[162:165], v[186:189], v[36:39]
	v_mfma_f32_16x16x32_bf16 v[32:35], v[170:173], v[186:189], v[32:35]
	v_mfma_f32_16x16x32_bf16 v[20:23], v[162:165], v[214:217], v[20:23]
	v_mfma_f32_16x16x32_bf16 v[16:19], v[170:173], v[214:217], v[16:19]
	v_mfma_f32_16x16x32_bf16 v[4:7], v[162:165], v[222:225], v[4:7]
	v_mfma_f32_16x16x32_bf16 v[0:3], v[170:173], v[222:225], v[0:3]
	v_mfma_f32_16x16x32_bf16 v[52:55], v[166:169], v[182:185], v[52:55]
	v_mfma_f32_16x16x32_bf16 v[48:51], v[174:177], v[182:185], v[48:51]
	v_mfma_f32_16x16x32_bf16 v[36:39], v[166:169], v[190:193], v[36:39]
	v_mfma_f32_16x16x32_bf16 v[32:35], v[174:177], v[190:193], v[32:35]
	v_mfma_f32_16x16x32_bf16 v[20:23], v[166:169], v[218:221], v[20:23]
	v_mfma_f32_16x16x32_bf16 v[16:19], v[174:177], v[218:221], v[16:19]
	v_mfma_f32_16x16x32_bf16 v[4:7], v[166:169], v[226:229], v[4:7]
	v_mfma_f32_16x16x32_bf16 v[0:3], v[174:177], v[226:229], v[0:3]
	s_setprio 0
	s_barrier
	s_add_i32 s21, s21, 2
	s_add_u32 s76, s76, 0x100
	s_addc_u32 s20, s20, 0
	s_add_u32 s92, s92, 0x100
	s_addc_u32 s93, s93, 0
	s_cmp_gt_u32 s21, 61
	s_cbranch_scc0 .LBB0_1118
	s_and_b64 vcc, exec, s[60:61]
	s_cbranch_vccz .LBB0_1121
	s_barrier

; #define PG8_STAGE(bufoff, gbase, voff) do { _Pragma("unroll") for (int _i = 0; _i < 2; ++_i) \
;         __builtin_amdgcn_global_load_lds((const unsigned*)((const char*)(gbase) + (voff)[_i]), (LAS unsigned*)(lds + (bufoff) + ldsw + _i * 8192), 16, 0, 0); } while (0)
; #define PG8_LDA(dst, b, h) do { _Pragma("unroll") for (int m = 0; m < 4; ++m) _Pragma("unroll") for (int k = 0; k < 2; ++k) dst[m][k] = *(const LAS bf16x8*)(lds + PG8_SA(b, h) + aoff + m * 2048 + k * 1024); } while (0)
; #define PG8_LDB(dst, b, h) do { _Pragma("unroll") for (int n = 0; n < 2; ++n) _Pragma("unroll") for (int k = 0; k < 2; ++k) dst[n][k] = *(const LAS bf16x8*)(lds + PG8_SB(b, h) + boff + n * 2048 + k * 1024); } while (0)
; #define PG8_WAIT_V(n) asm volatile("s_waitcnt vmcnt(" #n ")" ::: "memory")
; #define PG8_WAIT_L(n) asm volatile("s_waitcnt lgkmcnt(" #n ")" ::: "memory")
; #define PG8_BAR __builtin_amdgcn_s_barrier()
; #define PG8_SCHED __builtin_amdgcn_sched_barrier(0)
; template <class Epi, bool SP2, class Sched>
; __device__ __forceinline__ void gemm_phase(LAS unsigned char* lds, const Gemm g, const Sched& S, const Epi& E) {
;     ...
;         const bool has_next = S.next(ui + 1, nxt);
;         const char* nA = has_next ? (const char*)g.A + (size_t)nxt.pm * tstep + nxt.ko : cA; const char* nB = has_next ? (const char*)g.Bt + (size_t)nxt.pn * tstepB + nxt.ko : cB;
;         for (int t = 0; t < nt; t += 2) {
;             const bool last = (t == nt - 2);
;             const char* a1 = cA + (size_t)(t + 1) * kstep;
;             const char* a2 = last ? nA : cA + (size_t)(t + 2) * kstep; const char* b2 = last ? nB : cB + (size_t)(t + 2) * kstep;
;             const char* a3 = a2 + kstep; const char* b3 = b2 + kstep;
;             if constexpr (Epi::MID) { if (t == (nt >> 1)) E.mid(acc, cur, wr, fr); }
;             if constexpr (SP2) {
;             PG8_LDB(B0, 0, 0); PG8_LDB(B1, 0, 1); PG8_SCHED; PG8_LDA(At, 0, 0); PG8_STAGE(PG8_SA(1, 1), a1 + hstep, voffA);
;             PG8_WAIT_V(8); PG8_WAIT_L(0); PG8_BAR; PG8_MMA(0, 0, At, B0); PG8_MMA(0, 1, At, B1); PG8_BAR; PG8_SCHED;
;             PG8_LDA(At, 0, 1); PG8_STAGE(PG8_SB(0, 0), b2, voffB); PG8_STAGE(PG8_SB(0, 1), b2 + hstepB, voffB); PG8_STAGE(PG8_SA(0, 0), a2, voffA);
;             PG8_WAIT_V(8); PG8_WAIT_L(0); PG8_BAR; PG8_MMA(1, 0, At, B0); PG8_MMA(1, 1, At, B1); PG8_BAR; PG8_SCHED;
.LBB0_1150:
	s_add_u32 s6, s86, 0xfff00080
	s_addc_u32 s7, s87, -1
	s_add_i32 s22, 0, 0x10000
	s_cmp_eq_u32 s21, 12
	s_cselect_b32 s11, s3, s7
	s_cselect_b32 s10, s57, s6
	s_cselect_b32 s7, s53, s20
	s_cselect_b32 s6, s77, s79
	s_add_i32 s24, 0, 0x14000
	v_add_u32_e32 v152, s22, v137
	v_add_u32_e32 v168, s24, v137
	ds_read_b128 v[140:143], v152
	ds_read_b128 v[144:147], v152 offset:1024
	ds_read_b128 v[148:151], v152 offset:2048
	ds_read_b128 v[152:155], v152 offset:3072
	ds_read_b128 v[156:159], v168
	ds_read_b128 v[160:163], v168 offset:1024
	ds_read_b128 v[164:167], v168 offset:2048
	ds_read_b128 v[168:171], v168 offset:3072
	v_lshl_add_u64 v[192:193], s[86:87], 0, v[134:135]
	s_add_i32 m0, s5, 0xc000
	ds_read_b128 v[172:175], v139
	ds_read_b128 v[176:179], v139 offset:1024
	ds_read_b128 v[180:183], v139 offset:2048
	ds_read_b128 v[184:187], v139 offset:3072
	ds_read_b128 v[188:191], v139 offset:4096
	ds_read_b128 v[214:217], v139 offset:5120
	ds_read_b128 v[218:221], v139 offset:6144
	ds_read_b128 v[222:225], v139 offset:7168
	global_load_lds_dwordx4 v[192:193], off
	v_lshl_add_u64 v[192:193], s[86:87], 0, v[132:133]
	s_add_i32 m0, s5, 0xe000
	s_nop 0
	global_load_lds_dwordx4 v[192:193], off
	s_waitcnt vmcnt(8) lgkmcnt(0)
	s_barrier
	s_setprio 1
	v_mfma_f32_16x16x32_bf16 v[126:129], v[140:143], v[172:175], v[126:129]
	v_mfma_f32_16x16x32_bf16 v[122:125], v[148:151], v[172:175], v[122:125]
	v_mfma_f32_16x16x32_bf16 v[118:121], v[140:143], v[180:183], v[118:121]
	v_mfma_f32_16x16x32_bf16 v[114:117], v[148:151], v[180:183], v[114:117]
	v_mfma_f32_16x16x32_bf16 v[106:109], v[140:143], v[188:191], v[106:109]
	v_mfma_f32_16x16x32_bf16 v[98:101], v[148:151], v[188:191], v[98:101]
	v_mfma_f32_16x16x32_bf16 v[90:93], v[140:143], v[218:221], v[90:93]
	v_mfma_f32_16x16x32_bf16 v[82:85], v[148:151], v[218:221], v[82:85]
	v_mfma_f32_16x16x32_bf16 v[126:129], v[144:147], v[176:179], v[126:129]
	v_mfma_f32_16x16x32_bf16 v[122:125], v[152:155], v[176:179], v[122:125]
	v_mfma_f32_16x16x32_bf16 v[118:121], v[144:147], v[184:187], v[118:121]
	v_mfma_f32_16x16x32_bf16 v[114:117], v[152:155], v[184:187], v[114:117]
	v_mfma_f32_16x16x32_bf16 v[106:109], v[144:147], v[214:217], v[106:109]
	v_mfma_f32_16x16x32_bf16 v[98:101], v[152:155], v[214:217], v[98:101]
	v_mfma_f32_16x16x32_bf16 v[90:93], v[144:147], v[222:225], v[90:93]
	v_mfma_f32_16x16x32_bf16 v[82:85], v[152:155], v[222:225], v[82:85]
	s_setprio 0
	s_setprio 1
	v_mfma_f32_16x16x32_bf16 v[110:113], v[156:159], v[172:175], v[110:113]
	v_mfma_f32_16x16x32_bf16 v[102:105], v[164:167], v[172:175], v[102:105]
	v_mfma_f32_16x16x32_bf16 v[94:97], v[156:159], v[180:183], v[94:97]
	v_mfma_f32_16x16x32_bf16 v[86:89], v[164:167], v[180:183], v[86:89]
	v_mfma_f32_16x16x32_bf16 v[78:81], v[156:159], v[188:191], v[78:81]
	v_mfma_f32_16x16x32_bf16 v[74:77], v[164:167], v[188:191], v[74:77]
	v_mfma_f32_16x16x32_bf16 v[70:73], v[156:159], v[218:221], v[70:73]
	v_mfma_f32_16x16x32_bf16 v[66:69], v[164:167], v[218:221], v[66:69]
	v_mfma_f32_16x16x32_bf16 v[110:113], v[160:163], v[176:179], v[110:113]
	v_mfma_f32_16x16x32_bf16 v[102:105], v[168:171], v[176:179], v[102:105]
	v_mfma_f32_16x16x32_bf16 v[94:97], v[160:163], v[184:187], v[94:97]
	v_mfma_f32_16x16x32_bf16 v[86:89], v[168:171], v[184:187], v[86:89]
	v_mfma_f32_16x16x32_bf16 v[78:81], v[160:163], v[214:217], v[78:81]
	v_mfma_f32_16x16x32_bf16 v[74:77], v[168:171], v[214:217], v[74:77]
	v_mfma_f32_16x16x32_bf16 v[70:73], v[160:163], v[222:225], v[70:73]
	v_mfma_f32_16x16x32_bf16 v[66:69], v[168:171], v[222:225], v[66:69]
	s_setprio 0
	s_barrier
	s_add_i32 s22, s22, s18
	v_lshl_add_u64 v[192:193], s[6:7], 0, v[64:65]
	s_mov_b32 m0, s22
	ds_read_b128 v[172:175], v139 offset:16384
	ds_read_b128 v[176:179], v139 offset:17408
	ds_read_b128 v[180:183], v139 offset:18432
	ds_read_b128 v[184:187], v139 offset:19456
	ds_read_b128 v[188:191], v139 offset:20480
	ds_read_b128 v[214:217], v139 offset:21504
	ds_read_b128 v[218:221], v139 offset:22528
	ds_read_b128 v[222:225], v139 offset:23552
	global_load_lds_dwordx4 v[192:193], off
	s_add_i32 m0, s22, 0x2000
	s_add_u32 s22, s6, 0x100000
	v_lshl_add_u64 v[226:227], s[6:7], 0, v[130:131]
	s_addc_u32 s23, s7, 0
	s_add_i32 s24, s24, s18
	global_load_lds_dwordx4 v[226:227], off
	v_lshl_add_u64 v[228:229], s[22:23], 0, v[64:65]
	s_mov_b32 m0, s24
	v_lshl_add_u64 v[230:231], s[10:11], 0, v[130:131]
	global_load_lds_dwordx4 v[228:229], off
	v_lshl_add_u64 v[228:229], s[22:23], 0, v[130:131]
	s_add_i32 m0, s24, 0x2000
	s_nop 0
	global_load_lds_dwordx4 v[228:229], off
	v_lshl_add_u64 v[228:229], s[10:11], 0, v[64:65]
	s_mov_b32 m0, s5
	s_nop 0
	global_load_lds_dwordx4 v[228:229], off
	s_mov_b32 m0, s33
	s_nop 0
	global_load_lds_dwordx4 v[230:231], off
	s_waitcnt vmcnt(8) lgkmcnt(0)
	s_barrier
; #define PG8_STAGE(bufoff, gbase, voff) do { _Pragma("unroll") for (int _i = 0; _i < 2; ++_i) \
;         __builtin_amdgcn_global_load_lds((const unsigned*)((const char*)(gbase) + (voff)[_i]), (LAS unsigned*)(lds + (bufoff) + ldsw + _i * 8192), 16, 0, 0); } while (0)
; #define PG8_LDA(dst, b, h) do { _Pragma("unroll") for (int m = 0; m < 4; ++m) _Pragma("unroll") for (int k = 0; k < 2; ++k) dst[m][k] = *(const LAS bf16x8*)(lds + PG8_SA(b, h) + aoff + m * 2048 + k * 1024); } while (0)
; #define PG8_LDB(dst, b, h) do { _Pragma("unroll") for (int n = 0; n < 2; ++n) _Pragma("unroll") for (int k = 0; k < 2; ++k) dst[n][k] = *(const LAS bf16x8*)(lds + PG8_SB(b, h) + boff + n * 2048 + k * 1024); } while (0)
; #define PG8_MMA(ai, bj, At, Bt) do { __builtin_amdgcn_s_setprio(1); _Pragma("unroll") for (int m = 0; m < 4; ++m) _Pragma("unroll") for (int n = 0; n < 2; ++n) _Pragma("unroll") for (int k = 0; k < 2; ++k) \
;         acc[ai][bj][m][n] = __builtin_amdgcn_mfma_f32_16x16x32_bf16(Bt[n][k], At[m][k], acc[ai][bj][m][n], 0, 0, 0); __builtin_amdgcn_s_setprio(0); } while (0)
; #define PG8_WAIT_V(n) asm volatile("s_waitcnt vmcnt(" #n ")" ::: "memory")
; #define PG8_WAIT_L(n) asm volatile("s_waitcnt lgkmcnt(" #n ")" ::: "memory")
; #define PG8_BAR __builtin_amdgcn_s_barrier()
; #define PG8_SCHED __builtin_amdgcn_sched_barrier(0)
; template <class Epi, bool SP2, class Sched>
; __device__ __forceinline__ void gemm_phase(LAS unsigned char* lds, const Gemm g, const Sched& S, const Epi& E) {
;     ...
;             PG8_WAIT_V(8); PG8_WAIT_L(0); PG8_BAR; PG8_MMA(1, 0, At, B0); PG8_MMA(1, 1, At, B1); PG8_BAR; PG8_SCHED;
;             PG8_LDB(B0, 1, 0); PG8_LDB(B1, 1, 1); PG8_SCHED; PG8_LDA(At, 1, 0); PG8_STAGE(PG8_SA(0, 1), a2 + hstep, voffA);
;             PG8_WAIT_V(8); PG8_WAIT_L(0); PG8_BAR; PG8_MMA(0, 0, At, B0); PG8_MMA(0, 1, At, B1); PG8_BAR; PG8_SCHED;
	s_setprio 1
	v_mfma_f32_16x16x32_bf16 v[60:63], v[140:143], v[172:175], v[60:63]
	v_mfma_f32_16x16x32_bf16 v[56:59], v[148:151], v[172:175], v[56:59]
	v_mfma_f32_16x16x32_bf16 v[52:55], v[140:143], v[180:183], v[52:55]
	v_mfma_f32_16x16x32_bf16 v[48:51], v[148:151], v[180:183], v[48:51]
	v_mfma_f32_16x16x32_bf16 v[36:39], v[140:143], v[188:191], v[36:39]
	v_mfma_f32_16x16x32_bf16 v[32:35], v[148:151], v[188:191], v[32:35]
	v_mfma_f32_16x16x32_bf16 v[20:23], v[140:143], v[218:221], v[20:23]
	v_mfma_f32_16x16x32_bf16 v[16:19], v[148:151], v[218:221], v[16:19]
	v_mfma_f32_16x16x32_bf16 v[60:63], v[144:147], v[176:179], v[60:63]
	v_mfma_f32_16x16x32_bf16 v[56:59], v[152:155], v[176:179], v[56:59]
	v_mfma_f32_16x16x32_bf16 v[52:55], v[144:147], v[184:187], v[52:55]
	v_mfma_f32_16x16x32_bf16 v[48:51], v[152:155], v[184:187], v[48:51]
	v_mfma_f32_16x16x32_bf16 v[36:39], v[144:147], v[214:217], v[36:39]
	v_mfma_f32_16x16x32_bf16 v[32:35], v[152:155], v[214:217], v[32:35]
	v_mfma_f32_16x16x32_bf16 v[20:23], v[144:147], v[222:225], v[20:23]
	v_mfma_f32_16x16x32_bf16 v[16:19], v[152:155], v[222:225], v[16:19]
	s_setprio 0
	s_setprio 1
	v_mfma_f32_16x16x32_bf16 v[44:47], v[156:159], v[172:175], v[44:47]
	v_mfma_f32_16x16x32_bf16 v[40:43], v[164:167], v[172:175], v[40:43]
	v_mfma_f32_16x16x32_bf16 v[28:31], v[156:159], v[180:183], v[28:31]
	v_mfma_f32_16x16x32_bf16 v[24:27], v[164:167], v[180:183], v[24:27]
	v_mfma_f32_16x16x32_bf16 v[12:15], v[156:159], v[188:191], v[12:15]
	v_mfma_f32_16x16x32_bf16 v[8:11], v[164:167], v[188:191], v[8:11]
	v_mfma_f32_16x16x32_bf16 v[4:7], v[156:159], v[218:221], v[4:7]
	v_mfma_f32_16x16x32_bf16 v[0:3], v[164:167], v[218:221], v[0:3]
	v_mfma_f32_16x16x32_bf16 v[44:47], v[160:163], v[176:179], v[44:47]
	v_mfma_f32_16x16x32_bf16 v[40:43], v[168:171], v[176:179], v[40:43]
	v_mfma_f32_16x16x32_bf16 v[28:31], v[160:163], v[184:187], v[28:31]
	v_mfma_f32_16x16x32_bf16 v[24:27], v[168:171], v[184:187], v[24:27]
	v_mfma_f32_16x16x32_bf16 v[12:15], v[160:163], v[214:217], v[12:15]
	v_mfma_f32_16x16x32_bf16 v[8:11], v[168:171], v[214:217], v[8:11]
	v_mfma_f32_16x16x32_bf16 v[4:7], v[160:163], v[222:225], v[4:7]
	v_mfma_f32_16x16x32_bf16 v[0:3], v[168:171], v[222:225], v[0:3]
	s_setprio 0
	s_barrier
	s_add_i32 s22, 0, 0x18000
	s_add_i32 s23, 0, 0x1c000
	v_add_u32_e32 v152, s22, v137
	v_add_u32_e32 v168, s23, v137
	ds_read_b128 v[140:143], v152
	ds_read_b128 v[144:147], v152 offset:1024
	ds_read_b128 v[148:151], v152 offset:2048
	ds_read_b128 v[152:155], v152 offset:3072
	ds_read_b128 v[156:159], v168
	ds_read_b128 v[160:163], v168 offset:1024
	ds_read_b128 v[164:167], v168 offset:2048
	ds_read_b128 v[168:171], v168 offset:3072
	s_add_u32 s10, s10, 0x100000
	s_addc_u32 s11, s11, 0
	s_mov_b32 m0, s62
	v_lshl_add_u64 v[232:233], s[10:11], 0, v[64:65]
	ds_read_b128 v[172:175], v139 offset:32768
	ds_read_b128 v[176:179], v139 offset:33792
	ds_read_b128 v[180:183], v139 offset:34816
	ds_read_b128 v[184:187], v139 offset:35840
	ds_read_b128 v[188:191], v139 offset:36864
	ds_read_b128 v[214:217], v139 offset:37888
	ds_read_b128 v[218:221], v139 offset:38912
	ds_read_b128 v[222:225], v139 offset:39936
	global_load_lds_dwordx4 v[232:233], off
	v_lshl_add_u64 v[232:233], s[10:11], 0, v[130:131]
	s_mov_b32 m0, s64
	s_nop 0
	global_load_lds_dwordx4 v[232:233], off
	s_waitcnt vmcnt(8) lgkmcnt(0)
	s_barrier
	s_setprio 1
	v_mfma_f32_16x16x32_bf16 v[126:129], v[140:143], v[172:175], v[126:129]
	v_mfma_f32_16x16x32_bf16 v[122:125], v[148:151], v[172:175], v[122:125]
	v_mfma_f32_16x16x32_bf16 v[118:121], v[140:143], v[180:183], v[118:121]
	v_mfma_f32_16x16x32_bf16 v[114:117], v[148:151], v[180:183], v[114:117]
	v_mfma_f32_16x16x32_bf16 v[106:109], v[140:143], v[188:191], v[106:109]
	v_mfma_f32_16x16x32_bf16 v[98:101], v[148:151], v[188:191], v[98:101]
	v_mfma_f32_16x16x32_bf16 v[90:93], v[140:143], v[218:221], v[90:93]
	v_mfma_f32_16x16x32_bf16 v[82:85], v[148:151], v[218:221], v[82:85]
	v_mfma_f32_16x16x32_bf16 v[126:129], v[144:147], v[176:179], v[126:129]
	v_mfma_f32_16x16x32_bf16 v[122:125], v[152:155], v[176:179], v[122:125]
	v_mfma_f32_16x16x32_bf16 v[118:121], v[144:147], v[184:187], v[118:121]
	v_mfma_f32_16x16x32_bf16 v[114:117], v[152:155], v[184:187], v[114:117]
	v_mfma_f32_16x16x32_bf16 v[106:109], v[144:147], v[214:217], v[106:109]
	v_mfma_f32_16x16x32_bf16 v[98:101], v[152:155], v[214:217], v[98:101]
	v_mfma_f32_16x16x32_bf16 v[90:93], v[144:147], v[222:225], v[90:93]
	v_mfma_f32_16x16x32_bf16 v[82:85], v[152:155], v[222:225], v[82:85]
	s_setprio 0
	s_setprio 1
	v_mfma_f32_16x16x32_bf16 v[110:113], v[156:159], v[172:175], v[110:113]
	v_mfma_f32_16x16x32_bf16 v[102:105], v[164:167], v[172:175], v[102:105]
	v_mfma_f32_16x16x32_bf16 v[94:97], v[156:159], v[180:183], v[94:97]
	v_mfma_f32_16x16x32_bf16 v[86:89], v[164:167], v[180:183], v[86:89]
	v_mfma_f32_16x16x32_bf16 v[78:81], v[156:159], v[188:191], v[78:81]
	v_mfma_f32_16x16x32_bf16 v[74:77], v[164:167], v[188:191], v[74:77]
	v_mfma_f32_16x16x32_bf16 v[70:73], v[156:159], v[218:221], v[70:73]
	v_mfma_f32_16x16x32_bf16 v[66:69], v[164:167], v[218:221], v[66:69]
	v_mfma_f32_16x16x32_bf16 v[110:113], v[160:163], v[176:179], v[110:113]
	v_mfma_f32_16x16x32_bf16 v[102:105], v[168:171], v[176:179], v[102:105]
	v_mfma_f32_16x16x32_bf16 v[94:97], v[160:163], v[184:187], v[94:97]
	v_mfma_f32_16x16x32_bf16 v[86:89], v[168:171], v[184:187], v[86:89]
	v_mfma_f32_16x16x32_bf16 v[78:81], v[160:163], v[214:217], v[78:81]
	v_mfma_f32_16x16x32_bf16 v[74:77], v[168:171], v[214:217], v[74:77]
	v_mfma_f32_16x16x32_bf16 v[70:73], v[160:163], v[222:225], v[70:73]
	v_mfma_f32_16x16x32_bf16 v[66:69], v[168:171], v[222:225], v[66:69]
	s_setprio 0
	s_barrier
; #define PG8_STAGE(bufoff, gbase, voff) do { _Pragma("unroll") for (int _i = 0; _i < 2; ++_i) \
;         __builtin_amdgcn_global_load_lds((const unsigned*)((const char*)(gbase) + (voff)[_i]), (LAS unsigned*)(lds + (bufoff) + ldsw + _i * 8192), 16, 0, 0); } while (0)
; #define PG8_LDA(dst, b, h) do { _Pragma("unroll") for (int m = 0; m < 4; ++m) _Pragma("unroll") for (int k = 0; k < 2; ++k) dst[m][k] = *(const LAS bf16x8*)(lds + PG8_SA(b, h) + aoff + m * 2048 + k * 1024); } while (0)
; #define PG8_MMA(ai, bj, At, Bt) do { __builtin_amdgcn_s_setprio(1); _Pragma("unroll") for (int m = 0; m < 4; ++m) _Pragma("unroll") for (int n = 0; n < 2; ++n) _Pragma("unroll") for (int k = 0; k < 2; ++k) \
;         acc[ai][bj][m][n] = __builtin_amdgcn_mfma_f32_16x16x32_bf16(Bt[n][k], At[m][k], acc[ai][bj][m][n], 0, 0, 0); __builtin_amdgcn_s_setprio(0); } while (0)
; #define PG8_WAIT_V(n) asm volatile("s_waitcnt vmcnt(" #n ")" ::: "memory")
; #define PG8_WAIT_L(n) asm volatile("s_waitcnt lgkmcnt(" #n ")" ::: "memory")
; #define PG8_BAR __builtin_amdgcn_s_barrier()
; #define PG8_SCHED __builtin_amdgcn_sched_barrier(0)
; template <class Epi, bool SP2, class Sched>
; __device__ __forceinline__ void gemm_phase(LAS unsigned char* lds, const Gemm g, const Sched& S, const Epi& E) {
;     ...
;             PG8_LDA(At, 1, 1); PG8_STAGE(PG8_SB(1, 0), b3, voffB); PG8_STAGE(PG8_SB(1, 1), b3 + hstepB, voffB); PG8_STAGE(PG8_SA(1, 0), a3, voffA);
;             PG8_WAIT_V(8); PG8_WAIT_L(0); PG8_BAR; PG8_MMA(1, 0, At, B0); PG8_MMA(1, 1, At, B1); PG8_BAR; PG8_SCHED;
;     ...
;         if (wr == 0) PG8_BAR;
	s_add_i32 s10, s22, s18
	v_lshl_add_u64 v[192:193], v[192:193], 0, s[66:67]
	s_mov_b32 m0, s10
	ds_read_b128 v[172:175], v139 offset:49152
	ds_read_b128 v[176:179], v139 offset:50176
	ds_read_b128 v[180:183], v139 offset:51200
	ds_read_b128 v[184:187], v139 offset:52224
	ds_read_b128 v[188:191], v139 offset:53248
	ds_read_b128 v[214:217], v139 offset:54272
	ds_read_b128 v[218:221], v139 offset:55296
	ds_read_b128 v[222:225], v139 offset:56320
	global_load_lds_dwordx4 v[192:193], off
	s_add_i32 m0, s10, 0x2000
	s_add_u32 s6, s6, 0x100080
	v_lshl_add_u64 v[192:193], v[226:227], 0, s[66:67]
	s_addc_u32 s7, s7, 0
	s_add_i32 s10, s23, s18
	global_load_lds_dwordx4 v[192:193], off
	v_lshl_add_u64 v[192:193], s[6:7], 0, v[64:65]
	s_mov_b32 m0, s10
	s_nop 0
	global_load_lds_dwordx4 v[192:193], off
	v_lshl_add_u64 v[192:193], s[6:7], 0, v[130:131]
	s_add_i32 m0, s10, 0x2000
	s_nop 0
	global_load_lds_dwordx4 v[192:193], off
	v_lshl_add_u64 v[192:193], v[228:229], 0, s[66:67]
	s_mov_b32 m0, s72
	s_nop 0
	global_load_lds_dwordx4 v[192:193], off
	v_lshl_add_u64 v[192:193], v[230:231], 0, s[66:67]
	s_mov_b32 m0, s73
	s_nop 0
	global_load_lds_dwordx4 v[192:193], off
	s_waitcnt vmcnt(8) lgkmcnt(0)
	s_barrier
	s_setprio 1
	v_mfma_f32_16x16x32_bf16 v[60:63], v[140:143], v[172:175], v[60:63]
	v_mfma_f32_16x16x32_bf16 v[56:59], v[148:151], v[172:175], v[56:59]
	v_mfma_f32_16x16x32_bf16 v[52:55], v[140:143], v[180:183], v[52:55]
	v_mfma_f32_16x16x32_bf16 v[48:51], v[148:151], v[180:183], v[48:51]
	v_mfma_f32_16x16x32_bf16 v[36:39], v[140:143], v[188:191], v[36:39]
	v_mfma_f32_16x16x32_bf16 v[32:35], v[148:151], v[188:191], v[32:35]
	v_mfma_f32_16x16x32_bf16 v[20:23], v[140:143], v[218:221], v[20:23]
	v_mfma_f32_16x16x32_bf16 v[16:19], v[148:151], v[218:221], v[16:19]
	v_mfma_f32_16x16x32_bf16 v[60:63], v[144:147], v[176:179], v[60:63]
	v_mfma_f32_16x16x32_bf16 v[56:59], v[152:155], v[176:179], v[56:59]
	v_mfma_f32_16x16x32_bf16 v[52:55], v[144:147], v[184:187], v[52:55]
	v_mfma_f32_16x16x32_bf16 v[48:51], v[152:155], v[184:187], v[48:51]
	v_mfma_f32_16x16x32_bf16 v[36:39], v[144:147], v[214:217], v[36:39]
	v_mfma_f32_16x16x32_bf16 v[32:35], v[152:155], v[214:217], v[32:35]
	v_mfma_f32_16x16x32_bf16 v[20:23], v[144:147], v[222:225], v[20:23]
	v_mfma_f32_16x16x32_bf16 v[16:19], v[152:155], v[222:225], v[16:19]
	s_setprio 0
	s_setprio 1
	v_mfma_f32_16x16x32_bf16 v[44:47], v[156:159], v[172:175], v[44:47]
	v_mfma_f32_16x16x32_bf16 v[40:43], v[164:167], v[172:175], v[40:43]
	v_mfma_f32_16x16x32_bf16 v[28:31], v[156:159], v[180:183], v[28:31]
	v_mfma_f32_16x16x32_bf16 v[24:27], v[164:167], v[180:183], v[24:27]
	v_mfma_f32_16x16x32_bf16 v[12:15], v[156:159], v[188:191], v[12:15]
	v_mfma_f32_16x16x32_bf16 v[8:11], v[164:167], v[188:191], v[8:11]
	v_mfma_f32_16x16x32_bf16 v[4:7], v[156:159], v[218:221], v[4:7]
	v_mfma_f32_16x16x32_bf16 v[0:3], v[164:167], v[218:221], v[0:3]
	v_mfma_f32_16x16x32_bf16 v[44:47], v[160:163], v[176:179], v[44:47]
	v_mfma_f32_16x16x32_bf16 v[40:43], v[168:171], v[176:179], v[40:43]
	v_mfma_f32_16x16x32_bf16 v[28:31], v[160:163], v[184:187], v[28:31]
	v_mfma_f32_16x16x32_bf16 v[24:27], v[168:171], v[184:187], v[24:27]
	v_mfma_f32_16x16x32_bf16 v[12:15], v[160:163], v[214:217], v[12:15]
	v_mfma_f32_16x16x32_bf16 v[8:11], v[168:171], v[214:217], v[8:11]
	v_mfma_f32_16x16x32_bf16 v[4:7], v[160:163], v[222:225], v[4:7]
	v_mfma_f32_16x16x32_bf16 v[0:3], v[168:171], v[222:225], v[0:3]
	s_setprio 0
	s_barrier
	s_add_i32 s21, s21, 2
	s_add_u32 s79, s79, 0x100
	s_addc_u32 s20, s20, 0
	s_add_u32 s86, s86, 0x100
	s_addc_u32 s87, s87, 0
	s_cmp_gt_u32 s21, 13
	s_cbranch_scc0 .LBB0_1150
	s_and_b64 vcc, exec, s[16:17]
	s_cbranch_vccz .LBB0_1153
	s_barrier
